# win, gemm_f32, ffn_up k-loops: staging writes and global-load re-issue split across the MFMA groups, scalar-base loads, no vmcnt(0)/copies before the barrier
# speedup vs baseline: 1.0867x; 1.0271x over previous
; template <int MI, int NJ> ...
;     ...
;   const int lrow = tid >> 3, lkc = tid & 7;
;   const u16* Ag = A + (size_t)(row0 + lrow) * lda + kbeg + lkc * 8;
;   const u16* Bg = Bt + (size_t)(col0 + lrow) * ldb + kbeg + lkc * 8;
;   const size_t a64 = (size_t)64 * lda, b64 = (size_t)64 * ldb;
;   const int nk = (kend - kbeg) >> 6;
;   const long long nAoff = (long long)(nrow0 - row0) * lda + (nkbeg - kbeg);
;   const long long nBoff = (long long)(ncol0 - col0) * ldb + (nkbeg - kbeg);
;   u16* wa = sA + lrow * 64 + ((lkc ^ (lrow & 7)) * 8);
;   u16* wb = sB + lrow * 64 + ((lkc ^ (lrow & 7)) * 8);
;     ...
;   if (!pre) G8LOADP(Ag, Bg);
;   G8STORE(0);
;   {
;     const u16* ga_ = (1 < nk) ? Ag + 64 : Ag + nAoff;
;     const u16* gb_ = (1 < nk) ? Bg + 64 : Bg + nBoff;
;     G8LOADP(ga_, gb_);
;   }
;   __syncthreads();
;   const int sw0 = ((lane >> 4) ^ (lane & 7)) * 8;
;   const int dsw = (sw0 ^ 32) - sw0;
;   const u16* ra_ = sA + (wm * (16 * MI) + (lane & 15)) * 64 + sw0;
;   const u16* rb_ = sB + (wn * (16 * NJ) + (lane & 15)) * 64 + sw0;
; __device__ __forceinline__ void phase_win(const Params& p, int part, u16* smem, volatile LAS unsigned* vb_) {
;     ...
;   const int lane = tid & 63, wave = tid >> 6;
;   const int wm = wave >> 2, wn = wave & 3;
;   const int NT = part ? 20 : 12;
;   const int vb = real_vb(vb_);
;   G8REGS_DECL;
;   R_b1 = R_b2 = R_b3 = make_uint4(0u, 0u, 0u, 0u);
;   const int step = gridDim.x >> 3;
;   bool pre = false;
;   auto ntile = [&](int nl_) { return (part == 0) ? ((nl_ < 6) ? nl_ : (14 + nl_ - 6)) : ((nl_ < 8) ? (6 + nl_) : (20 + nl_ - 8)); };
;   for (int lt = vb >> 3; lt < 8 * NT; lt += step) {
;     const int nl = lt >> 3, mt = (vb & 7) * 8 + (lt & 7);
;     const int nt = ntile(nl);
;     const int ltn = (lt + step < 8 * NT) ? lt + step : lt;
;     const int nmt = (vb & 7) * 8 + (ltn & 7), nnt = ntile(ltn >> 3);
.LBB0_439:
	s_waitcnt vmcnt(15)
	v_mov_b32_e32 v2, v175
	ds_read_b32 v0, v230
	s_waitcnt lgkmcnt(0)
	v_readfirstlane_b32 s0, v0
	s_ashr_i32 s38, s0, 3
	s_cmp_ge_i32 s38, s22
	s_cbranch_scc1 .LBB0_472
	s_lshl_b32 s0, s0, 3
	s_and_b32 s23, s0, 56
	v_lshlrev_b32_e32 v0, 4, v2
	v_readlane_b32 s0, v252, 38
	v_and_b32_e32 v0, 0x70, v0
	v_readlane_b32 s1, v252, 39
	v_ashrrev_i32_e32 v184, 3, v2
	v_and_b32_e32 v3, 7, v2
	v_lshl_add_u64 v[176:177], s[0:1], 0, v[0:1]
	v_readlane_b32 s0, v253, 7
	v_readlane_b32 s1, v253, 8
	s_mov_b64 s[12:13], 0
	s_nop 0
	v_lshl_add_u64 v[178:179], s[0:1], 0, v[0:1]
	v_and_b32_e32 v234, 7, v184
	v_lshl_add_u32 v234, v234, 11, v0
	v_add_u32_e32 v235, 0x20000, v234
	v_add_u32_e32 v236, 0x40000, v234
	v_add_u32_e32 v237, 0x60000, v234
	v_xor_b32_e32 v0, v184, v2
	v_lshlrev_b32_e32 v0, 4, v0
	v_and_b32_e32 v0, 0x70, v0
	v_lshl_or_b32 v185, v184, 7, v0
	v_lshrrev_b32_e32 v0, 4, v2
	v_bitop3_b32 v0, v0, v3, 3 bitop3:0x6c
	v_lshlrev_b32_e32 v3, 3, v0
	v_xor_b32_e32 v4, 32, v3
	v_sub_u32_e32 v3, v4, v3
	v_ashrrev_i32_e32 v4, 1, v2
	v_and_b32_e32 v4, 0xffffff80, v4
	v_and_or_b32 v5, v2, 15, v4
	v_lshlrev_b32_e32 v0, 4, v0
	v_lshl_or_b32 v187, v5, 7, v0
	v_lshlrev_b32_e32 v5, 7, v2
	v_and_b32_e32 v5, 0x6780, v5
	s_mov_b32 s0, 0x10000
	v_or3_b32 v188, v5, v0, s0
	v_lshrrev_b32_e32 v0, 2, v2
	v_and_or_b32 v0, v0, 12, v4
	v_and_b32_e32 v2, 0xcf, v2
	v_mul_lo_u32 v0, v0, s2
	v_lshl_add_u32 v189, v2, 1, v0
	v_mov_b32_e32 v0, v1
	v_add_u32_e32 v186, 0x10000, v185
	v_lshlrev_b32_e32 v190, 1, v3
	s_waitcnt vmcnt(10)
	v_mov_b64_e32 v[22:23], v[0:1]
	v_mov_b64_e32 v[24:25], v[0:1]
	s_waitcnt vmcnt(9)
	v_mov_b64_e32 v[26:27], v[0:1]
	s_waitcnt vmcnt(12)
	v_mov_b64_e32 v[28:29], v[0:1]
	s_waitcnt vmcnt(8)
	v_mov_b64_e32 v[30:31], v[0:1]
	s_waitcnt vmcnt(4)
	v_mov_b64_e32 v[32:33], v[0:1]

; #define ZERO_ACC8(acc, NJ_)                             \
;   _Pragma("unroll") for (int i_ = 0; i_ < 8; ++i_)      \
;   _Pragma("unroll") for (int j_ = 0; j_ < (NJ_); ++j_) { acc[i_][j_] = (f32x4){0.f, 0.f, 0.f, 0.f}; }
; template <int MI, int NJ> ...
;     ...
;   if (!pre) G8LOADP(Ag, Bg);
;   G8STORE(0);
;   {
;     const u16* ga_ = (1 < nk) ? Ag + 64 : Ag + nAoff;
;     const u16* gb_ = (1 < nk) ? Bg + 64 : Bg + nBoff;
;     G8LOADP(ga_, gb_);
;   }
;   __syncthreads();
; __device__ __forceinline__ void phase_win(const Params& p, int part, u16* smem, volatile LAS unsigned* vb_) {
;     ...
;     const int nl = lt >> 3, mt = (vb & 7) * 8 + (lt & 7);
;     const int nt = ntile(nl);
;     const int ltn = (lt + step < 8 * NT) ? lt + step : lt;
;     const int nmt = (vb & 7) * 8 + (ltn & 7), nnt = ntile(ltn >> 3);
;     u16* dstA; u16* dstB; int ldA, ldB;
;     {
;       const int ct = nt * 2;
;       if (ct < 12) { dstA = (u16*)(p.ws + OFF_UCONV) + ct * 128; ldA = 1536; }
;       else if (ct < 28) { dstA = (u16*)(p.ws + OFF_UHG) + (ct - 12) * 128; ldA = 2048; }
;       else if (ct < 40) { dstA = (u16*)(p.ws + OFF_UNSA) + (ct - 28) * 128; ldA = 1536; }
;       else { dstA = (u16*)(p.ws + OFF_UMG) + (ct - 40) * 128; ldA = 3072; }
;       dstB = dstA + 128; ldB = ldA;
;     }
;     f32x4 acc[8][4];
;     ZERO_ACC8(acc, 4);
;     gemm8<8, 4>(acc, G8REGS_ARGS, pre, H, 1024, W, 1024, 0, 1024, mt * 256, nt * 256, nmt * 256, nnt * 256, 0, smem, tid);
.LBB0_467:
	s_and_b32 s11, s38, 7
	s_or_b32 s10, s11, s23
	s_lshl_b32 s10, s10, 8
	v_add_u32_e32 v34, s10, v184
	v_ashrrev_i32_e32 v35, 31, v34
	v_lshlrev_b64 v[34:35], 11, v[34:35]
	v_lshl_add_u64 v[180:181], v[176:177], 0, v[34:35]
	v_add_u32_e32 v34, s20, v184
	v_ashrrev_i32_e32 v35, 31, v34
	v_lshlrev_b64 v[34:35], 11, v[34:35]
	s_xor_b64 s[12:13], s[12:13], -1
	s_andn2_b64 vcc, exec, s[12:13]
	v_lshl_add_u64 v[182:183], v[178:179], 0, v[34:35]
	v_readfirstlane_b32 s62, v180
	v_readfirstlane_b32 s63, v181
	v_readfirstlane_b32 s64, v182
	v_readfirstlane_b32 s65, v183
	s_nop 4
	s_cbranch_vccnz .LBB0_469
	global_load_dwordx4 v[10:13], v234, s[62:63]
	global_load_dwordx4 v[2:5], v235, s[62:63]
	global_load_dwordx4 v[6:9], v236, s[62:63]
	global_load_dwordx4 v[18:21], v237, s[62:63]
	global_load_dwordx4 v[14:17], v234, s[64:65]
	global_load_dwordx4 v[22:25], v235, s[64:65]
	global_load_dwordx4 v[26:29], v236, s[64:65]
	global_load_dwordx4 v[30:33], v237, s[64:65]
.LBB0_469:
	s_waitcnt vmcnt(5)
	ds_write_b128 v185, v[10:13]
	ds_write_b128 v185, v[2:5] offset:8192
	ds_write_b128 v185, v[6:9] offset:16384
	s_waitcnt vmcnt(3)
	ds_write_b128 v185, v[18:21] offset:24576
	ds_write_b128 v186, v[14:17]
	s_waitcnt vmcnt(2)
	ds_write_b128 v186, v[22:25] offset:8192
	s_waitcnt vmcnt(1)
	ds_write_b128 v186, v[26:29] offset:16384
	s_waitcnt vmcnt(0)
	ds_write_b128 v186, v[30:33] offset:24576
	s_and_b32 s12, s39, 7
	s_sub_i32 s11, s12, s11
	s_lshl_b32 s12, s11, 8
	s_sub_i32 s11, s46, s37
	global_load_dwordx4 v[10:13], v234, s[62:63] offset:128
	global_load_dwordx4 v[2:5], v235, s[62:63] offset:128
	global_load_dwordx4 v[6:9], v236, s[62:63] offset:128
	global_load_dwordx4 v[18:21], v237, s[62:63] offset:128
	global_load_dwordx4 v[14:17], v234, s[64:65] offset:128
	global_load_dwordx4 v[22:25], v235, s[64:65] offset:128
	global_load_dwordx4 v[26:29], v236, s[64:65] offset:128
	global_load_dwordx4 v[30:33], v237, s[64:65] offset:128
	s_lshl_b32 s20, s11, 8
	s_ashr_i32 s13, s12, 31
	s_ashr_i32 s21, s20, 31
	v_mov_b32_e32 v34, 0
	s_lshl_b64 s[12:13], s[12:13], 10
	s_lshl_b64 s[46:47], s[20:21], 10
	s_mov_b32 s11, 0
	s_mov_b64 s[20:21], 0x80
	s_mov_b32 s37, 0
	v_mov_b32_e32 v35, v34
	v_mov_b32_e32 v36, v34
	v_mov_b32_e32 v37, v34
	v_mov_b32_e32 v38, v34
	v_mov_b32_e32 v39, v34
	v_mov_b32_e32 v40, v34
	v_mov_b32_e32 v41, v34
	v_mov_b32_e32 v42, v34
	v_mov_b32_e32 v43, v34
	v_mov_b32_e32 v44, v34
	v_mov_b32_e32 v45, v34
	v_mov_b32_e32 v46, v34
	v_mov_b32_e32 v47, v34
	v_mov_b32_e32 v48, v34
	v_mov_b32_e32 v49, v34
	v_mov_b32_e32 v50, v34
	v_mov_b32_e32 v51, v34
	v_mov_b32_e32 v52, v34
	v_mov_b32_e32 v53, v34
	v_mov_b32_e32 v54, v34
	v_mov_b32_e32 v55, v34
	v_mov_b32_e32 v56, v34
	v_mov_b32_e32 v57, v34
	v_mov_b32_e32 v58, v34
	v_mov_b32_e32 v59, v34
	v_mov_b32_e32 v60, v34
	v_mov_b32_e32 v61, v34
	v_mov_b32_e32 v62, v34
	v_mov_b32_e32 v63, v34
	v_mov_b32_e32 v64, v34
	v_mov_b32_e32 v65, v34
	v_mov_b32_e32 v66, v34
	v_mov_b32_e32 v67, v34
	v_mov_b32_e32 v68, v34
	v_mov_b32_e32 v69, v34
	v_mov_b32_e32 v70, v34
	v_mov_b32_e32 v71, v34
	v_mov_b32_e32 v72, v34
	v_mov_b32_e32 v73, v34
	v_mov_b32_e32 v74, v34
	v_mov_b32_e32 v75, v34
	v_mov_b32_e32 v76, v34
	v_mov_b32_e32 v77, v34
	v_mov_b32_e32 v78, v34
	v_mov_b32_e32 v79, v34
	v_mov_b32_e32 v80, v34
	v_mov_b32_e32 v81, v34
	v_mov_b32_e32 v82, v34
	v_mov_b32_e32 v83, v34
	v_mov_b32_e32 v84, v34
	v_mov_b32_e32 v85, v34
	v_mov_b32_e32 v86, v34
	v_mov_b32_e32 v87, v34
	v_mov_b32_e32 v88, v34
	v_mov_b32_e32 v89, v34
	v_mov_b32_e32 v90, v34
	v_mov_b32_e32 v91, v34
	v_mov_b32_e32 v92, v34
	v_mov_b32_e32 v93, v34
	v_mov_b32_e32 v94, v34
	v_mov_b32_e32 v95, v34
	v_mov_b32_e32 v96, v34
	v_mov_b32_e32 v97, v34
	v_mov_b32_e32 v98, v34
	v_mov_b32_e32 v99, v34
	v_mov_b32_e32 v100, v34
	v_mov_b32_e32 v101, v34
	v_mov_b32_e32 v102, v34
	v_mov_b32_e32 v103, v34
	v_mov_b32_e32 v104, v34
	v_mov_b32_e32 v105, v34
	v_mov_b32_e32 v106, v34
	v_mov_b32_e32 v107, v34
	v_mov_b32_e32 v108, v34
	v_mov_b32_e32 v109, v34
	v_mov_b32_e32 v110, v34
	v_mov_b32_e32 v111, v34
	v_mov_b32_e32 v112, v34
	v_mov_b32_e32 v113, v34
	v_mov_b32_e32 v114, v34
	v_mov_b32_e32 v115, v34
	v_mov_b32_e32 v116, v34
	v_mov_b32_e32 v117, v34
	v_mov_b32_e32 v118, v34
	v_mov_b32_e32 v119, v34
	v_mov_b32_e32 v120, v34
	v_mov_b32_e32 v121, v34
	v_mov_b32_e32 v122, v34
	v_mov_b32_e32 v123, v34
	v_mov_b32_e32 v124, v34
	v_mov_b32_e32 v125, v34
	v_mov_b32_e32 v126, v34
	v_mov_b32_e32 v127, v34
	v_mov_b32_e32 v128, v34
	v_mov_b32_e32 v129, v34
	v_mov_b32_e32 v130, v34
	v_mov_b32_e32 v131, v34
	v_mov_b32_e32 v132, v34
	v_mov_b32_e32 v133, v34
	v_mov_b32_e32 v134, v34
	v_mov_b32_e32 v135, v34
	v_mov_b32_e32 v136, v34
	v_mov_b32_e32 v137, v34
	v_mov_b32_e32 v138, v34
	v_mov_b32_e32 v139, v34
	v_mov_b32_e32 v140, v34
	v_mov_b32_e32 v141, v34
	v_mov_b32_e32 v142, v34
	v_mov_b32_e32 v143, v34
	v_mov_b32_e32 v144, v34
	v_mov_b32_e32 v145, v34
	v_mov_b32_e32 v146, v34
	v_mov_b32_e32 v147, v34
	v_mov_b32_e32 v148, v34
	v_mov_b32_e32 v149, v34
	v_mov_b32_e32 v150, v34
	v_mov_b32_e32 v151, v34
	v_mov_b32_e32 v152, v34
	v_mov_b32_e32 v153, v34
	v_mov_b32_e32 v154, v34
	v_mov_b32_e32 v155, v34
	v_mov_b32_e32 v156, v34
	v_mov_b32_e32 v157, v34
	v_mov_b32_e32 v158, v34
	v_mov_b32_e32 v159, v34
	v_mov_b32_e32 v160, v34
	v_mov_b32_e32 v161, v34
	s_waitcnt lgkmcnt(0)
	s_barrier
; template <int MI, int NJ> ...
;     ...
;   for (int kt = 0; kt < nk; ++kt) {
;     const int buf = kt & 1;
;     {
;       G8STORE(buf ^ 1);
;       const u16* ga_ = (kt + 2 < nk) ? Ag + (kt + 2) * 64 : Ag + nAoff;
;       const u16* gb_ = (kt + 2 < nk) ? Bg + (kt + 2) * 64 : Bg + nBoff;
;       G8LOADP(ga_, gb_);
;     }
;     __builtin_amdgcn_sched_barrier(0);
;     __builtin_amdgcn_s_setprio(1);
;     const u16* a = ra_ + buf * AROWS * 64;
;     const u16* b = rb_ + buf * BROWS * 64;
; #pragma unroll
;     for (int ks = 0; ks < 2; ++ks) {
;       const u16* a_ = ks ? a + dsw : a;
;       const u16* b_ = ks ? b + dsw : b;
;       bf16x8 bfr[NJ];
; #pragma unroll
;       for (int j = 0; j < NJ; ++j) bfr[j] = *(const bf16x8*)(b_ + j * 16 * 64);
; #pragma unroll
;       for (int ih = 0; ih < MI / 4; ++ih) {
;         bf16x8 af[4];
; #pragma unroll
;         for (int i = 0; i < 4; ++i) af[i] = *(const bf16x8*)(a_ + (ih * 4 + i) * 16 * 64);
; #pragma unroll
;         for (int i = 0; i < 4; ++i)
; #pragma unroll
;           for (int j = 0; j < NJ; ++j) acc[ih * 4 + i][j] = mfma16(af[i], bfr[j], acc[ih * 4 + i][j]);
;       }
;     }
.LBB0_470:
	s_and_b32 s38, s11, 0x4000
	s_xor_b32 s39, s38, 0x4000
	s_lshl_b32 s39, s39, 1
	v_add_u32_e32 v228, s39, v185
	v_add_u32_e32 v229, s39, v186
	s_cmp_lt_u32 s37, 14
	s_cselect_b32 s49, s21, s13
	s_cselect_b32 s48, s20, s12
	s_cselect_b32 s51, s21, s47
	s_cselect_b32 s50, s20, s46
	s_lshl_b64 s[48:49], s[48:49], 1
	s_lshl_b64 s[50:51], s[50:51], 1
	s_add_u32 s52, s62, s48
	s_addc_u32 s53, s63, s49
	s_add_u32 s66, s64, s50
	s_addc_u32 s67, s65, s51
	s_setprio 1
	s_lshl_b32 s38, s38, 1
	v_add_u32_e32 v0, s38, v187
	v_add_u32_e32 v191, s38, v188
	ds_read_b128 v[166:169], v191
	ds_read_b128 v[162:165], v0
	ds_read_b128 v[170:173], v191 offset:2048
	ds_read_b128 v[192:195], v191 offset:4096
	ds_read_b128 v[196:199], v191 offset:6144
	ds_read_b128 v[204:207], v0 offset:2048
	ds_read_b128 v[208:211], v0 offset:4096
	v_add_u32_e32 v191, v191, v190
	s_waitcnt lgkmcnt(5)
	v_mfma_f32_16x16x32_bf16 v[158:161], v[162:165], v[166:169], v[158:161]
	s_waitcnt lgkmcnt(4)
	v_mfma_f32_16x16x32_bf16 v[154:157], v[162:165], v[170:173], v[154:157]
	s_waitcnt lgkmcnt(3)
	v_mfma_f32_16x16x32_bf16 v[150:153], v[162:165], v[192:195], v[150:153]
	s_waitcnt lgkmcnt(2)
	v_mfma_f32_16x16x32_bf16 v[146:149], v[162:165], v[196:199], v[146:149]
	ds_read_b128 v[162:165], v0 offset:6144
	s_waitcnt lgkmcnt(2)
	v_mfma_f32_16x16x32_bf16 v[142:145], v[204:207], v[166:169], v[142:145]
	v_mfma_f32_16x16x32_bf16 v[138:141], v[204:207], v[170:173], v[138:141]
	v_mfma_f32_16x16x32_bf16 v[134:137], v[204:207], v[192:195], v[134:137]
	v_mfma_f32_16x16x32_bf16 v[130:133], v[204:207], v[196:199], v[130:133]
	ds_read_b128 v[204:207], v0 offset:8192
	s_waitcnt vmcnt(7)
	ds_write_b128 v228, v[10:13]
	global_load_dwordx4 v[10:13], v234, s[52:53]
	s_waitcnt lgkmcnt(3)
	v_mfma_f32_16x16x32_bf16 v[126:129], v[208:211], v[166:169], v[126:129]
	v_mfma_f32_16x16x32_bf16 v[122:125], v[208:211], v[170:173], v[122:125]
	v_mfma_f32_16x16x32_bf16 v[118:121], v[208:211], v[192:195], v[118:121]
	v_mfma_f32_16x16x32_bf16 v[114:117], v[208:211], v[196:199], v[114:117]
	ds_read_b128 v[208:211], v0 offset:10240
	s_waitcnt vmcnt(7)
	ds_write_b128 v228, v[2:5] offset:8192
	global_load_dwordx4 v[2:5], v235, s[52:53]
	ds_read_b128 v[212:215], v191
	ds_read_b128 v[216:219], v191 offset:2048
	s_waitcnt lgkmcnt(6)
	v_mfma_f32_16x16x32_bf16 v[110:113], v[162:165], v[166:169], v[110:113]
	v_mfma_f32_16x16x32_bf16 v[106:109], v[162:165], v[170:173], v[106:109]
	v_mfma_f32_16x16x32_bf16 v[102:105], v[162:165], v[192:195], v[102:105]
	v_mfma_f32_16x16x32_bf16 v[98:101], v[162:165], v[196:199], v[98:101]
	ds_read_b128 v[162:165], v0 offset:12288
	s_waitcnt vmcnt(7)
	ds_write_b128 v228, v[6:9] offset:16384
	global_load_dwordx4 v[6:9], v236, s[52:53]
	ds_read_b128 v[220:223], v191 offset:4096
	ds_read_b128 v[224:227], v191 offset:6144
	s_waitcnt lgkmcnt(9)
	v_mfma_f32_16x16x32_bf16 v[94:97], v[204:207], v[166:169], v[94:97]
	v_mfma_f32_16x16x32_bf16 v[90:93], v[204:207], v[170:173], v[90:93]
	v_mfma_f32_16x16x32_bf16 v[86:89], v[204:207], v[192:195], v[86:89]
	v_mfma_f32_16x16x32_bf16 v[82:85], v[204:207], v[196:199], v[82:85]
	ds_read_b128 v[204:207], v0 offset:14336
	s_waitcnt vmcnt(7)
	ds_write_b128 v228, v[18:21] offset:24576
	global_load_dwordx4 v[18:21], v237, s[52:53]
	s_waitcnt lgkmcnt(9)
	v_mfma_f32_16x16x32_bf16 v[78:81], v[208:211], v[166:169], v[78:81]
	v_mfma_f32_16x16x32_bf16 v[74:77], v[208:211], v[170:173], v[74:77]
	v_mfma_f32_16x16x32_bf16 v[70:73], v[208:211], v[192:195], v[70:73]
	v_mfma_f32_16x16x32_bf16 v[66:69], v[208:211], v[196:199], v[66:69]
	v_add_u32_e32 v0, v0, v190
	ds_read_b128 v[208:211], v0
	s_waitcnt vmcnt(7)
	ds_write_b128 v229, v[14:17]
	global_load_dwordx4 v[14:17], v234, s[66:67]
	s_waitcnt lgkmcnt(7)
	v_mfma_f32_16x16x32_bf16 v[62:65], v[162:165], v[166:169], v[62:65]
	v_mfma_f32_16x16x32_bf16 v[58:61], v[162:165], v[170:173], v[58:61]
	v_mfma_f32_16x16x32_bf16 v[54:57], v[162:165], v[192:195], v[54:57]
	v_mfma_f32_16x16x32_bf16 v[50:53], v[162:165], v[196:199], v[50:53]
	ds_read_b128 v[162:165], v0 offset:2048
	s_waitcnt vmcnt(7)
	ds_write_b128 v229, v[22:25] offset:8192
	global_load_dwordx4 v[22:25], v235, s[66:67]
	s_waitcnt lgkmcnt(5)
	v_mfma_f32_16x16x32_bf16 v[46:49], v[204:207], v[166:169], v[46:49]
	v_mfma_f32_16x16x32_bf16 v[42:45], v[204:207], v[170:173], v[42:45]
	v_mfma_f32_16x16x32_bf16 v[38:41], v[204:207], v[192:195], v[38:41]
	v_mfma_f32_16x16x32_bf16 v[34:37], v[204:207], v[196:199], v[34:37]
	ds_read_b128 v[204:207], v0 offset:4096
	s_waitcnt vmcnt(7)
	ds_write_b128 v229, v[26:29] offset:16384
	global_load_dwordx4 v[26:29], v236, s[66:67]
	s_waitcnt lgkmcnt(5)
	v_mfma_f32_16x16x32_bf16 v[158:161], v[208:211], v[212:215], v[158:161]
	v_mfma_f32_16x16x32_bf16 v[154:157], v[208:211], v[216:219], v[154:157]
	v_mfma_f32_16x16x32_bf16 v[150:153], v[208:211], v[220:223], v[150:153]
	v_mfma_f32_16x16x32_bf16 v[146:149], v[208:211], v[224:227], v[146:149]
	ds_read_b128 v[208:211], v0 offset:6144
	s_waitcnt vmcnt(7)
	ds_write_b128 v229, v[30:33] offset:24576
	global_load_dwordx4 v[30:33], v237, s[66:67]
	s_waitcnt lgkmcnt(5)
	v_mfma_f32_16x16x32_bf16 v[142:145], v[162:165], v[212:215], v[142:145]
	v_mfma_f32_16x16x32_bf16 v[138:141], v[162:165], v[216:219], v[138:141]
	v_mfma_f32_16x16x32_bf16 v[134:137], v[162:165], v[220:223], v[134:137]
	v_mfma_f32_16x16x32_bf16 v[130:133], v[162:165], v[224:227], v[130:133]
	ds_read_b128 v[162:165], v0 offset:8192
	s_waitcnt lgkmcnt(4)
	v_mfma_f32_16x16x32_bf16 v[126:129], v[204:207], v[212:215], v[126:129]
	v_mfma_f32_16x16x32_bf16 v[122:125], v[204:207], v[216:219], v[122:125]
	v_mfma_f32_16x16x32_bf16 v[118:121], v[204:207], v[220:223], v[118:121]
	v_mfma_f32_16x16x32_bf16 v[114:117], v[204:207], v[224:227], v[114:117]
	ds_read_b128 v[204:207], v0 offset:10240
	s_waitcnt lgkmcnt(3)
; template <int MI, int NJ> ...
;     ...
; #pragma unroll
;     for (int ks = 0; ks < 2; ++ks) {
;       const u16* a_ = ks ? a + dsw : a;
;       const u16* b_ = ks ? b + dsw : b;
;       bf16x8 bfr[NJ];
; #pragma unroll
;       for (int j = 0; j < NJ; ++j) bfr[j] = *(const bf16x8*)(b_ + j * 16 * 64);
; #pragma unroll
;       for (int ih = 0; ih < MI / 4; ++ih) {
;         bf16x8 af[4];
; #pragma unroll
;         for (int i = 0; i < 4; ++i) af[i] = *(const bf16x8*)(a_ + (ih * 4 + i) * 16 * 64);
; #pragma unroll
;         for (int i = 0; i < 4; ++i)
; #pragma unroll
;           for (int j = 0; j < NJ; ++j) acc[ih * 4 + i][j] = mfma16(af[i], bfr[j], acc[ih * 4 + i][j]);
;       }
;     }
;     __builtin_amdgcn_s_setprio(0);
;     __builtin_amdgcn_sched_barrier(0);
;     __syncthreads();
; __device__ __forceinline__ void phase_win(const Params& p, int part, u16* smem, volatile LAS unsigned* vb_) {
;     ...
; #pragma unroll
;     for (int i = 0; i < 8; ++i)
; #pragma unroll
;       for (int j = 0; j < 4; ++j)
; #pragma unroll
;         for (int r = 0; r < 4; ++r)
;           smem[(wm * 128 + i * 16 + (lane >> 4) * 4 + r) * 264 + wn * 64 + j * 16 + (lane & 15)] = f2bf(acc[i][j][r]);
	v_mfma_f32_16x16x32_bf16 v[110:113], v[208:211], v[212:215], v[110:113]
	v_mfma_f32_16x16x32_bf16 v[106:109], v[208:211], v[216:219], v[106:109]
	v_mfma_f32_16x16x32_bf16 v[102:105], v[208:211], v[220:223], v[102:105]
	v_mfma_f32_16x16x32_bf16 v[98:101], v[208:211], v[224:227], v[98:101]
	ds_read_b128 v[208:211], v0 offset:12288
	s_waitcnt lgkmcnt(2)
	v_mfma_f32_16x16x32_bf16 v[94:97], v[162:165], v[212:215], v[94:97]
	v_mfma_f32_16x16x32_bf16 v[90:93], v[162:165], v[216:219], v[90:93]
	v_mfma_f32_16x16x32_bf16 v[86:89], v[162:165], v[220:223], v[86:89]
	v_mfma_f32_16x16x32_bf16 v[82:85], v[162:165], v[224:227], v[82:85]
	ds_read_b128 v[162:165], v0 offset:14336
	s_waitcnt lgkmcnt(2)
	v_mfma_f32_16x16x32_bf16 v[78:81], v[204:207], v[212:215], v[78:81]
	v_mfma_f32_16x16x32_bf16 v[74:77], v[204:207], v[216:219], v[74:77]
	v_mfma_f32_16x16x32_bf16 v[70:73], v[204:207], v[220:223], v[70:73]
	v_mfma_f32_16x16x32_bf16 v[66:69], v[204:207], v[224:227], v[66:69]
	s_waitcnt lgkmcnt(1)
	v_mfma_f32_16x16x32_bf16 v[62:65], v[208:211], v[212:215], v[62:65]
	v_mfma_f32_16x16x32_bf16 v[58:61], v[208:211], v[216:219], v[58:61]
	v_mfma_f32_16x16x32_bf16 v[54:57], v[208:211], v[220:223], v[54:57]
	v_mfma_f32_16x16x32_bf16 v[50:53], v[208:211], v[224:227], v[50:53]
	s_waitcnt lgkmcnt(0)
	v_mfma_f32_16x16x32_bf16 v[46:49], v[162:165], v[212:215], v[46:49]
	v_mfma_f32_16x16x32_bf16 v[42:45], v[162:165], v[216:219], v[42:45]
	v_mfma_f32_16x16x32_bf16 v[38:41], v[162:165], v[220:223], v[38:41]
	v_mfma_f32_16x16x32_bf16 v[34:37], v[162:165], v[224:227], v[34:37]
	s_setprio 0
	s_add_i32 s37, s37, 1
	s_add_u32 s20, s20, 64
	s_addc_u32 s21, s21, 0
	s_addk_i32 s11, 0x4000
	s_cmpk_lg_i32 s20, 0x480
	s_barrier
	s_cbranch_scc1 .LBB0_470
	v_cvt_pk_bf16_f32 v0, v158, s0
	ds_write_b16 v189, v0
	v_cvt_pk_bf16_f32 v0, v159, s0
	ds_write_b16 v189, v0 offset:528
	v_cvt_pk_bf16_f32 v0, v160, s0
	ds_write_b16 v189, v0 offset:1056
	v_cvt_pk_bf16_f32 v0, v161, s0
	ds_write_b16 v189, v0 offset:1584
	v_cvt_pk_bf16_f32 v0, v154, s0
	ds_write_b16 v189, v0 offset:32
	v_cvt_pk_bf16_f32 v0, v155, s0
	ds_write_b16 v189, v0 offset:560
	v_cvt_pk_bf16_f32 v0, v156, s0
	ds_write_b16 v189, v0 offset:1088
	v_cvt_pk_bf16_f32 v0, v157, s0
	ds_write_b16 v189, v0 offset:1616
	v_cvt_pk_bf16_f32 v0, v150, s0
	ds_write_b16 v189, v0 offset:64
	v_cvt_pk_bf16_f32 v0, v151, s0
	ds_write_b16 v189, v0 offset:592
	v_cvt_pk_bf16_f32 v0, v152, s0
	ds_write_b16 v189, v0 offset:1120
	v_cvt_pk_bf16_f32 v0, v153, s0
	ds_write_b16 v189, v0 offset:1648
	v_cvt_pk_bf16_f32 v0, v146, s0
	ds_write_b16 v189, v0 offset:96
	v_cvt_pk_bf16_f32 v0, v147, s0
	ds_write_b16 v189, v0 offset:624
	v_cvt_pk_bf16_f32 v0, v148, s0
	ds_write_b16 v189, v0 offset:1152
	v_cvt_pk_bf16_f32 v0, v149, s0
	ds_write_b16 v189, v0 offset:1680
	v_cvt_pk_bf16_f32 v0, v142, s0
	ds_write_b16 v189, v0 offset:8448
	v_cvt_pk_bf16_f32 v0, v143, s0
	ds_write_b16 v189, v0 offset:8976
	v_cvt_pk_bf16_f32 v0, v144, s0
	ds_write_b16 v189, v0 offset:9504
	v_cvt_pk_bf16_f32 v0, v145, s0
	ds_write_b16 v189, v0 offset:10032
	v_cvt_pk_bf16_f32 v0, v138, s0
	ds_write_b16 v189, v0 offset:8480
	v_cvt_pk_bf16_f32 v0, v139, s0
	ds_write_b16 v189, v0 offset:9008
	v_cvt_pk_bf16_f32 v0, v140, s0
	ds_write_b16 v189, v0 offset:9536
	v_cvt_pk_bf16_f32 v0, v141, s0
	ds_write_b16 v189, v0 offset:10064
	v_cvt_pk_bf16_f32 v0, v134, s0
	ds_write_b16 v189, v0 offset:8512
	v_cvt_pk_bf16_f32 v0, v135, s0
	ds_write_b16 v189, v0 offset:9040
	v_cvt_pk_bf16_f32 v0, v136, s0
	ds_write_b16 v189, v0 offset:9568
	v_cvt_pk_bf16_f32 v0, v137, s0
	ds_write_b16 v189, v0 offset:10096
	v_cvt_pk_bf16_f32 v0, v130, s0
	ds_write_b16 v189, v0 offset:8544
	v_cvt_pk_bf16_f32 v0, v131, s0
	ds_write_b16 v189, v0 offset:9072
	v_cvt_pk_bf16_f32 v0, v132, s0
	ds_write_b16 v189, v0 offset:9600
	v_cvt_pk_bf16_f32 v0, v133, s0
	ds_write_b16 v189, v0 offset:10128
	v_cvt_pk_bf16_f32 v0, v126, s0
	ds_write_b16 v189, v0 offset:16896
	v_cvt_pk_bf16_f32 v0, v127, s0
	ds_write_b16 v189, v0 offset:17424
	v_cvt_pk_bf16_f32 v0, v128, s0
	ds_write_b16 v189, v0 offset:17952
	v_cvt_pk_bf16_f32 v0, v129, s0
	ds_write_b16 v189, v0 offset:18480
	v_cvt_pk_bf16_f32 v0, v122, s0
	ds_write_b16 v189, v0 offset:16928
	v_cvt_pk_bf16_f32 v0, v123, s0
	ds_write_b16 v189, v0 offset:17456
	v_cvt_pk_bf16_f32 v0, v124, s0
	ds_write_b16 v189, v0 offset:17984
	v_cvt_pk_bf16_f32 v0, v125, s0
	ds_write_b16 v189, v0 offset:18512
	v_cvt_pk_bf16_f32 v0, v118, s0
	ds_write_b16 v189, v0 offset:16960
	v_cvt_pk_bf16_f32 v0, v119, s0
	ds_write_b16 v189, v0 offset:17488
	v_cvt_pk_bf16_f32 v0, v120, s0
	ds_write_b16 v189, v0 offset:18016
	v_cvt_pk_bf16_f32 v0, v121, s0
	ds_write_b16 v189, v0 offset:18544
	v_cvt_pk_bf16_f32 v0, v114, s0
	ds_write_b16 v189, v0 offset:16992
	v_cvt_pk_bf16_f32 v0, v115, s0
	ds_write_b16 v189, v0 offset:17520
	v_cvt_pk_bf16_f32 v0, v116, s0
	ds_write_b16 v189, v0 offset:18048
	v_cvt_pk_bf16_f32 v0, v117, s0
	ds_write_b16 v189, v0 offset:18576
	v_cvt_pk_bf16_f32 v0, v110, s0
	ds_write_b16 v189, v0 offset:25344
	v_cvt_pk_bf16_f32 v0, v111, s0
	ds_write_b16 v189, v0 offset:25872
	v_cvt_pk_bf16_f32 v0, v112, s0
	ds_write_b16 v189, v0 offset:26400
	v_cvt_pk_bf16_f32 v0, v113, s0
	ds_write_b16 v189, v0 offset:26928
	v_cvt_pk_bf16_f32 v0, v106, s0
	ds_write_b16 v189, v0 offset:25376
	v_cvt_pk_bf16_f32 v0, v107, s0
	ds_write_b16 v189, v0 offset:25904
	v_cvt_pk_bf16_f32 v0, v108, s0
	ds_write_b16 v189, v0 offset:26432
	v_cvt_pk_bf16_f32 v0, v109, s0
	ds_write_b16 v189, v0 offset:26960
	v_cvt_pk_bf16_f32 v0, v102, s0
	ds_write_b16 v189, v0 offset:25408
	v_cvt_pk_bf16_f32 v0, v103, s0
	ds_write_b16 v189, v0 offset:25936
; __device__ __forceinline__ void phase_win(const Params& p, int part, u16* smem, volatile LAS unsigned* vb_) {
;     ...
; #pragma unroll
;     for (int i = 0; i < 8; ++i)
; #pragma unroll
;       for (int j = 0; j < 4; ++j)
; #pragma unroll
;         for (int r = 0; r < 4; ++r)
;           smem[(wm * 128 + i * 16 + (lane >> 4) * 4 + r) * 264 + wn * 64 + j * 16 + (lane & 15)] = f2bf(acc[i][j][r]);
;     __syncthreads();
	v_cvt_pk_bf16_f32 v0, v104, s0
	ds_write_b16 v189, v0 offset:26464
	v_cvt_pk_bf16_f32 v0, v105, s0
	ds_write_b16 v189, v0 offset:26992
	v_cvt_pk_bf16_f32 v0, v98, s0
	ds_write_b16 v189, v0 offset:25440
	v_cvt_pk_bf16_f32 v0, v99, s0
	ds_write_b16 v189, v0 offset:25968
	v_cvt_pk_bf16_f32 v0, v100, s0
	ds_write_b16 v189, v0 offset:26496
	v_cvt_pk_bf16_f32 v0, v101, s0
	ds_write_b16 v189, v0 offset:27024
	v_cvt_pk_bf16_f32 v0, v94, s0
	ds_write_b16 v189, v0 offset:33792
	v_cvt_pk_bf16_f32 v0, v95, s0
	ds_write_b16 v189, v0 offset:34320
	v_cvt_pk_bf16_f32 v0, v96, s0
	ds_write_b16 v189, v0 offset:34848
	v_cvt_pk_bf16_f32 v0, v97, s0
	ds_write_b16 v189, v0 offset:35376
	v_cvt_pk_bf16_f32 v0, v90, s0
	ds_write_b16 v189, v0 offset:33824
	v_cvt_pk_bf16_f32 v0, v91, s0
	ds_write_b16 v189, v0 offset:34352
	v_cvt_pk_bf16_f32 v0, v92, s0
	ds_write_b16 v189, v0 offset:34880
	v_cvt_pk_bf16_f32 v0, v93, s0
	ds_write_b16 v189, v0 offset:35408
	v_cvt_pk_bf16_f32 v0, v86, s0
	ds_write_b16 v189, v0 offset:33856
	v_cvt_pk_bf16_f32 v0, v87, s0
	ds_write_b16 v189, v0 offset:34384
	v_cvt_pk_bf16_f32 v0, v88, s0
	ds_write_b16 v189, v0 offset:34912
	v_cvt_pk_bf16_f32 v0, v89, s0
	ds_write_b16 v189, v0 offset:35440
	v_cvt_pk_bf16_f32 v0, v82, s0
	ds_write_b16 v189, v0 offset:33888
	v_cvt_pk_bf16_f32 v0, v83, s0
	ds_write_b16 v189, v0 offset:34416
	v_cvt_pk_bf16_f32 v0, v84, s0
	ds_write_b16 v189, v0 offset:34944
	v_cvt_pk_bf16_f32 v0, v85, s0
	ds_write_b16 v189, v0 offset:35472
	v_cvt_pk_bf16_f32 v0, v78, s0
	ds_write_b16 v189, v0 offset:42240
	v_cvt_pk_bf16_f32 v0, v79, s0
	ds_write_b16 v189, v0 offset:42768
	v_cvt_pk_bf16_f32 v0, v80, s0
	ds_write_b16 v189, v0 offset:43296
	v_cvt_pk_bf16_f32 v0, v81, s0
	ds_write_b16 v189, v0 offset:43824
	v_cvt_pk_bf16_f32 v0, v74, s0
	ds_write_b16 v189, v0 offset:42272
	v_cvt_pk_bf16_f32 v0, v75, s0
	ds_write_b16 v189, v0 offset:42800
	v_cvt_pk_bf16_f32 v0, v76, s0
	ds_write_b16 v189, v0 offset:43328
	v_cvt_pk_bf16_f32 v0, v77, s0
	ds_write_b16 v189, v0 offset:43856
	v_cvt_pk_bf16_f32 v0, v70, s0
	ds_write_b16 v189, v0 offset:42304
	v_cvt_pk_bf16_f32 v0, v71, s0
	ds_write_b16 v189, v0 offset:42832
	v_cvt_pk_bf16_f32 v0, v72, s0
	ds_write_b16 v189, v0 offset:43360
	v_cvt_pk_bf16_f32 v0, v73, s0
	ds_write_b16 v189, v0 offset:43888
	v_cvt_pk_bf16_f32 v0, v66, s0
	ds_write_b16 v189, v0 offset:42336
	v_cvt_pk_bf16_f32 v0, v67, s0
	ds_write_b16 v189, v0 offset:42864
	v_cvt_pk_bf16_f32 v0, v68, s0
	ds_write_b16 v189, v0 offset:43392
	v_cvt_pk_bf16_f32 v0, v69, s0
	ds_write_b16 v189, v0 offset:43920
	v_cvt_pk_bf16_f32 v0, v62, s0
	ds_write_b16 v189, v0 offset:50688
	v_cvt_pk_bf16_f32 v0, v63, s0
	ds_write_b16 v189, v0 offset:51216
	v_cvt_pk_bf16_f32 v0, v64, s0
	ds_write_b16 v189, v0 offset:51744
	v_cvt_pk_bf16_f32 v0, v65, s0
	ds_write_b16 v189, v0 offset:52272
	v_cvt_pk_bf16_f32 v0, v58, s0
	ds_write_b16 v189, v0 offset:50720
	v_cvt_pk_bf16_f32 v0, v59, s0
	ds_write_b16 v189, v0 offset:51248
	v_cvt_pk_bf16_f32 v0, v60, s0
	ds_write_b16 v189, v0 offset:51776
	v_cvt_pk_bf16_f32 v0, v61, s0
	ds_write_b16 v189, v0 offset:52304
	v_cvt_pk_bf16_f32 v0, v54, s0
	ds_write_b16 v189, v0 offset:50752
	v_cvt_pk_bf16_f32 v0, v55, s0
	ds_write_b16 v189, v0 offset:51280
	v_cvt_pk_bf16_f32 v0, v56, s0
	ds_write_b16 v189, v0 offset:51808
	v_cvt_pk_bf16_f32 v0, v57, s0
	ds_write_b16 v189, v0 offset:52336
	v_cvt_pk_bf16_f32 v0, v50, s0
	ds_write_b16 v189, v0 offset:50784
	v_cvt_pk_bf16_f32 v0, v51, s0
	ds_write_b16 v189, v0 offset:51312
	v_cvt_pk_bf16_f32 v0, v52, s0
	ds_write_b16 v189, v0 offset:51840
	v_cvt_pk_bf16_f32 v0, v53, s0
	ds_write_b16 v189, v0 offset:52368
	v_cvt_pk_bf16_f32 v0, v46, s0
	ds_write_b16 v189, v0 offset:59136
	v_cvt_pk_bf16_f32 v0, v47, s0
	ds_write_b16 v189, v0 offset:59664
	v_cvt_pk_bf16_f32 v0, v48, s0
	ds_write_b16 v189, v0 offset:60192
	v_cvt_pk_bf16_f32 v0, v49, s0
	ds_write_b16 v189, v0 offset:60720
	v_cvt_pk_bf16_f32 v0, v42, s0
	ds_write_b16 v189, v0 offset:59168
	v_cvt_pk_bf16_f32 v0, v43, s0
	ds_write_b16 v189, v0 offset:59696
	v_cvt_pk_bf16_f32 v0, v44, s0
	ds_write_b16 v189, v0 offset:60224
	v_cvt_pk_bf16_f32 v0, v45, s0
	ds_write_b16 v189, v0 offset:60752
	v_cvt_pk_bf16_f32 v0, v38, s0
	ds_write_b16 v189, v0 offset:59200
	v_cvt_pk_bf16_f32 v0, v39, s0
	ds_write_b16 v189, v0 offset:59728
	v_cvt_pk_bf16_f32 v0, v40, s0
	ds_write_b16 v189, v0 offset:60256
	v_cvt_pk_bf16_f32 v0, v41, s0
	ds_write_b16 v189, v0 offset:60784
	v_cvt_pk_bf16_f32 v0, v34, s0
	ds_write_b16 v189, v0 offset:59232
	v_cvt_pk_bf16_f32 v0, v35, s0
	ds_write_b16 v189, v0 offset:59760
	v_cvt_pk_bf16_f32 v0, v36, s0
	ds_write_b16 v189, v0 offset:60288
	v_cvt_pk_bf16_f32 v0, v37, s0
	v_mov_b32_e32 v43, v175
	ds_write_b16 v189, v0 offset:60816
	s_waitcnt lgkmcnt(0)
	s_barrier
; #define RTID opaque_tid()
; __device__ __forceinline__ void phase_win(const Params& p, int part, u16* smem, volatile LAS unsigned* vb_) {
;     ...
;     const int tid2 = RTID;
; #pragma unroll
;     for (int k = 0; k < 16; ++k) {
;       const int c = tid2 + 512 * k;
;       const int row = c >> 5, ch = c & 31;
;       const uint4 v = *(const uint4*)(smem + row * 264 + ch * 8);
;       u16* d_ = (ch < 16) ? dstA : dstB;
;       const int l_ = (ch < 16) ? ldA : ldB;
;       *(uint4*)(d_ + (size_t)(mt * 256 + row) * l_ + (ch & 15) * 8) = v;
;     }
;     __syncthreads();
	s_mov_b32 s38, s36
	v_and_b32_e32 v0, 31, v43
	v_lshlrev_b32_e32 v42, 4, v0
	v_cmp_gt_u32_e32 vcc, 16, v0
	v_mov_b32_e32 v0, 0x100
	s_nop 0
	v_cndmask_b32_e64 v0, v0, 0, vcc
	v_lshl_add_u64 v[34:35], s[44:45], 0, v[0:1]
	v_lshlrev_b32_e32 v0, 4, v43
	v_and_b32_e32 v0, 0xf0, v0
	v_lshl_add_u64 v[44:45], v[34:35], 0, v[0:1]
	v_ashrrev_i32_e32 v0, 5, v43
	v_mad_u64_u32 v[34:35], s[12:13], v0, s2, v[42:43]
	v_add_u32_e32 v0, s10, v0
	ds_read_b128 v[34:37], v34
	v_ashrrev_i32_e32 v38, 31, v0
	v_mul_lo_u32 v40, s0, v38
	v_mul_lo_u32 v41, s1, v0
	v_mad_u64_u32 v[38:39], s[12:13], s0, v0, 0
	v_add_u32_e32 v0, 0x200, v43
	v_add3_u32 v39, v39, v40, v41
	v_ashrrev_i32_e32 v0, 5, v0
	v_lshl_add_u64 v[46:47], v[38:39], 1, v[44:45]
	v_mad_u64_u32 v[38:39], s[12:13], v0, s2, v[42:43]
	ds_read_b128 v[38:41], v38
	v_add_u32_e32 v0, s10, v0
	s_waitcnt lgkmcnt(1)
	global_store_dwordx4 v[46:47], v[34:37], off
	s_and_b64 vcc, exec, s[42:43]
	s_nop 0
	v_ashrrev_i32_e32 v34, 31, v0
	v_mul_lo_u32 v36, s0, v34
	v_mul_lo_u32 v37, s1, v0
	v_mad_u64_u32 v[34:35], s[12:13], s0, v0, 0
	v_add3_u32 v35, v35, v36, v37
	v_add_u32_e32 v0, 0x400, v43
	v_lshl_add_u64 v[34:35], v[34:35], 1, v[44:45]
	v_ashrrev_i32_e32 v0, 5, v0
	s_waitcnt lgkmcnt(0)
	global_store_dwordx4 v[34:35], v[38:41], off
	v_mad_u64_u32 v[34:35], s[12:13], v0, s2, v[42:43]
	v_add_u32_e32 v0, s10, v0
	ds_read_b128 v[34:37], v34
	v_ashrrev_i32_e32 v38, 31, v0
	v_mul_lo_u32 v40, s0, v38
	v_mul_lo_u32 v41, s1, v0
	v_mad_u64_u32 v[38:39], s[12:13], s0, v0, 0
	v_add_u32_e32 v0, 0x600, v43
	v_add3_u32 v39, v39, v40, v41
	v_ashrrev_i32_e32 v0, 5, v0
	v_lshl_add_u64 v[46:47], v[38:39], 1, v[44:45]
	v_mad_u64_u32 v[38:39], s[12:13], v0, s2, v[42:43]
	ds_read_b128 v[38:41], v38
	v_add_u32_e32 v0, s10, v0
	s_waitcnt lgkmcnt(1)
	global_store_dwordx4 v[46:47], v[34:37], off
	s_nop 1
	v_ashrrev_i32_e32 v34, 31, v0
	v_mul_lo_u32 v36, s0, v34
	v_mul_lo_u32 v37, s1, v0
	v_mad_u64_u32 v[34:35], s[12:13], s0, v0, 0
	v_add3_u32 v35, v35, v36, v37
	v_add_u32_e32 v0, 0x800, v43
	v_lshl_add_u64 v[34:35], v[34:35], 1, v[44:45]
	v_ashrrev_i32_e32 v0, 5, v0
	s_waitcnt lgkmcnt(0)
	global_store_dwordx4 v[34:35], v[38:41], off
	v_mad_u64_u32 v[34:35], s[12:13], v0, s2, v[42:43]
	v_add_u32_e32 v0, s10, v0
	ds_read_b128 v[34:37], v34
	v_ashrrev_i32_e32 v38, 31, v0
	v_mul_lo_u32 v40, s0, v38
	v_mul_lo_u32 v41, s1, v0
	v_mad_u64_u32 v[38:39], s[12:13], s0, v0, 0
	v_add_u32_e32 v0, 0xa00, v43
	v_add3_u32 v39, v39, v40, v41
	v_ashrrev_i32_e32 v0, 5, v0
	v_lshl_add_u64 v[46:47], v[38:39], 1, v[44:45]
	v_mad_u64_u32 v[38:39], s[12:13], v0, s2, v[42:43]
	ds_read_b128 v[38:41], v38
	v_add_u32_e32 v0, s10, v0
	s_waitcnt lgkmcnt(1)
	global_store_dwordx4 v[46:47], v[34:37], off
	s_nop 1
	v_ashrrev_i32_e32 v34, 31, v0
	v_mul_lo_u32 v36, s0, v34
	v_mul_lo_u32 v37, s1, v0
	v_mad_u64_u32 v[34:35], s[12:13], s0, v0, 0
	v_add3_u32 v35, v35, v36, v37
	v_add_u32_e32 v0, 0xc00, v43
	v_lshl_add_u64 v[34:35], v[34:35], 1, v[44:45]
	v_ashrrev_i32_e32 v0, 5, v0
	s_waitcnt lgkmcnt(0)
	global_store_dwordx4 v[34:35], v[38:41], off
	v_mad_u64_u32 v[34:35], s[12:13], v0, s2, v[42:43]
	v_add_u32_e32 v0, s10, v0
	ds_read_b128 v[34:37], v34
	v_ashrrev_i32_e32 v38, 31, v0
	v_mul_lo_u32 v40, s0, v38
	v_mul_lo_u32 v41, s1, v0
	v_mad_u64_u32 v[38:39], s[12:13], s0, v0, 0
	v_add_u32_e32 v0, 0xe00, v43
	v_add3_u32 v39, v39, v40, v41
	v_ashrrev_i32_e32 v0, 5, v0
	v_lshl_add_u64 v[46:47], v[38:39], 1, v[44:45]
	v_mad_u64_u32 v[38:39], s[12:13], v0, s2, v[42:43]
	ds_read_b128 v[38:41], v38
	v_add_u32_e32 v0, s10, v0
	s_waitcnt lgkmcnt(1)
	global_store_dwordx4 v[46:47], v[34:37], off
	s_nop 1
	v_ashrrev_i32_e32 v34, 31, v0
	v_mul_lo_u32 v36, s0, v34
	v_mul_lo_u32 v37, s1, v0
	v_mad_u64_u32 v[34:35], s[12:13], s0, v0, 0
	v_add3_u32 v35, v35, v36, v37
	v_add_u32_e32 v0, 0x1000, v43
	v_lshl_add_u64 v[34:35], v[34:35], 1, v[44:45]
	v_ashrrev_i32_e32 v0, 5, v0
	s_waitcnt lgkmcnt(0)
; #define RTID opaque_tid()
; __device__ __forceinline__ void phase_win(const Params& p, int part, u16* smem, volatile LAS unsigned* vb_) {
;     ...
;     const int tid2 = RTID;
; #pragma unroll
;     for (int k = 0; k < 16; ++k) {
;       const int c = tid2 + 512 * k;
;       const int row = c >> 5, ch = c & 31;
;       const uint4 v = *(const uint4*)(smem + row * 264 + ch * 8);
;       u16* d_ = (ch < 16) ? dstA : dstB;
;       const int l_ = (ch < 16) ? ldA : ldB;
;       *(uint4*)(d_ + (size_t)(mt * 256 + row) * l_ + (ch & 15) * 8) = v;
;     }
;     __syncthreads();
;   }
	global_store_dwordx4 v[34:35], v[38:41], off
	v_mad_u64_u32 v[34:35], s[12:13], v0, s2, v[42:43]
	v_add_u32_e32 v0, s10, v0
	ds_read_b128 v[34:37], v34
	v_ashrrev_i32_e32 v38, 31, v0
	v_mul_lo_u32 v40, s0, v38
	v_mul_lo_u32 v41, s1, v0
	v_mad_u64_u32 v[38:39], s[12:13], s0, v0, 0
	v_add_u32_e32 v0, 0x1200, v43
	v_add3_u32 v39, v39, v40, v41
	v_ashrrev_i32_e32 v0, 5, v0
	v_lshl_add_u64 v[46:47], v[38:39], 1, v[44:45]
	v_mad_u64_u32 v[38:39], s[12:13], v0, s2, v[42:43]
	ds_read_b128 v[38:41], v38
	v_add_u32_e32 v0, s10, v0
	s_waitcnt lgkmcnt(1)
	global_store_dwordx4 v[46:47], v[34:37], off
	s_nop 1
	v_ashrrev_i32_e32 v34, 31, v0
	v_mul_lo_u32 v36, s0, v34
	v_mul_lo_u32 v37, s1, v0
	v_mad_u64_u32 v[34:35], s[12:13], s0, v0, 0
	v_add3_u32 v35, v35, v36, v37
	v_add_u32_e32 v0, 0x1400, v43
	v_lshl_add_u64 v[34:35], v[34:35], 1, v[44:45]
	v_ashrrev_i32_e32 v0, 5, v0
	s_waitcnt lgkmcnt(0)
	global_store_dwordx4 v[34:35], v[38:41], off
	v_mad_u64_u32 v[34:35], s[12:13], v0, s2, v[42:43]
	v_add_u32_e32 v0, s10, v0
	ds_read_b128 v[34:37], v34
	v_ashrrev_i32_e32 v38, 31, v0
	v_mul_lo_u32 v40, s0, v38
	v_mul_lo_u32 v41, s1, v0
	v_mad_u64_u32 v[38:39], s[12:13], s0, v0, 0
	v_add_u32_e32 v0, 0x1600, v43
	v_add3_u32 v39, v39, v40, v41
	v_ashrrev_i32_e32 v0, 5, v0
	v_lshl_add_u64 v[46:47], v[38:39], 1, v[44:45]
	v_mad_u64_u32 v[38:39], s[12:13], v0, s2, v[42:43]
	ds_read_b128 v[38:41], v38
	v_add_u32_e32 v0, s10, v0
	s_waitcnt lgkmcnt(1)
	global_store_dwordx4 v[46:47], v[34:37], off
	s_nop 1
	v_ashrrev_i32_e32 v34, 31, v0
	v_mul_lo_u32 v36, s0, v34
	v_mul_lo_u32 v37, s1, v0
	v_mad_u64_u32 v[34:35], s[12:13], s0, v0, 0
	v_add3_u32 v35, v35, v36, v37
	v_add_u32_e32 v0, 0x1800, v43
	v_lshl_add_u64 v[34:35], v[34:35], 1, v[44:45]
	v_ashrrev_i32_e32 v0, 5, v0
	s_waitcnt lgkmcnt(0)
	global_store_dwordx4 v[34:35], v[38:41], off
	v_mad_u64_u32 v[34:35], s[12:13], v0, s2, v[42:43]
	v_add_u32_e32 v0, s10, v0
	ds_read_b128 v[34:37], v34
	v_ashrrev_i32_e32 v38, 31, v0
	v_mul_lo_u32 v40, s0, v38
	v_mul_lo_u32 v41, s1, v0
	v_mad_u64_u32 v[38:39], s[12:13], s0, v0, 0
	v_add_u32_e32 v0, 0x1a00, v43
	v_add3_u32 v39, v39, v40, v41
	v_ashrrev_i32_e32 v0, 5, v0
	v_lshl_add_u64 v[46:47], v[38:39], 1, v[44:45]
	v_mad_u64_u32 v[38:39], s[12:13], v0, s2, v[42:43]
	ds_read_b128 v[38:41], v38
	v_add_u32_e32 v0, s10, v0
	s_waitcnt lgkmcnt(1)
	global_store_dwordx4 v[46:47], v[34:37], off
	s_nop 1
	v_ashrrev_i32_e32 v34, 31, v0
	v_mul_lo_u32 v36, s0, v34
	v_mul_lo_u32 v37, s1, v0
	v_mad_u64_u32 v[34:35], s[12:13], s0, v0, 0
	v_add3_u32 v35, v35, v36, v37
	v_add_u32_e32 v0, 0x1c00, v43
	v_lshl_add_u64 v[34:35], v[34:35], 1, v[44:45]
	v_ashrrev_i32_e32 v0, 5, v0
	s_waitcnt lgkmcnt(0)
	global_store_dwordx4 v[34:35], v[38:41], off
	v_mad_u64_u32 v[34:35], s[12:13], v0, s2, v[42:43]
	v_add_u32_e32 v0, s10, v0
	ds_read_b128 v[34:37], v34
	v_ashrrev_i32_e32 v38, 31, v0
	v_mul_lo_u32 v40, s0, v38
	v_mul_lo_u32 v41, s1, v0
	v_mad_u64_u32 v[38:39], s[12:13], s0, v0, 0
	v_add_u32_e32 v0, 0x1e00, v43
	v_add3_u32 v39, v39, v40, v41
	v_ashrrev_i32_e32 v0, 5, v0
	v_lshl_add_u64 v[46:47], v[38:39], 1, v[44:45]
	v_mad_u64_u32 v[38:39], s[12:13], v0, s2, v[42:43]
	ds_read_b128 v[38:41], v38
	v_add_u32_e32 v0, s10, v0
	s_waitcnt lgkmcnt(1)
	global_store_dwordx4 v[46:47], v[34:37], off
	s_mov_b64 s[12:13], -1
	s_nop 0
	v_ashrrev_i32_e32 v34, 31, v0
	v_mul_lo_u32 v36, s0, v34
	v_mul_lo_u32 v37, s1, v0
	v_mad_u64_u32 v[34:35], s[0:1], s0, v0, 0
	v_add3_u32 v35, v35, v36, v37
	v_lshl_add_u64 v[34:35], v[34:35], 1, v[44:45]
	s_waitcnt lgkmcnt(0)
	global_store_dwordx4 v[34:35], v[38:41], off
	s_barrier
	s_cbranch_vccz .LBB0_441
.LBB0_472:
	s_waitcnt vmcnt(0)
	s_mov_b64 s[12:13], 0

; #define RTID opaque_tid()
; #define ZERO_ACC8(acc, NJ_)                             \
;   _Pragma("unroll") for (int i_ = 0; i_ < 8; ++i_)      \
;   _Pragma("unroll") for (int j_ = 0; j_ < (NJ_); ++j_) { acc[i_][j_] = (f32x4){0.f, 0.f, 0.f, 0.f}; }
; template <int MI, int NJ> ...
;     ...
;   const int lrow = tid >> 3, lkc = tid & 7;
;   const u16* Ag = A + (size_t)(row0 + lrow) * lda + kbeg + lkc * 8;
;   const u16* Bg = Bt + (size_t)(col0 + lrow) * ldb + kbeg + lkc * 8;
;   const size_t a64 = (size_t)64 * lda, b64 = (size_t)64 * ldb;
;   const int nk = (kend - kbeg) >> 6;
;   const long long nAoff = (long long)(nrow0 - row0) * lda + (nkbeg - kbeg);
;   const long long nBoff = (long long)(ncol0 - col0) * ldb + (nkbeg - kbeg);
;   u16* wa = sA + lrow * 64 + ((lkc ^ (lrow & 7)) * 8);
;   u16* wb = sB + lrow * 64 + ((lkc ^ (lrow & 7)) * 8);
;     ...
;   if (!pre) G8LOADP(Ag, Bg);
;   G8STORE(0);
;   {
;     const u16* ga_ = (1 < nk) ? Ag + 64 : Ag + nAoff;
;     const u16* gb_ = (1 < nk) ? Bg + 64 : Bg + nBoff;
;     G8LOADP(ga_, gb_);
;   }
;   __syncthreads();
; __device__ __forceinline__ void phase_gemm_f32(const u16* A, const u16* Bt, int K, u16* out, u16* smem,
;                                                volatile LAS unsigned* vb_) {
;   const int tid = RTID;
;   const int lane = tid & 63, wave = tid >> 6;
;   const int wm = wave >> 2, wn = wave & 3;
;   const int vb = real_vb(vb_);
;   G8REGS_DECL;
;   R_b1 = R_b2 = R_b3 = make_uint4(0u, 0u, 0u, 0u);
;   const int step = gridDim.x >> 3;
;   bool pre = false;
;   for (int lt = vb >> 3; lt < 8 * 4; lt += step) {
;     const int nt = lt >> 3, mt = (vb & 7) * 8 + (lt & 7);
;     const int ltn = (lt + step < 8 * 4) ? lt + step : lt;
;     f32x4 acc[8][4];
;     ZERO_ACC8(acc, 4);
;     gemm8<8, 4>(acc, G8REGS_ARGS, pre, A, K, Bt, K, 0, K, mt * 256, nt * 256, ((vb & 7) * 8 + (ltn & 7)) * 256, (ltn >> 3) * 256, 0, smem, tid);
.LBB0_475:
	s_nop 0
	v_readlane_b32 s0, v255, 4
	v_readlane_b32 s1, v255, 5
	s_and_b64 vcc, exec, s[0:1]
	s_cbranch_vccz .LBB0_484
	s_waitcnt vmcnt(15)
	v_mov_b32_e32 v2, v175
	ds_read_b32 v0, v230
	s_waitcnt lgkmcnt(0)
	v_readfirstlane_b32 s0, v0
	s_ashr_i32 s37, s0, 3
	s_cmp_gt_i32 s37, 31
	s_cbranch_scc1 .LBB0_483
	s_cmp_eq_u32 s82, 10
	s_movk_i32 s1, 0xb00
	s_cselect_b32 s10, 0x400, s1
	s_mov_b32 s1, 0x3810000
	s_cselect_b32 s1, s1, 0x5810000
	s_cmp_eq_u32 s82, 1
	s_mov_b32 s11, 0xb00000
	s_cselect_b32 s11, s11, 0x1b80000
	s_cmp_eq_u32 s82, 10
	s_mov_b32 s12, 0xf010000
	s_cselect_b32 s12, s12, 0xb010000
	s_cselect_b32 s13, 0x3400000, s11
	s_add_u32 s11, s72, s12
	s_addc_u32 s20, s73, 0
	s_add_u32 s12, s72, s13
	s_addc_u32 s13, s73, 0
	s_add_u32 s38, s72, s1
	v_lshlrev_b32_e32 v0, 4, v2
	s_addc_u32 s39, s73, 0
	v_ashrrev_i32_e32 v184, 3, v2
	v_and_b32_e32 v0, 0x70, v0
	v_and_b32_e32 v234, 7, v184
	s_lshl_b32 s48, s10, 1
	s_lshl_b32 s49, s10, 7
	v_mul_lo_u32 v234, v234, s48
	v_add_u32_e32 v234, v234, v0
	v_add_u32_e32 v235, s49, v234
	v_add_u32_e32 v236, s49, v235
	v_add_u32_e32 v237, s49, v236
	v_lshl_add_u64 v[176:177], s[38:39], 0, v[0:1]
	v_lshl_add_u64 v[178:179], s[12:13], 0, v[0:1]
	v_xor_b32_e32 v0, v184, v2
	v_lshlrev_b32_e32 v0, 4, v0
	v_and_b32_e32 v0, 0x70, v0
	v_lshl_or_b32 v185, v184, 7, v0
	v_lshrrev_b32_e32 v0, 4, v2
	v_and_b32_e32 v3, 7, v2
	v_bitop3_b32 v0, v0, v3, 3 bitop3:0x6c
	v_lshlrev_b32_e32 v3, 3, v0
	v_xor_b32_e32 v4, 32, v3
	v_sub_u32_e32 v3, v4, v3
	v_ashrrev_i32_e32 v4, 1, v2
	v_and_b32_e32 v4, 0xffffff80, v4
	v_and_or_b32 v5, v2, 15, v4
	v_lshlrev_b32_e32 v0, 4, v0
	s_lshl_b32 s0, s0, 3
	v_lshl_or_b32 v187, v5, 7, v0
	v_lshlrev_b32_e32 v5, 7, v2
	s_and_b32 s22, s0, 56
	v_and_b32_e32 v5, 0x6780, v5
	s_mov_b32 s0, 0x10000
	v_or3_b32 v188, v5, v0, s0
	v_lshrrev_b32_e32 v0, 2, v2
	v_and_or_b32 v0, v0, 12, v4
	v_and_b32_e32 v2, 0xcf, v2
	v_mul_lo_u32 v0, v0, s2
	s_lshl_b32 s23, s10, 6
	v_lshl_add_u32 v189, v2, 1, v0
	v_mov_b32_e32 v0, v1
	s_lshr_b32 s21, s10, 6
	v_add_u32_e32 v186, 0x10000, v185
	s_lshl_b32 s0, s10, 7
	s_mov_b32 s1, s59
	s_mov_b64 s[12:13], 0
	s_lshl_b32 s58, s23, 1
	v_lshlrev_b32_e32 v190, 1, v3
	s_waitcnt vmcnt(6)
	v_mov_b64_e32 v[42:43], v[0:1]
	v_mov_b64_e32 v[44:45], v[0:1]
	v_mov_b64_e32 v[62:63], v[0:1]
	v_mov_b64_e32 v[64:65], v[0:1]
	v_mov_b64_e32 v[74:75], v[0:1]
	v_mov_b64_e32 v[76:77], v[0:1]
.LBB0_478:
	s_and_b32 s38, s37, 7
	s_or_b32 s23, s38, s22
	s_lshl_b32 s23, s23, 8
	s_lshl_b32 s36, s37, 5
	s_and_b32 s42, s36, 0xffffff00
	v_add_u32_e32 v0, s23, v184
	v_mad_i64_i32 v[22:23], s[40:41], v0, s10, 0
	v_add_u32_e32 v0, s42, v184
	v_lshl_add_u64 v[180:181], v[22:23], 1, v[176:177]
	v_mad_i64_i32 v[22:23], s[40:41], v0, s10, 0
	v_lshl_add_u64 v[182:183], v[22:23], 1, v[178:179]
	v_readfirstlane_b32 s62, v180
	v_readfirstlane_b32 s63, v181
	v_readfirstlane_b32 s64, v182
	v_readfirstlane_b32 s65, v183
	s_nop 4
	s_and_b64 vcc, exec, s[12:13]
	s_cbranch_vccnz .LBB0_480
	global_load_dwordx4 v[10:13], v234, s[62:63]
	global_load_dwordx4 v[2:5], v235, s[62:63]
	global_load_dwordx4 v[6:9], v236, s[62:63]
	global_load_dwordx4 v[14:17], v237, s[62:63]
	global_load_dwordx4 v[18:21], v234, s[64:65]
	global_load_dwordx4 v[42:45], v235, s[64:65]
	global_load_dwordx4 v[62:65], v236, s[64:65]
	global_load_dwordx4 v[74:77], v237, s[64:65]
.LBB0_480:
	s_waitcnt vmcnt(5)
	ds_write_b128 v185, v[10:13]
	ds_write_b128 v185, v[2:5] offset:8192
	ds_write_b128 v185, v[6:9] offset:16384
	s_waitcnt vmcnt(3)
	ds_write_b128 v185, v[14:17] offset:24576
	ds_write_b128 v186, v[18:21]
	s_waitcnt vmcnt(2)
	ds_write_b128 v186, v[42:45] offset:8192
	s_waitcnt vmcnt(1)
	ds_write_b128 v186, v[62:65] offset:16384
	s_waitcnt vmcnt(0)
	ds_write_b128 v186, v[74:77] offset:24576
	global_load_dwordx4 v[10:13], v234, s[62:63] offset:128
	global_load_dwordx4 v[2:5], v235, s[62:63] offset:128
	global_load_dwordx4 v[6:9], v236, s[62:63] offset:128
	global_load_dwordx4 v[14:17], v237, s[62:63] offset:128
	global_load_dwordx4 v[18:21], v234, s[64:65] offset:128
	global_load_dwordx4 v[42:45], v235, s[64:65] offset:128
	global_load_dwordx4 v[62:65], v236, s[64:65] offset:128
	global_load_dwordx4 v[74:77], v237, s[64:65] offset:128
	s_add_i32 s36, s37, s70
	s_cmp_gt_i32 s36, 31
	s_cselect_b64 s[40:41], -1, 0
	s_cmp_lt_i32 s36, 32
	s_cselect_b32 s12, s36, s37
	s_and_b32 s13, s12, 7
	s_lshl_b32 s12, s12, 5
	s_and_b32 s37, s12, 0xffffff00
	s_sub_i32 s12, s13, s38
	s_lshl_b32 s13, s12, 8
	s_sub_i32 s38, s37, s42
	v_mov_b32_e32 v22, 0
	s_mul_hi_i32 s12, s13, s10
	s_mul_i32 s13, s13, s10
	s_mul_hi_i32 s37, s38, s10
	s_mul_i32 s38, s38, s10
	s_movk_i32 s39, 0x80
	s_mov_b32 s43, 0
	s_mov_b32 s44, 0
	v_mov_b32_e32 v23, v22
	v_mov_b32_e32 v24, v22
	v_mov_b32_e32 v25, v22
	v_mov_b32_e32 v26, v22
	v_mov_b32_e32 v27, v22
	v_mov_b32_e32 v28, v22
	v_mov_b32_e32 v29, v22
	v_mov_b32_e32 v30, v22
	v_mov_b32_e32 v31, v22
	v_mov_b32_e32 v32, v22
	v_mov_b32_e32 v33, v22
	v_mov_b32_e32 v34, v22
	v_mov_b32_e32 v35, v22
	v_mov_b32_e32 v36, v22
	v_mov_b32_e32 v37, v22
	v_mov_b32_e32 v38, v22
	v_mov_b32_e32 v39, v22
	v_mov_b32_e32 v40, v22
	v_mov_b32_e32 v41, v22
	v_mov_b32_e32 v46, v22
	v_mov_b32_e32 v47, v22
	v_mov_b32_e32 v48, v22
	v_mov_b32_e32 v49, v22
	v_mov_b32_e32 v50, v22
	v_mov_b32_e32 v51, v22
	v_mov_b32_e32 v52, v22
	v_mov_b32_e32 v53, v22
	v_mov_b32_e32 v54, v22
	v_mov_b32_e32 v55, v22
	v_mov_b32_e32 v56, v22
	v_mov_b32_e32 v57, v22
	v_mov_b32_e32 v58, v22
	v_mov_b32_e32 v59, v22
	v_mov_b32_e32 v60, v22
	v_mov_b32_e32 v61, v22
	v_mov_b32_e32 v66, v22
	v_mov_b32_e32 v67, v22
	v_mov_b32_e32 v68, v22
	v_mov_b32_e32 v69, v22
	v_mov_b32_e32 v70, v22
; #define ZERO_ACC8(acc, NJ_)                             \
;   _Pragma("unroll") for (int i_ = 0; i_ < 8; ++i_)      \
;   _Pragma("unroll") for (int j_ = 0; j_ < (NJ_); ++j_) { acc[i_][j_] = (f32x4){0.f, 0.f, 0.f, 0.f}; }
; template <int MI, int NJ> ...
;     ...
;   for (int kt = 0; kt < nk; ++kt) {
;     const int buf = kt & 1;
;     {
;       G8STORE(buf ^ 1);
;       const u16* ga_ = (kt + 2 < nk) ? Ag + (kt + 2) * 64 : Ag + nAoff;
;       const u16* gb_ = (kt + 2 < nk) ? Bg + (kt + 2) * 64 : Bg + nBoff;
;       G8LOADP(ga_, gb_);
;     }
;     __builtin_amdgcn_sched_barrier(0);
;     __builtin_amdgcn_s_setprio(1);
;     const u16* a = ra_ + buf * AROWS * 64;
;     const u16* b = rb_ + buf * BROWS * 64;
; #pragma unroll
;     for (int ks = 0; ks < 2; ++ks) {
;       const u16* a_ = ks ? a + dsw : a;
;       const u16* b_ = ks ? b + dsw : b;
;       bf16x8 bfr[NJ];
; #pragma unroll
;       for (int j = 0; j < NJ; ++j) bfr[j] = *(const bf16x8*)(b_ + j * 16 * 64);
; #pragma unroll
;       for (int ih = 0; ih < MI / 4; ++ih) {
;         bf16x8 af[4];
; #pragma unroll
;         for (int i = 0; i < 4; ++i) af[i] = *(const bf16x8*)(a_ + (ih * 4 + i) * 16 * 64);
; #pragma unroll
;         for (int i = 0; i < 4; ++i)
; #pragma unroll
;           for (int j = 0; j < NJ; ++j) acc[ih * 4 + i][j] = mfma16(af[i], bfr[j], acc[ih * 4 + i][j]);
;       }
;     }
; __device__ __forceinline__ void phase_gemm_f32(const u16* A, const u16* Bt, int K, u16* out, u16* smem,
;                                                volatile LAS unsigned* vb_) {
;     ...
;     ZERO_ACC8(acc, 4);
;     gemm8<8, 4>(acc, G8REGS_ARGS, pre, A, K, Bt, K, 0, K, mt * 256, nt * 256, ((vb & 7) * 8 + (ltn & 7)) * 256, (ltn >> 3) * 256, 0, smem, tid);
	v_mov_b32_e32 v71, v22
	v_mov_b32_e32 v72, v22
	v_mov_b32_e32 v73, v22
	v_mov_b32_e32 v78, v22
	v_mov_b32_e32 v79, v22
	v_mov_b32_e32 v80, v22
	v_mov_b32_e32 v81, v22
	v_mov_b32_e32 v82, v22
	v_mov_b32_e32 v83, v22
	v_mov_b32_e32 v84, v22
	v_mov_b32_e32 v85, v22
	v_mov_b32_e32 v86, v22
	v_mov_b32_e32 v87, v22
	v_mov_b32_e32 v88, v22
	v_mov_b32_e32 v89, v22
	v_mov_b32_e32 v90, v22
	v_mov_b32_e32 v91, v22
	v_mov_b32_e32 v92, v22
	v_mov_b32_e32 v93, v22
	v_mov_b32_e32 v94, v22
	v_mov_b32_e32 v95, v22
	v_mov_b32_e32 v96, v22
	v_mov_b32_e32 v97, v22
	v_mov_b32_e32 v98, v22
	v_mov_b32_e32 v99, v22
	v_mov_b32_e32 v100, v22
	v_mov_b32_e32 v101, v22
	v_mov_b32_e32 v102, v22
	v_mov_b32_e32 v103, v22
	v_mov_b32_e32 v104, v22
	v_mov_b32_e32 v105, v22
	v_mov_b32_e32 v106, v22
	v_mov_b32_e32 v107, v22
	v_mov_b32_e32 v108, v22
	v_mov_b32_e32 v109, v22
	v_mov_b32_e32 v110, v22
	v_mov_b32_e32 v111, v22
	v_mov_b32_e32 v112, v22
	v_mov_b32_e32 v113, v22
	v_mov_b32_e32 v114, v22
	v_mov_b32_e32 v115, v22
	v_mov_b32_e32 v116, v22
	v_mov_b32_e32 v117, v22
	v_mov_b32_e32 v118, v22
	v_mov_b32_e32 v119, v22
	v_mov_b32_e32 v120, v22
	v_mov_b32_e32 v121, v22
	v_mov_b32_e32 v122, v22
	v_mov_b32_e32 v123, v22
	v_mov_b32_e32 v124, v22
	v_mov_b32_e32 v125, v22
	v_mov_b32_e32 v126, v22
	v_mov_b32_e32 v127, v22
	v_mov_b32_e32 v128, v22
	v_mov_b32_e32 v129, v22
	v_mov_b32_e32 v130, v22
	v_mov_b32_e32 v131, v22
	v_mov_b32_e32 v132, v22
	v_mov_b32_e32 v133, v22
	v_mov_b32_e32 v134, v22
	v_mov_b32_e32 v135, v22
	v_mov_b32_e32 v136, v22
	v_mov_b32_e32 v137, v22
	v_mov_b32_e32 v138, v22
	v_mov_b32_e32 v139, v22
	v_mov_b32_e32 v140, v22
	v_mov_b32_e32 v141, v22
	v_mov_b32_e32 v142, v22
	v_mov_b32_e32 v143, v22
	v_mov_b32_e32 v144, v22
	v_mov_b32_e32 v145, v22
	v_mov_b32_e32 v146, v22
	v_mov_b32_e32 v147, v22
	v_mov_b32_e32 v148, v22
	v_mov_b32_e32 v149, v22
	v_mov_b32_e32 v150, v22
	v_mov_b32_e32 v151, v22
	v_mov_b32_e32 v152, v22
	v_mov_b32_e32 v153, v22
	v_mov_b32_e32 v154, v22
	v_mov_b32_e32 v155, v22
	v_mov_b32_e32 v156, v22
	v_mov_b32_e32 v157, v22
	v_mov_b32_e32 v158, v22
	v_mov_b32_e32 v159, v22
	v_mov_b32_e32 v160, v22
	v_mov_b32_e32 v161, v22
	s_waitcnt lgkmcnt(0)
	s_barrier
.LBB0_481:
	s_and_b32 s45, s43, 0x4000
	s_xor_b32 s46, s45, 0x4000
	s_lshl_b32 s46, s46, 1
	v_add_u32_e32 v228, s46, v185
	v_add_u32_e32 v229, s46, v186
	s_add_i32 s46, s44, 2
	s_cmp_lt_u32 s46, s21
	s_cselect_b32 s47, 0, s12
	s_cselect_b32 s46, s39, s13
	s_cselect_b32 s49, 0, s37
	s_cselect_b32 s48, s39, s38
	s_lshl_b64 s[46:47], s[46:47], 1
	s_lshl_b64 s[48:49], s[48:49], 1
	s_add_u32 s50, s62, s46
	s_addc_u32 s51, s63, s47
	s_add_u32 s52, s64, s48
	s_addc_u32 s53, s65, s49
	s_setprio 1
	s_lshl_b32 s45, s45, 1
	v_add_u32_e32 v0, s45, v187
	v_add_u32_e32 v191, s45, v188
	ds_read_b128 v[166:169], v191
	ds_read_b128 v[162:165], v0
	ds_read_b128 v[170:173], v191 offset:2048
	ds_read_b128 v[192:195], v191 offset:4096
	ds_read_b128 v[196:199], v191 offset:6144
	ds_read_b128 v[204:207], v0 offset:2048
	ds_read_b128 v[208:211], v0 offset:4096
	v_add_u32_e32 v191, v191, v190
	s_waitcnt lgkmcnt(5)
	v_mfma_f32_16x16x32_bf16 v[158:161], v[162:165], v[166:169], v[158:161]
	s_waitcnt lgkmcnt(4)
	v_mfma_f32_16x16x32_bf16 v[154:157], v[162:165], v[170:173], v[154:157]
	s_waitcnt lgkmcnt(3)
	v_mfma_f32_16x16x32_bf16 v[150:153], v[162:165], v[192:195], v[150:153]
	s_waitcnt lgkmcnt(2)
	v_mfma_f32_16x16x32_bf16 v[146:149], v[162:165], v[196:199], v[146:149]
	ds_read_b128 v[162:165], v0 offset:6144
	s_waitcnt lgkmcnt(2)
	v_mfma_f32_16x16x32_bf16 v[142:145], v[204:207], v[166:169], v[142:145]
	v_mfma_f32_16x16x32_bf16 v[138:141], v[204:207], v[170:173], v[138:141]
	v_mfma_f32_16x16x32_bf16 v[134:137], v[204:207], v[192:195], v[134:137]
	v_mfma_f32_16x16x32_bf16 v[130:133], v[204:207], v[196:199], v[130:133]
	ds_read_b128 v[204:207], v0 offset:8192
	s_waitcnt vmcnt(7)
	ds_write_b128 v228, v[10:13]
	global_load_dwordx4 v[10:13], v234, s[50:51]
	s_waitcnt lgkmcnt(3)
	v_mfma_f32_16x16x32_bf16 v[126:129], v[208:211], v[166:169], v[126:129]
	v_mfma_f32_16x16x32_bf16 v[122:125], v[208:211], v[170:173], v[122:125]
	v_mfma_f32_16x16x32_bf16 v[118:121], v[208:211], v[192:195], v[118:121]
	v_mfma_f32_16x16x32_bf16 v[114:117], v[208:211], v[196:199], v[114:117]
	ds_read_b128 v[208:211], v0 offset:10240
	s_waitcnt vmcnt(7)
	ds_write_b128 v228, v[2:5] offset:8192
	global_load_dwordx4 v[2:5], v235, s[50:51]
	ds_read_b128 v[212:215], v191
	ds_read_b128 v[216:219], v191 offset:2048
	s_waitcnt lgkmcnt(6)
	v_mfma_f32_16x16x32_bf16 v[110:113], v[162:165], v[166:169], v[110:113]
	v_mfma_f32_16x16x32_bf16 v[106:109], v[162:165], v[170:173], v[106:109]
	v_mfma_f32_16x16x32_bf16 v[102:105], v[162:165], v[192:195], v[102:105]
	v_mfma_f32_16x16x32_bf16 v[98:101], v[162:165], v[196:199], v[98:101]
	ds_read_b128 v[162:165], v0 offset:12288
	s_waitcnt vmcnt(7)
	ds_write_b128 v228, v[6:9] offset:16384
	global_load_dwordx4 v[6:9], v236, s[50:51]
	ds_read_b128 v[220:223], v191 offset:4096
	ds_read_b128 v[224:227], v191 offset:6144
	s_waitcnt lgkmcnt(9)
	v_mfma_f32_16x16x32_bf16 v[94:97], v[204:207], v[166:169], v[94:97]
	v_mfma_f32_16x16x32_bf16 v[90:93], v[204:207], v[170:173], v[90:93]
	v_mfma_f32_16x16x32_bf16 v[86:89], v[204:207], v[192:195], v[86:89]
	v_mfma_f32_16x16x32_bf16 v[82:85], v[204:207], v[196:199], v[82:85]
	ds_read_b128 v[204:207], v0 offset:14336
	s_waitcnt vmcnt(7)
	ds_write_b128 v228, v[14:17] offset:24576
	global_load_dwordx4 v[14:17], v237, s[50:51]
	s_waitcnt lgkmcnt(9)
; template <int MI, int NJ> ...
;     ...
; #pragma unroll
;     for (int ks = 0; ks < 2; ++ks) {
;       const u16* a_ = ks ? a + dsw : a;
;       const u16* b_ = ks ? b + dsw : b;
;       bf16x8 bfr[NJ];
; #pragma unroll
;       for (int j = 0; j < NJ; ++j) bfr[j] = *(const bf16x8*)(b_ + j * 16 * 64);
; #pragma unroll
;       for (int ih = 0; ih < MI / 4; ++ih) {
;         bf16x8 af[4];
; #pragma unroll
;         for (int i = 0; i < 4; ++i) af[i] = *(const bf16x8*)(a_ + (ih * 4 + i) * 16 * 64);
; #pragma unroll
;         for (int i = 0; i < 4; ++i)
; #pragma unroll
;           for (int j = 0; j < NJ; ++j) acc[ih * 4 + i][j] = mfma16(af[i], bfr[j], acc[ih * 4 + i][j]);
;       }
;     }
;     __builtin_amdgcn_s_setprio(0);
;     __builtin_amdgcn_sched_barrier(0);
;     __syncthreads();
;   }
	v_mfma_f32_16x16x32_bf16 v[78:81], v[208:211], v[166:169], v[78:81]
	v_mfma_f32_16x16x32_bf16 v[70:73], v[208:211], v[170:173], v[70:73]
	v_mfma_f32_16x16x32_bf16 v[66:69], v[208:211], v[192:195], v[66:69]
	v_mfma_f32_16x16x32_bf16 v[58:61], v[208:211], v[196:199], v[58:61]
	v_add_u32_e32 v0, v0, v190
	ds_read_b128 v[208:211], v0
	s_waitcnt vmcnt(7)
	ds_write_b128 v229, v[18:21]
	global_load_dwordx4 v[18:21], v234, s[52:53]
	s_waitcnt lgkmcnt(7)
	v_mfma_f32_16x16x32_bf16 v[54:57], v[162:165], v[166:169], v[54:57]
	v_mfma_f32_16x16x32_bf16 v[50:53], v[162:165], v[170:173], v[50:53]
	v_mfma_f32_16x16x32_bf16 v[46:49], v[162:165], v[192:195], v[46:49]
	v_mfma_f32_16x16x32_bf16 v[38:41], v[162:165], v[196:199], v[38:41]
	ds_read_b128 v[162:165], v0 offset:2048
	s_waitcnt vmcnt(7)
	ds_write_b128 v229, v[42:45] offset:8192
	global_load_dwordx4 v[42:45], v235, s[52:53]
	s_waitcnt lgkmcnt(5)
	v_mfma_f32_16x16x32_bf16 v[34:37], v[204:207], v[166:169], v[34:37]
	v_mfma_f32_16x16x32_bf16 v[30:33], v[204:207], v[170:173], v[30:33]
	v_mfma_f32_16x16x32_bf16 v[26:29], v[204:207], v[192:195], v[26:29]
	v_mfma_f32_16x16x32_bf16 v[22:25], v[204:207], v[196:199], v[22:25]
	ds_read_b128 v[204:207], v0 offset:4096
	s_waitcnt vmcnt(7)
	ds_write_b128 v229, v[62:65] offset:16384
	global_load_dwordx4 v[62:65], v236, s[52:53]
	s_waitcnt lgkmcnt(5)
	v_mfma_f32_16x16x32_bf16 v[158:161], v[208:211], v[212:215], v[158:161]
	v_mfma_f32_16x16x32_bf16 v[154:157], v[208:211], v[216:219], v[154:157]
	v_mfma_f32_16x16x32_bf16 v[150:153], v[208:211], v[220:223], v[150:153]
	v_mfma_f32_16x16x32_bf16 v[146:149], v[208:211], v[224:227], v[146:149]
	ds_read_b128 v[208:211], v0 offset:6144
	s_waitcnt vmcnt(7)
	ds_write_b128 v229, v[74:77] offset:24576
	global_load_dwordx4 v[74:77], v237, s[52:53]
	s_waitcnt lgkmcnt(5)
	v_mfma_f32_16x16x32_bf16 v[142:145], v[162:165], v[212:215], v[142:145]
	v_mfma_f32_16x16x32_bf16 v[138:141], v[162:165], v[216:219], v[138:141]
	v_mfma_f32_16x16x32_bf16 v[134:137], v[162:165], v[220:223], v[134:137]
	v_mfma_f32_16x16x32_bf16 v[130:133], v[162:165], v[224:227], v[130:133]
	ds_read_b128 v[162:165], v0 offset:8192
	s_waitcnt lgkmcnt(4)
	v_mfma_f32_16x16x32_bf16 v[126:129], v[204:207], v[212:215], v[126:129]
	v_mfma_f32_16x16x32_bf16 v[122:125], v[204:207], v[216:219], v[122:125]
	v_mfma_f32_16x16x32_bf16 v[118:121], v[204:207], v[220:223], v[118:121]
	v_mfma_f32_16x16x32_bf16 v[114:117], v[204:207], v[224:227], v[114:117]
	ds_read_b128 v[204:207], v0 offset:10240
	s_waitcnt lgkmcnt(3)
	v_mfma_f32_16x16x32_bf16 v[110:113], v[208:211], v[212:215], v[110:113]
	v_mfma_f32_16x16x32_bf16 v[106:109], v[208:211], v[216:219], v[106:109]
	v_mfma_f32_16x16x32_bf16 v[102:105], v[208:211], v[220:223], v[102:105]
	v_mfma_f32_16x16x32_bf16 v[98:101], v[208:211], v[224:227], v[98:101]
	ds_read_b128 v[208:211], v0 offset:12288
	s_waitcnt lgkmcnt(2)
	v_mfma_f32_16x16x32_bf16 v[94:97], v[162:165], v[212:215], v[94:97]
	v_mfma_f32_16x16x32_bf16 v[90:93], v[162:165], v[216:219], v[90:93]
	v_mfma_f32_16x16x32_bf16 v[86:89], v[162:165], v[220:223], v[86:89]
	v_mfma_f32_16x16x32_bf16 v[82:85], v[162:165], v[224:227], v[82:85]
	ds_read_b128 v[162:165], v0 offset:14336
	s_waitcnt lgkmcnt(2)
	v_mfma_f32_16x16x32_bf16 v[78:81], v[204:207], v[212:215], v[78:81]
	v_mfma_f32_16x16x32_bf16 v[70:73], v[204:207], v[216:219], v[70:73]
	v_mfma_f32_16x16x32_bf16 v[66:69], v[204:207], v[220:223], v[66:69]
	v_mfma_f32_16x16x32_bf16 v[58:61], v[204:207], v[224:227], v[58:61]
	s_waitcnt lgkmcnt(1)
	v_mfma_f32_16x16x32_bf16 v[54:57], v[208:211], v[212:215], v[54:57]
	v_mfma_f32_16x16x32_bf16 v[50:53], v[208:211], v[216:219], v[50:53]
	v_mfma_f32_16x16x32_bf16 v[46:49], v[208:211], v[220:223], v[46:49]
	v_mfma_f32_16x16x32_bf16 v[38:41], v[208:211], v[224:227], v[38:41]
	s_waitcnt lgkmcnt(0)
	v_mfma_f32_16x16x32_bf16 v[34:37], v[162:165], v[212:215], v[34:37]
	v_mfma_f32_16x16x32_bf16 v[30:33], v[162:165], v[216:219], v[30:33]
	v_mfma_f32_16x16x32_bf16 v[26:29], v[162:165], v[220:223], v[26:29]
	v_mfma_f32_16x16x32_bf16 v[22:25], v[162:165], v[224:227], v[22:25]
	s_setprio 0
	s_add_i32 s44, s44, 1
	s_add_i32 s39, s39, 64
	s_addk_i32 s43, 0x4000
	s_cmp_lg_u32 s21, s44
	s_barrier
	s_cbranch_scc1 .LBB0_481
; __device__ __forceinline__ void phase_gemm_f32(const u16* A, const u16* Bt, int K, u16* out, u16* smem,
;                                                volatile LAS unsigned* vb_) {
;     ...
; #pragma unroll
;     for (int i = 0; i < 8; ++i)
; #pragma unroll
;       for (int j = 0; j < 4; ++j)
; #pragma unroll
;         for (int r = 0; r < 4; ++r)
;           smem[(wm * 128 + i * 16 + (lane >> 4) * 4 + r) * 264 + wn * 64 + j * 16 + (lane & 15)] = f2bf(acc[i][j][r]);
	v_cvt_pk_bf16_f32 v0, v158, s0
	ds_write_b16 v189, v0
	v_cvt_pk_bf16_f32 v0, v159, s0
	ds_write_b16 v189, v0 offset:528
	v_cvt_pk_bf16_f32 v0, v160, s0
	ds_write_b16 v189, v0 offset:1056
	v_cvt_pk_bf16_f32 v0, v161, s0
	ds_write_b16 v189, v0 offset:1584
	v_cvt_pk_bf16_f32 v0, v154, s0
	ds_write_b16 v189, v0 offset:32
	v_cvt_pk_bf16_f32 v0, v155, s0
	ds_write_b16 v189, v0 offset:560
	v_cvt_pk_bf16_f32 v0, v156, s0
	ds_write_b16 v189, v0 offset:1088
	v_cvt_pk_bf16_f32 v0, v157, s0
	ds_write_b16 v189, v0 offset:1616
	v_cvt_pk_bf16_f32 v0, v150, s0
	ds_write_b16 v189, v0 offset:64
	v_cvt_pk_bf16_f32 v0, v151, s0
	ds_write_b16 v189, v0 offset:592
	v_cvt_pk_bf16_f32 v0, v152, s0
	ds_write_b16 v189, v0 offset:1120
	v_cvt_pk_bf16_f32 v0, v153, s0
	ds_write_b16 v189, v0 offset:1648
	v_cvt_pk_bf16_f32 v0, v146, s0
	ds_write_b16 v189, v0 offset:96
	v_cvt_pk_bf16_f32 v0, v147, s0
	ds_write_b16 v189, v0 offset:624
	v_cvt_pk_bf16_f32 v0, v148, s0
	ds_write_b16 v189, v0 offset:1152
	v_cvt_pk_bf16_f32 v0, v149, s0
	ds_write_b16 v189, v0 offset:1680
	v_cvt_pk_bf16_f32 v0, v142, s0
	ds_write_b16 v189, v0 offset:8448
	v_cvt_pk_bf16_f32 v0, v143, s0
	ds_write_b16 v189, v0 offset:8976
	v_cvt_pk_bf16_f32 v0, v144, s0
	ds_write_b16 v189, v0 offset:9504
	v_cvt_pk_bf16_f32 v0, v145, s0
	ds_write_b16 v189, v0 offset:10032
	v_cvt_pk_bf16_f32 v0, v138, s0
	ds_write_b16 v189, v0 offset:8480
	v_cvt_pk_bf16_f32 v0, v139, s0
	ds_write_b16 v189, v0 offset:9008
	v_cvt_pk_bf16_f32 v0, v140, s0
	ds_write_b16 v189, v0 offset:9536
	v_cvt_pk_bf16_f32 v0, v141, s0
	ds_write_b16 v189, v0 offset:10064
	v_cvt_pk_bf16_f32 v0, v134, s0
	ds_write_b16 v189, v0 offset:8512
	v_cvt_pk_bf16_f32 v0, v135, s0
	ds_write_b16 v189, v0 offset:9040
	v_cvt_pk_bf16_f32 v0, v136, s0
	ds_write_b16 v189, v0 offset:9568
	v_cvt_pk_bf16_f32 v0, v137, s0
	ds_write_b16 v189, v0 offset:10096
	v_cvt_pk_bf16_f32 v0, v130, s0
	ds_write_b16 v189, v0 offset:8544
	v_cvt_pk_bf16_f32 v0, v131, s0
	ds_write_b16 v189, v0 offset:9072
	v_cvt_pk_bf16_f32 v0, v132, s0
	ds_write_b16 v189, v0 offset:9600
	v_cvt_pk_bf16_f32 v0, v133, s0
	ds_write_b16 v189, v0 offset:10128
	v_cvt_pk_bf16_f32 v0, v126, s0
	ds_write_b16 v189, v0 offset:16896
	v_cvt_pk_bf16_f32 v0, v127, s0
	ds_write_b16 v189, v0 offset:17424
	v_cvt_pk_bf16_f32 v0, v128, s0
	ds_write_b16 v189, v0 offset:17952
	v_cvt_pk_bf16_f32 v0, v129, s0
	ds_write_b16 v189, v0 offset:18480
	v_cvt_pk_bf16_f32 v0, v122, s0
	ds_write_b16 v189, v0 offset:16928
	v_cvt_pk_bf16_f32 v0, v123, s0
	ds_write_b16 v189, v0 offset:17456
	v_cvt_pk_bf16_f32 v0, v124, s0
	ds_write_b16 v189, v0 offset:17984
	v_cvt_pk_bf16_f32 v0, v125, s0
	ds_write_b16 v189, v0 offset:18512
	v_cvt_pk_bf16_f32 v0, v118, s0
	ds_write_b16 v189, v0 offset:16960
	v_cvt_pk_bf16_f32 v0, v119, s0
	ds_write_b16 v189, v0 offset:17488
	v_cvt_pk_bf16_f32 v0, v120, s0
	ds_write_b16 v189, v0 offset:18016
	v_cvt_pk_bf16_f32 v0, v121, s0
	ds_write_b16 v189, v0 offset:18544
	v_cvt_pk_bf16_f32 v0, v114, s0
	ds_write_b16 v189, v0 offset:16992
	v_cvt_pk_bf16_f32 v0, v115, s0
	ds_write_b16 v189, v0 offset:17520
	v_cvt_pk_bf16_f32 v0, v116, s0
	ds_write_b16 v189, v0 offset:18048
	v_cvt_pk_bf16_f32 v0, v117, s0
	ds_write_b16 v189, v0 offset:18576
	v_cvt_pk_bf16_f32 v0, v110, s0
	ds_write_b16 v189, v0 offset:25344
	v_cvt_pk_bf16_f32 v0, v111, s0
	ds_write_b16 v189, v0 offset:25872
	v_cvt_pk_bf16_f32 v0, v112, s0
	ds_write_b16 v189, v0 offset:26400
	v_cvt_pk_bf16_f32 v0, v113, s0
	ds_write_b16 v189, v0 offset:26928
	v_cvt_pk_bf16_f32 v0, v106, s0
	ds_write_b16 v189, v0 offset:25376
	v_cvt_pk_bf16_f32 v0, v107, s0
	ds_write_b16 v189, v0 offset:25904
	v_cvt_pk_bf16_f32 v0, v108, s0
	ds_write_b16 v189, v0 offset:26432
	v_cvt_pk_bf16_f32 v0, v109, s0
	ds_write_b16 v189, v0 offset:26960
	v_cvt_pk_bf16_f32 v0, v102, s0
	ds_write_b16 v189, v0 offset:25408
	v_cvt_pk_bf16_f32 v0, v103, s0
	ds_write_b16 v189, v0 offset:25936
	v_cvt_pk_bf16_f32 v0, v104, s0
	ds_write_b16 v189, v0 offset:26464
	v_cvt_pk_bf16_f32 v0, v105, s0
	ds_write_b16 v189, v0 offset:26992
	v_cvt_pk_bf16_f32 v0, v98, s0
	ds_write_b16 v189, v0 offset:25440
	v_cvt_pk_bf16_f32 v0, v99, s0
	ds_write_b16 v189, v0 offset:25968
	v_cvt_pk_bf16_f32 v0, v100, s0
	ds_write_b16 v189, v0 offset:26496
	v_cvt_pk_bf16_f32 v0, v101, s0
	ds_write_b16 v189, v0 offset:27024
	v_cvt_pk_bf16_f32 v0, v94, s0
	ds_write_b16 v189, v0 offset:33792
	v_cvt_pk_bf16_f32 v0, v95, s0
	ds_write_b16 v189, v0 offset:34320
	v_cvt_pk_bf16_f32 v0, v96, s0
	ds_write_b16 v189, v0 offset:34848
	v_cvt_pk_bf16_f32 v0, v97, s0
	ds_write_b16 v189, v0 offset:35376
	v_cvt_pk_bf16_f32 v0, v90, s0
	ds_write_b16 v189, v0 offset:33824
	v_cvt_pk_bf16_f32 v0, v91, s0
	ds_write_b16 v189, v0 offset:34352
	v_cvt_pk_bf16_f32 v0, v92, s0
	ds_write_b16 v189, v0 offset:34880
	v_cvt_pk_bf16_f32 v0, v93, s0
	ds_write_b16 v189, v0 offset:35408
	v_cvt_pk_bf16_f32 v0, v86, s0
	ds_write_b16 v189, v0 offset:33856
	v_cvt_pk_bf16_f32 v0, v87, s0
	ds_write_b16 v189, v0 offset:34384
	v_cvt_pk_bf16_f32 v0, v88, s0
	ds_write_b16 v189, v0 offset:34912
	v_cvt_pk_bf16_f32 v0, v89, s0
	ds_write_b16 v189, v0 offset:35440
	v_cvt_pk_bf16_f32 v0, v82, s0
	ds_write_b16 v189, v0 offset:33888
	v_cvt_pk_bf16_f32 v0, v83, s0
	ds_write_b16 v189, v0 offset:34416
	v_cvt_pk_bf16_f32 v0, v84, s0
	ds_write_b16 v189, v0 offset:34944
	v_cvt_pk_bf16_f32 v0, v85, s0
	ds_write_b16 v189, v0 offset:35472
	v_cvt_pk_bf16_f32 v0, v78, s0
	ds_write_b16 v189, v0 offset:42240
	v_cvt_pk_bf16_f32 v0, v79, s0
	ds_write_b16 v189, v0 offset:42768
	v_cvt_pk_bf16_f32 v0, v80, s0
	ds_write_b16 v189, v0 offset:43296
	v_cvt_pk_bf16_f32 v0, v81, s0
	ds_write_b16 v189, v0 offset:43824
; __device__ __forceinline__ void phase_gemm_f32(const u16* A, const u16* Bt, int K, u16* out, u16* smem,
;                                                volatile LAS unsigned* vb_) {
;     ...
; #pragma unroll
;     for (int i = 0; i < 8; ++i)
; #pragma unroll
;       for (int j = 0; j < 4; ++j)
; #pragma unroll
;         for (int r = 0; r < 4; ++r)
;           smem[(wm * 128 + i * 16 + (lane >> 4) * 4 + r) * 264 + wn * 64 + j * 16 + (lane & 15)] = f2bf(acc[i][j][r]);
;     __syncthreads();
	v_cvt_pk_bf16_f32 v0, v70, s0
	ds_write_b16 v189, v0 offset:42272
	v_cvt_pk_bf16_f32 v0, v71, s0
	ds_write_b16 v189, v0 offset:42800
	v_cvt_pk_bf16_f32 v0, v72, s0
	ds_write_b16 v189, v0 offset:43328
	v_cvt_pk_bf16_f32 v0, v73, s0
	ds_write_b16 v189, v0 offset:43856
	v_cvt_pk_bf16_f32 v0, v66, s0
	ds_write_b16 v189, v0 offset:42304
	v_cvt_pk_bf16_f32 v0, v67, s0
	ds_write_b16 v189, v0 offset:42832
	v_cvt_pk_bf16_f32 v0, v68, s0
	ds_write_b16 v189, v0 offset:43360
	v_cvt_pk_bf16_f32 v0, v69, s0
	ds_write_b16 v189, v0 offset:43888
	v_cvt_pk_bf16_f32 v0, v58, s0
	ds_write_b16 v189, v0 offset:42336
	v_cvt_pk_bf16_f32 v0, v59, s0
	ds_write_b16 v189, v0 offset:42864
	v_cvt_pk_bf16_f32 v0, v60, s0
	ds_write_b16 v189, v0 offset:43392
	v_cvt_pk_bf16_f32 v0, v61, s0
	ds_write_b16 v189, v0 offset:43920
	v_cvt_pk_bf16_f32 v0, v54, s0
	ds_write_b16 v189, v0 offset:50688
	v_cvt_pk_bf16_f32 v0, v55, s0
	ds_write_b16 v189, v0 offset:51216
	v_cvt_pk_bf16_f32 v0, v56, s0
	ds_write_b16 v189, v0 offset:51744
	v_cvt_pk_bf16_f32 v0, v57, s0
	ds_write_b16 v189, v0 offset:52272
	v_cvt_pk_bf16_f32 v0, v50, s0
	ds_write_b16 v189, v0 offset:50720
	v_cvt_pk_bf16_f32 v0, v51, s0
	ds_write_b16 v189, v0 offset:51248
	v_cvt_pk_bf16_f32 v0, v52, s0
	ds_write_b16 v189, v0 offset:51776
	v_cvt_pk_bf16_f32 v0, v53, s0
	ds_write_b16 v189, v0 offset:52304
	v_cvt_pk_bf16_f32 v0, v46, s0
	ds_write_b16 v189, v0 offset:50752
	v_cvt_pk_bf16_f32 v0, v47, s0
	ds_write_b16 v189, v0 offset:51280
	v_cvt_pk_bf16_f32 v0, v48, s0
	ds_write_b16 v189, v0 offset:51808
	v_cvt_pk_bf16_f32 v0, v49, s0
	ds_write_b16 v189, v0 offset:52336
	v_cvt_pk_bf16_f32 v0, v38, s0
	ds_write_b16 v189, v0 offset:50784
	v_cvt_pk_bf16_f32 v0, v39, s0
	ds_write_b16 v189, v0 offset:51312
	v_cvt_pk_bf16_f32 v0, v40, s0
	ds_write_b16 v189, v0 offset:51840
	v_cvt_pk_bf16_f32 v0, v41, s0
	ds_write_b16 v189, v0 offset:52368
	v_cvt_pk_bf16_f32 v0, v34, s0
	ds_write_b16 v189, v0 offset:59136
	v_cvt_pk_bf16_f32 v0, v35, s0
	ds_write_b16 v189, v0 offset:59664
	v_cvt_pk_bf16_f32 v0, v36, s0
	ds_write_b16 v189, v0 offset:60192
	v_cvt_pk_bf16_f32 v0, v37, s0
	ds_write_b16 v189, v0 offset:60720
	v_cvt_pk_bf16_f32 v0, v30, s0
	ds_write_b16 v189, v0 offset:59168
	v_cvt_pk_bf16_f32 v0, v31, s0
	ds_write_b16 v189, v0 offset:59696
	v_cvt_pk_bf16_f32 v0, v32, s0
	ds_write_b16 v189, v0 offset:60224
	v_cvt_pk_bf16_f32 v0, v33, s0
	ds_write_b16 v189, v0 offset:60752
	v_cvt_pk_bf16_f32 v0, v26, s0
	ds_write_b16 v189, v0 offset:59200
	v_cvt_pk_bf16_f32 v0, v27, s0
	ds_write_b16 v189, v0 offset:59728
	v_cvt_pk_bf16_f32 v0, v28, s0
	ds_write_b16 v189, v0 offset:60256
	v_cvt_pk_bf16_f32 v0, v29, s0
	ds_write_b16 v189, v0 offset:60784
	v_cvt_pk_bf16_f32 v0, v22, s0
	ds_write_b16 v189, v0 offset:59232
	v_cvt_pk_bf16_f32 v0, v23, s0
	ds_write_b16 v189, v0 offset:59760
	v_cvt_pk_bf16_f32 v0, v24, s0
	s_ashr_i32 s43, s42, 31
	ds_write_b16 v189, v0 offset:60288
	v_cvt_pk_bf16_f32 v0, v25, s0
	v_mov_b32_e32 v34, v175
	s_lshl_b64 s[12:13], s[42:43], 1
	ds_write_b16 v189, v0 offset:60816
	s_waitcnt lgkmcnt(0)
	s_barrier
; #define RTID opaque_tid()
; __device__ __forceinline__ void phase_gemm_f32(const u16* A, const u16* Bt, int K, u16* out, u16* smem,
;                                                volatile LAS unsigned* vb_) {
;     ...
;     const int tid2 = RTID;
; #pragma unroll
;     for (int k = 0; k < 16; ++k) {
;       const int c = tid2 + 512 * k;
;       const int row = c >> 5, ch = c & 31;
;       const uint4 v = *(const uint4*)(smem + row * 264 + ch * 8);
;       *(uint4*)(out + (size_t)(mt * 256 + row) * 1024 + nt * 256 + ch * 8) = v;
;     }
;     __syncthreads();
;   }
	s_add_u32 s12, s11, s12
	v_lshlrev_b32_e32 v0, 4, v34
	v_and_b32_e32 v0, 0x1f0, v0
	s_addc_u32 s13, s20, s13
	v_ashrrev_i32_e32 v26, 5, v34
	v_lshl_add_u64 v[30:31], s[12:13], 0, v[0:1]
	v_mad_u64_u32 v[22:23], s[12:13], v26, s2, v[0:1]
	v_add_u32_e32 v26, s23, v26
	v_ashrrev_i32_e32 v27, 31, v26
	ds_read_b128 v[22:25], v22
	v_lshlrev_b64 v[26:27], 11, v[26:27]
	v_lshl_add_u64 v[32:33], v[30:31], 0, v[26:27]
	v_add_u32_e32 v26, 0x200, v34
	v_ashrrev_i32_e32 v35, 5, v26
	v_mad_u64_u32 v[26:27], s[12:13], v35, s2, v[0:1]
	ds_read_b128 v[26:29], v26
	s_waitcnt lgkmcnt(1)
	global_store_dwordx4 v[32:33], v[22:25], off
	s_and_b64 vcc, exec, s[40:41]
	s_mov_b32 s37, s36
	v_add_u32_e32 v22, s23, v35
	v_ashrrev_i32_e32 v23, 31, v22
	v_lshlrev_b64 v[22:23], 11, v[22:23]
	v_lshl_add_u64 v[22:23], v[30:31], 0, v[22:23]
	s_waitcnt lgkmcnt(0)
	global_store_dwordx4 v[22:23], v[26:29], off
	v_add_u32_e32 v22, 0x400, v34
	s_nop 0
	v_ashrrev_i32_e32 v26, 5, v22
	v_mad_u64_u32 v[22:23], s[12:13], v26, s2, v[0:1]
	v_add_u32_e32 v26, s23, v26
	v_ashrrev_i32_e32 v27, 31, v26
	ds_read_b128 v[22:25], v22
	v_lshlrev_b64 v[26:27], 11, v[26:27]
	v_lshl_add_u64 v[32:33], v[30:31], 0, v[26:27]
	v_add_u32_e32 v26, 0x600, v34
	v_ashrrev_i32_e32 v35, 5, v26
	v_mad_u64_u32 v[26:27], s[12:13], v35, s2, v[0:1]
	ds_read_b128 v[26:29], v26
	s_waitcnt lgkmcnt(1)
	global_store_dwordx4 v[32:33], v[22:25], off
	s_nop 1
	v_add_u32_e32 v22, s23, v35
	v_ashrrev_i32_e32 v23, 31, v22
	v_lshlrev_b64 v[22:23], 11, v[22:23]
	v_lshl_add_u64 v[22:23], v[30:31], 0, v[22:23]
	s_waitcnt lgkmcnt(0)
	global_store_dwordx4 v[22:23], v[26:29], off
	v_add_u32_e32 v22, 0x800, v34
	s_nop 0
	v_ashrrev_i32_e32 v26, 5, v22
	v_mad_u64_u32 v[22:23], s[12:13], v26, s2, v[0:1]
	v_add_u32_e32 v26, s23, v26
	v_ashrrev_i32_e32 v27, 31, v26
	ds_read_b128 v[22:25], v22
	v_lshlrev_b64 v[26:27], 11, v[26:27]
	v_lshl_add_u64 v[32:33], v[30:31], 0, v[26:27]
	v_add_u32_e32 v26, 0xa00, v34
	v_ashrrev_i32_e32 v35, 5, v26
	v_mad_u64_u32 v[26:27], s[12:13], v35, s2, v[0:1]
	ds_read_b128 v[26:29], v26
	s_waitcnt lgkmcnt(1)
	global_store_dwordx4 v[32:33], v[22:25], off
	s_nop 1
	v_add_u32_e32 v22, s23, v35
	v_ashrrev_i32_e32 v23, 31, v22
	v_lshlrev_b64 v[22:23], 11, v[22:23]
	v_lshl_add_u64 v[22:23], v[30:31], 0, v[22:23]
	s_waitcnt lgkmcnt(0)
	global_store_dwordx4 v[22:23], v[26:29], off
	v_add_u32_e32 v22, 0xc00, v34
	s_nop 0
	v_ashrrev_i32_e32 v26, 5, v22
	v_mad_u64_u32 v[22:23], s[12:13], v26, s2, v[0:1]
	v_add_u32_e32 v26, s23, v26
	v_ashrrev_i32_e32 v27, 31, v26
	ds_read_b128 v[22:25], v22
	v_lshlrev_b64 v[26:27], 11, v[26:27]
	v_lshl_add_u64 v[32:33], v[30:31], 0, v[26:27]
	v_add_u32_e32 v26, 0xe00, v34
	v_ashrrev_i32_e32 v35, 5, v26
	v_mad_u64_u32 v[26:27], s[12:13], v35, s2, v[0:1]
	ds_read_b128 v[26:29], v26
	s_waitcnt lgkmcnt(1)
	global_store_dwordx4 v[32:33], v[22:25], off
	s_nop 1
	v_add_u32_e32 v22, s23, v35
	v_ashrrev_i32_e32 v23, 31, v22
	v_lshlrev_b64 v[22:23], 11, v[22:23]
	v_lshl_add_u64 v[22:23], v[30:31], 0, v[22:23]
	s_waitcnt lgkmcnt(0)
	global_store_dwordx4 v[22:23], v[26:29], off
	v_add_u32_e32 v22, 0x1000, v34
	s_nop 0
	v_ashrrev_i32_e32 v26, 5, v22
	v_mad_u64_u32 v[22:23], s[12:13], v26, s2, v[0:1]
	v_add_u32_e32 v26, s23, v26
	v_ashrrev_i32_e32 v27, 31, v26
	ds_read_b128 v[22:25], v22
	v_lshlrev_b64 v[26:27], 11, v[26:27]
	v_lshl_add_u64 v[32:33], v[30:31], 0, v[26:27]
	v_add_u32_e32 v26, 0x1200, v34
	v_ashrrev_i32_e32 v35, 5, v26
	v_mad_u64_u32 v[26:27], s[12:13], v35, s2, v[0:1]
	ds_read_b128 v[26:29], v26
	s_waitcnt lgkmcnt(1)
	global_store_dwordx4 v[32:33], v[22:25], off
	s_nop 1
	v_add_u32_e32 v22, s23, v35
	v_ashrrev_i32_e32 v23, 31, v22
	v_lshlrev_b64 v[22:23], 11, v[22:23]
	v_lshl_add_u64 v[22:23], v[30:31], 0, v[22:23]
	s_waitcnt lgkmcnt(0)
	global_store_dwordx4 v[22:23], v[26:29], off
	v_add_u32_e32 v22, 0x1400, v34
	s_nop 0
	v_ashrrev_i32_e32 v26, 5, v22
	v_mad_u64_u32 v[22:23], s[12:13], v26, s2, v[0:1]
	v_add_u32_e32 v26, s23, v26
	v_ashrrev_i32_e32 v27, 31, v26
	ds_read_b128 v[22:25], v22
	v_lshlrev_b64 v[26:27], 11, v[26:27]
	v_lshl_add_u64 v[32:33], v[30:31], 0, v[26:27]
	v_add_u32_e32 v26, 0x1600, v34
	v_ashrrev_i32_e32 v35, 5, v26
	v_mad_u64_u32 v[26:27], s[12:13], v35, s2, v[0:1]
	ds_read_b128 v[26:29], v26
	s_waitcnt lgkmcnt(1)
	global_store_dwordx4 v[32:33], v[22:25], off
	s_nop 1
	v_add_u32_e32 v22, s23, v35
	v_ashrrev_i32_e32 v23, 31, v22
	v_lshlrev_b64 v[22:23], 11, v[22:23]
	v_lshl_add_u64 v[22:23], v[30:31], 0, v[22:23]
	s_waitcnt lgkmcnt(0)
	global_store_dwordx4 v[22:23], v[26:29], off
	v_add_u32_e32 v22, 0x1800, v34
	s_nop 0
	v_ashrrev_i32_e32 v26, 5, v22
	v_mad_u64_u32 v[22:23], s[12:13], v26, s2, v[0:1]
	v_add_u32_e32 v26, s23, v26
	v_ashrrev_i32_e32 v27, 31, v26
	ds_read_b128 v[22:25], v22
	v_lshlrev_b64 v[26:27], 11, v[26:27]
	v_lshl_add_u64 v[32:33], v[30:31], 0, v[26:27]
	v_add_u32_e32 v26, 0x1a00, v34
	v_ashrrev_i32_e32 v35, 5, v26
	v_mad_u64_u32 v[26:27], s[12:13], v35, s2, v[0:1]
	ds_read_b128 v[26:29], v26
	s_waitcnt lgkmcnt(1)
	global_store_dwordx4 v[32:33], v[22:25], off
	s_nop 1
	v_add_u32_e32 v22, s23, v35
	v_ashrrev_i32_e32 v23, 31, v22
	v_lshlrev_b64 v[22:23], 11, v[22:23]
	v_lshl_add_u64 v[22:23], v[30:31], 0, v[22:23]
	s_waitcnt lgkmcnt(0)
	global_store_dwordx4 v[22:23], v[26:29], off
	v_add_u32_e32 v22, 0x1c00, v34
	s_nop 0
	v_ashrrev_i32_e32 v26, 5, v22
	v_mad_u64_u32 v[22:23], s[12:13], v26, s2, v[0:1]
	v_add_u32_e32 v26, s23, v26
	v_ashrrev_i32_e32 v27, 31, v26
	ds_read_b128 v[22:25], v22
	v_lshlrev_b64 v[26:27], 11, v[26:27]
	v_lshl_add_u64 v[32:33], v[30:31], 0, v[26:27]
	v_add_u32_e32 v26, 0x1e00, v34
	v_ashrrev_i32_e32 v34, 5, v26
	v_mad_u64_u32 v[26:27], s[12:13], v34, s2, v[0:1]
	ds_read_b128 v[26:29], v26
	s_waitcnt lgkmcnt(1)
	global_store_dwordx4 v[32:33], v[22:25], off
	s_mov_b64 s[12:13], -1
	s_nop 0
	v_add_u32_e32 v22, s23, v34
	v_ashrrev_i32_e32 v23, 31, v22
	v_lshlrev_b64 v[22:23], 11, v[22:23]
	v_lshl_add_u64 v[22:23], v[30:31], 0, v[22:23]
	s_waitcnt lgkmcnt(0)
	global_store_dwordx4 v[22:23], v[26:29], off
	s_barrier
	s_cbranch_vccz .LBB0_478

; #define RTID opaque_tid()
; #define ZERO_ACC8(acc, NJ_)                             \
;   _Pragma("unroll") for (int i_ = 0; i_ < 8; ++i_)      \
;   _Pragma("unroll") for (int j_ = 0; j_ < (NJ_); ++j_) { acc[i_][j_] = (f32x4){0.f, 0.f, 0.f, 0.f}; }
; template <int MI, int NJ> ...
;     ...
;   const int lrow = tid >> 3, lkc = tid & 7;
;   const u16* Ag = A + (size_t)(row0 + lrow) * lda + kbeg + lkc * 8;
;   const u16* Bg = Bt + (size_t)(col0 + lrow) * ldb + kbeg + lkc * 8;
;   const size_t a64 = (size_t)64 * lda, b64 = (size_t)64 * ldb;
;   const int nk = (kend - kbeg) >> 6;
;   const long long nAoff = (long long)(nrow0 - row0) * lda + (nkbeg - kbeg);
;   const long long nBoff = (long long)(ncol0 - col0) * ldb + (nkbeg - kbeg);
;   u16* wa = sA + lrow * 64 + ((lkc ^ (lrow & 7)) * 8);
;   u16* wb = sB + lrow * 64 + ((lkc ^ (lrow & 7)) * 8);
;     ...
;   if (!pre) G8LOADP(Ag, Bg);
;   G8STORE(0);
;   {
;     const u16* ga_ = (1 < nk) ? Ag + 64 : Ag + nAoff;
;     const u16* gb_ = (1 < nk) ? Bg + 64 : Bg + nBoff;
;     G8LOADP(ga_, gb_);
;   }
;   __syncthreads();
; __device__ __forceinline__ void phase_ffn_up(const Params& p, const u16* Wgu, u16* smem, volatile LAS unsigned* vb_) {
;     ...
;   const int tid = RTID;
;   const int lane = tid & 63, wave = tid >> 6;
;   const int wm = wave >> 2, wn = wave & 3;
;   const int vb = real_vb(vb_);
;   const int step = gridDim.x >> 3;
;   G8REGS_DECL;
;   bool pre = false;
;   for (int lt = vb >> 3; lt < 8 * 20; lt += step) {
;     const int nt = lt >> 3, mt = (vb & 7) * 8 + (lt & 7);
;     const int ltn = (lt + step < 8 * 20) ? lt + step : lt;
;     f32x4 acc[8][4];
;     ZERO_ACC8(acc, 4);
;     gemm8<8, 4>(acc, G8REGS_ARGS, pre, H, 1024, Wgu, 1024, 0, 1024, mt * 256, nt * 256,
;                 ((vb & 7) * 8 + (ltn & 7)) * 256, (ltn >> 3) * 256, 0, smem, tid);
.LBB0_595:
	s_nop 0
	v_readlane_b32 s0, v255, 0
	v_readlane_b32 s1, v255, 1
	s_and_b64 vcc, exec, s[0:1]
	s_cbranch_vccz .LBB0_608
	s_waitcnt vmcnt(15)
	v_mov_b32_e32 v2, v175
	ds_read_b32 v0, v230
	s_cmp_eq_u32 s82, 0
	s_cselect_b32 s0, 0, 0x1080000
	s_add_u32 s0, s72, s0
	s_addc_u32 s1, s73, 0
	s_waitcnt lgkmcnt(0)
	v_readfirstlane_b32 s37, v0
	s_ashr_i32 s36, s37, 3
	v_ashrrev_i32_e32 v176, 3, v2
	v_lshlrev_b32_e32 v3, 4, v2
	v_lshrrev_b32_e32 v4, 4, v2
	v_and_b32_e32 v5, 7, v2
	v_lshrrev_b32_e32 v180, 1, v2
	v_and_b32_e32 v179, 15, v2
	s_waitcnt vmcnt(13)
	v_lshrrev_b32_e32 v6, 2, v2
	s_mov_b32 s10, 0x1ffff80
	v_ashrrev_i32_e32 v177, 8, v2
	v_bfe_u32 v178, v2, 6, 2
	s_cmpk_gt_i32 s36, 0x9f
	v_and_b32_e32 v0, 0x70, v3
	v_xor_b32_e32 v184, v176, v2
	v_bitop3_b32 v182, v4, v5, 3 bitop3:0x6c
	v_and_or_b32 v183, v180, s10, v179
	v_and_b32_e32 v181, 12, v6
	s_cbranch_scc1 .LBB0_603
	v_lshlrev_b32_e32 v4, 4, v184
	s_lshl_b32 s10, s37, 3
	v_and_b32_e32 v4, 0x70, v4
	s_and_b32 s38, s10, 56
	v_readlane_b32 s10, v252, 38
	v_lshl_or_b32 v185, v176, 7, v4
	v_lshlrev_b32_e32 v4, 3, v182
	v_readlane_b32 s11, v252, 39
	v_xor_b32_e32 v5, 32, v4
	v_lshlrev_b32_e32 v6, 7, v2
	v_lshl_add_u64 v[162:163], s[10:11], 0, v[0:1]
	v_sub_u32_e32 v5, v5, v4
	v_lshlrev_b32_e32 v4, 4, v182
	v_and_b32_e32 v6, 0x6780, v6
	s_mov_b32 s10, 0x10000
	v_lshl_or_b32 v187, v183, 7, v4
	v_or3_b32 v188, v6, v4, s10
	v_lshlrev_b32_e32 v4, 1, v179
	v_lshl_or_b32 v8, v177, 7, v181
	v_lshl_or_b32 v4, v178, 6, v4
	v_and_b32_e32 v6, 0xf0, v3
	v_mov_b32_e32 v7, v1
	s_movk_i32 s12, 0x110
	v_lshl_add_u64 v[166:167], s[78:79], 0, v[6:7]
	v_ashrrev_i32_e32 v189, 4, v2
	v_mad_u64_u32 v[168:169], s[10:11], v8, s12, v[4:5]
	v_add_u32_e32 v4, 0x200, v2
	v_add_u32_e32 v7, 0x400, v2
	v_add_u32_e32 v8, 0x600, v2
	v_add_u32_e32 v9, 0x800, v2
	s_waitcnt vmcnt(12)
	v_add_u32_e32 v10, 0xa00, v2
	v_add_u32_e32 v11, 0xc00, v2
	v_add_u32_e32 v2, 0xe00, v2
	v_ashrrev_i32_e32 v169, 4, v4
	v_ashrrev_i32_e32 v190, 4, v7
	v_ashrrev_i32_e32 v191, 4, v8
	v_ashrrev_i32_e32 v192, 4, v9
	v_ashrrev_i32_e32 v193, 4, v10
	v_ashrrev_i32_e32 v194, 4, v11
	v_ashrrev_i32_e32 v195, 4, v2
	v_mul_lo_u32 v3, v189, s12
	v_mul_lo_u32 v4, v169, s12
	v_mul_lo_u32 v7, v190, s12
	v_mul_lo_u32 v8, v191, s12
	v_mul_lo_u32 v9, v192, s12
	v_mul_lo_u32 v10, v193, s12
	v_mul_lo_u32 v11, v194, s12
	v_mul_lo_u32 v2, v195, s12
	v_lshl_add_u64 v[164:165], s[0:1], 0, v[0:1]
	v_add_u32_e32 v186, 0x10000, v185
	s_mov_b64 s[12:13], 0
	v_lshlrev_b32_e32 v196, 1, v5
	v_add_u32_e32 v197, v6, v3
	v_add_u32_e32 v198, v6, v4
	v_add_u32_e32 v199, v6, v7
	v_add_u32_e32 v200, v6, v8
	v_add_u32_e32 v204, v6, v9
	v_add_u32_e32 v205, v6, v10
	v_add_u32_e32 v206, v6, v11
	v_add_u32_e32 v207, v6, v2
	s_mov_b32 s20, s36
	v_bfe_u32 v250, v175, 3, 3
	v_and_b32_e32 v251, 7, v175
	v_lshlrev_b32_e32 v251, 4, v251
	v_lshl_add_u32 v250, v250, 11, v251
	v_add_u32_e32 v251, 0x20000, v250
.LBB0_598:
	s_and_b32 s22, s20, 7
	s_or_b32 s10, s22, s38
	s_lshl_b32 s39, s10, 8
	s_waitcnt vmcnt(4)
	v_add_u32_e32 v34, s39, v176
	s_ashr_i32 s40, s20, 3
	v_ashrrev_i32_e32 v35, 31, v34
	s_lshl_b32 s21, s40, 8
	v_lshlrev_b64 v[34:35], 11, v[34:35]
	v_lshl_add_u64 v[170:171], v[162:163], 0, v[34:35]
	v_add_u32_e32 v34, s21, v176
	v_ashrrev_i32_e32 v35, 31, v34
	v_lshlrev_b64 v[34:35], 11, v[34:35]
	v_lshl_add_u64 v[172:173], v[164:165], 0, v[34:35]
	v_readfirstlane_b32 s62, v170
	v_readfirstlane_b32 s63, v171
	v_readfirstlane_b32 s64, v172
	v_readfirstlane_b32 s65, v173
	v_add_u32_e32 v172, 0x40000, v250
	v_add_u32_e32 v173, 0x60000, v250
	s_nop 1
	s_and_b64 vcc, exec, s[12:13]
	s_cbranch_vccnz .LBB0_600
	global_load_dwordx4 v[2:5], v250, s[62:63]
	global_load_dwordx4 v[6:9], v251, s[62:63]
	global_load_dwordx4 v[10:13], v172, s[62:63]
	global_load_dwordx4 v[18:21], v173, s[62:63]
	global_load_dwordx4 v[14:17], v250, s[64:65]
	global_load_dwordx4 v[22:25], v251, s[64:65]
	global_load_dwordx4 v[26:29], v172, s[64:65]
	global_load_dwordx4 v[30:33], v173, s[64:65]
.LBB0_600:
	s_waitcnt vmcnt(5)
	ds_write_b128 v185, v[2:5]
	ds_write_b128 v185, v[6:9] offset:8192
	ds_write_b128 v185, v[10:13] offset:16384
	s_waitcnt vmcnt(3)
	ds_write_b128 v185, v[18:21] offset:24576
	ds_write_b128 v186, v[14:17]
	s_waitcnt vmcnt(2)
	ds_write_b128 v186, v[22:25] offset:8192
	s_waitcnt vmcnt(1)
	ds_write_b128 v186, v[26:29] offset:16384
	s_waitcnt vmcnt(0)
; template <int MI, int NJ> ...
;     ...
;   if (!pre) G8LOADP(Ag, Bg);
;   G8STORE(0);
;   {
;     const u16* ga_ = (1 < nk) ? Ag + 64 : Ag + nAoff;
;     const u16* gb_ = (1 < nk) ? Bg + 64 : Bg + nBoff;
;     G8LOADP(ga_, gb_);
;   }
;   __syncthreads();
;   const int sw0 = ((lane >> 4) ^ (lane & 7)) * 8;
;   const int dsw = (sw0 ^ 32) - sw0;
;   const u16* ra_ = sA + (wm * (16 * MI) + (lane & 15)) * 64 + sw0;
;   const u16* rb_ = sB + (wn * (16 * NJ) + (lane & 15)) * 64 + sw0;
;   for (int kt = 0; kt < nk; ++kt) {
;     const int buf = kt & 1;
;     {
;       G8STORE(buf ^ 1);
;       const u16* ga_ = (kt + 2 < nk) ? Ag + (kt + 2) * 64 : Ag + nAoff;
;       const u16* gb_ = (kt + 2 < nk) ? Bg + (kt + 2) * 64 : Bg + nBoff;
;       G8LOADP(ga_, gb_);
	ds_write_b128 v186, v[30:33] offset:24576
	s_add_i32 s41, s20, s70
	s_cmpk_gt_i32 s41, 0x9f
	s_cselect_b64 s[10:11], -1, 0
	global_load_dwordx4 v[2:5], v250, s[62:63] offset:128
	global_load_dwordx4 v[6:9], v251, s[62:63] offset:128
	global_load_dwordx4 v[10:13], v172, s[62:63] offset:128
	global_load_dwordx4 v[18:21], v173, s[62:63] offset:128
	global_load_dwordx4 v[14:17], v250, s[64:65] offset:128
	global_load_dwordx4 v[22:25], v251, s[64:65] offset:128
	global_load_dwordx4 v[26:29], v172, s[64:65] offset:128
	global_load_dwordx4 v[30:33], v173, s[64:65] offset:128
	s_cmpk_lt_i32 s41, 0xa0
	s_cselect_b32 s12, s41, s20
	s_and_b32 s13, s12, 7
	s_lshl_b32 s12, s12, 5
	s_and_b32 s20, s12, 0xffffff00
	s_sub_i32 s12, s13, s22
	s_lshl_b32 s12, s12, 8
	s_sub_i32 s20, s20, s21
	s_ashr_i32 s13, s12, 31
	s_ashr_i32 s21, s20, 31
	v_mov_b32_e32 v34, 0
	s_lshl_b64 s[12:13], s[12:13], 10
	s_lshl_b64 s[20:21], s[20:21], 10
	s_mov_b32 s42, 0
	s_mov_b64 s[22:23], 0x80
	s_mov_b32 s43, 0
	v_mov_b32_e32 v35, v34
	v_mov_b32_e32 v36, v34
	v_mov_b32_e32 v37, v34
	v_mov_b32_e32 v38, v34
	v_mov_b32_e32 v39, v34
	v_mov_b32_e32 v40, v34
	v_mov_b32_e32 v41, v34
	v_mov_b32_e32 v42, v34
	v_mov_b32_e32 v43, v34
	v_mov_b32_e32 v44, v34
	v_mov_b32_e32 v45, v34
	v_mov_b32_e32 v46, v34
	v_mov_b32_e32 v47, v34
	v_mov_b32_e32 v48, v34
	v_mov_b32_e32 v49, v34
	v_mov_b32_e32 v50, v34
	v_mov_b32_e32 v51, v34
	v_mov_b32_e32 v52, v34
	v_mov_b32_e32 v53, v34
	v_mov_b32_e32 v54, v34
	v_mov_b32_e32 v55, v34
	v_mov_b32_e32 v56, v34
	v_mov_b32_e32 v57, v34
	v_mov_b32_e32 v58, v34
	v_mov_b32_e32 v59, v34
	v_mov_b32_e32 v60, v34
	v_mov_b32_e32 v61, v34
	v_mov_b32_e32 v62, v34
	v_mov_b32_e32 v63, v34
	v_mov_b32_e32 v64, v34
	v_mov_b32_e32 v65, v34
	v_mov_b32_e32 v66, v34
	v_mov_b32_e32 v67, v34
	v_mov_b32_e32 v68, v34
	v_mov_b32_e32 v69, v34
	v_mov_b32_e32 v70, v34
	v_mov_b32_e32 v71, v34
	v_mov_b32_e32 v72, v34
	v_mov_b32_e32 v73, v34
	v_mov_b32_e32 v74, v34
	v_mov_b32_e32 v75, v34
	v_mov_b32_e32 v76, v34
	v_mov_b32_e32 v77, v34
	v_mov_b32_e32 v78, v34
	v_mov_b32_e32 v79, v34
	v_mov_b32_e32 v80, v34
	v_mov_b32_e32 v81, v34
	v_mov_b32_e32 v82, v34
	v_mov_b32_e32 v83, v34
	v_mov_b32_e32 v84, v34
	v_mov_b32_e32 v85, v34
	v_mov_b32_e32 v86, v34
	v_mov_b32_e32 v87, v34
	v_mov_b32_e32 v88, v34
	v_mov_b32_e32 v89, v34
	v_mov_b32_e32 v90, v34
	v_mov_b32_e32 v91, v34
	v_mov_b32_e32 v92, v34
	v_mov_b32_e32 v93, v34
	v_mov_b32_e32 v94, v34
	v_mov_b32_e32 v95, v34
	v_mov_b32_e32 v96, v34
	v_mov_b32_e32 v97, v34
	v_mov_b32_e32 v98, v34
	v_mov_b32_e32 v99, v34
	v_mov_b32_e32 v100, v34
	v_mov_b32_e32 v101, v34
	v_mov_b32_e32 v102, v34
	v_mov_b32_e32 v103, v34
	v_mov_b32_e32 v104, v34
	v_mov_b32_e32 v105, v34
	v_mov_b32_e32 v106, v34
	v_mov_b32_e32 v107, v34
	v_mov_b32_e32 v108, v34
	v_mov_b32_e32 v109, v34
	v_mov_b32_e32 v110, v34
	v_mov_b32_e32 v111, v34
	v_mov_b32_e32 v112, v34
	v_mov_b32_e32 v113, v34
	v_mov_b32_e32 v114, v34
	v_mov_b32_e32 v115, v34
	v_mov_b32_e32 v116, v34
	v_mov_b32_e32 v117, v34
	v_mov_b32_e32 v118, v34
	v_mov_b32_e32 v119, v34
	v_mov_b32_e32 v120, v34
	v_mov_b32_e32 v121, v34
	v_mov_b32_e32 v122, v34
	v_mov_b32_e32 v123, v34
	v_mov_b32_e32 v124, v34
	v_mov_b32_e32 v125, v34
	v_mov_b32_e32 v126, v34
	v_mov_b32_e32 v127, v34
	v_mov_b32_e32 v128, v34
	v_mov_b32_e32 v129, v34
	v_mov_b32_e32 v130, v34
	v_mov_b32_e32 v131, v34
	v_mov_b32_e32 v132, v34
	v_mov_b32_e32 v133, v34
	v_mov_b32_e32 v134, v34
	v_mov_b32_e32 v135, v34
	v_mov_b32_e32 v136, v34
	v_mov_b32_e32 v137, v34
	v_mov_b32_e32 v138, v34
	v_mov_b32_e32 v139, v34
	v_mov_b32_e32 v140, v34
	v_mov_b32_e32 v141, v34
	v_mov_b32_e32 v142, v34
	v_mov_b32_e32 v143, v34
	v_mov_b32_e32 v144, v34
	v_mov_b32_e32 v145, v34
	v_mov_b32_e32 v146, v34
	v_mov_b32_e32 v147, v34
	v_mov_b32_e32 v148, v34
	v_mov_b32_e32 v149, v34
	v_mov_b32_e32 v150, v34
	v_mov_b32_e32 v151, v34
	v_mov_b32_e32 v152, v34
	v_mov_b32_e32 v153, v34
	v_mov_b32_e32 v154, v34
	v_mov_b32_e32 v155, v34
	v_mov_b32_e32 v156, v34
	v_mov_b32_e32 v157, v34
	v_mov_b32_e32 v158, v34
	v_mov_b32_e32 v159, v34
	v_mov_b32_e32 v160, v34
	v_mov_b32_e32 v161, v34
	s_waitcnt lgkmcnt(0)
	s_barrier
.LBB0_601:
	s_and_b32 s48, s42, 0x4000
	s_xor_b32 s44, s48, 0x4000
	s_lshl_b32 s44, s44, 1
	v_add_u32_e32 v170, s44, v185
	v_add_u32_e32 v171, s44, v186
	s_cmp_lt_u32 s43, 14
	s_cselect_b32 s45, s23, s13
	s_cselect_b32 s44, s22, s12
	s_cselect_b32 s47, s23, s21
	s_cselect_b32 s46, s22, s20
	s_lshl_b64 s[44:45], s[44:45], 1
	s_lshl_b64 s[46:47], s[46:47], 1
	s_add_u32 s50, s62, s44
	s_addc_u32 s51, s63, s45
	s_add_u32 s52, s64, s46
	s_addc_u32 s53, s65, s47
	s_setprio 1
	s_lshl_b32 s44, s48, 1
	v_add_u32_e32 v228, s44, v187
	v_add_u32_e32 v229, s44, v188
	ds_read_b128 v[212:215], v229
	ds_read_b128 v[208:211], v228
	ds_read_b128 v[216:219], v229 offset:2048
	ds_read_b128 v[220:223], v229 offset:4096
	ds_read_b128 v[224:227], v229 offset:6144
	ds_read_b128 v[234:237], v228 offset:2048
	ds_read_b128 v[238:241], v228 offset:4096
	v_add_u32_e32 v229, v229, v196
	s_waitcnt lgkmcnt(5)
	v_mfma_f32_16x16x32_bf16 v[158:161], v[208:211], v[212:215], v[158:161]
	s_waitcnt lgkmcnt(4)
	v_mfma_f32_16x16x32_bf16 v[154:157], v[208:211], v[216:219], v[154:157]
	s_waitcnt lgkmcnt(3)
	v_mfma_f32_16x16x32_bf16 v[150:153], v[208:211], v[220:223], v[150:153]
	s_waitcnt lgkmcnt(2)
	v_mfma_f32_16x16x32_bf16 v[146:149], v[208:211], v[224:227], v[146:149]
	ds_read_b128 v[208:211], v228 offset:6144
	s_waitcnt lgkmcnt(2)
	v_mfma_f32_16x16x32_bf16 v[142:145], v[234:237], v[212:215], v[142:145]
	v_mfma_f32_16x16x32_bf16 v[138:141], v[234:237], v[216:219], v[138:141]
	v_mfma_f32_16x16x32_bf16 v[134:137], v[234:237], v[220:223], v[134:137]
	v_mfma_f32_16x16x32_bf16 v[130:133], v[234:237], v[224:227], v[130:133]
	ds_read_b128 v[234:237], v228 offset:8192
	s_waitcnt vmcnt(7)
; template <int MI, int NJ> ...
;     ...
;   for (int kt = 0; kt < nk; ++kt) {
;     const int buf = kt & 1;
;     {
;       G8STORE(buf ^ 1);
;       const u16* ga_ = (kt + 2 < nk) ? Ag + (kt + 2) * 64 : Ag + nAoff;
;       const u16* gb_ = (kt + 2 < nk) ? Bg + (kt + 2) * 64 : Bg + nBoff;
;       G8LOADP(ga_, gb_);
;     }
;     __builtin_amdgcn_sched_barrier(0);
;     __builtin_amdgcn_s_setprio(1);
;     const u16* a = ra_ + buf * AROWS * 64;
;     const u16* b = rb_ + buf * BROWS * 64;
; #pragma unroll
;     for (int ks = 0; ks < 2; ++ks) {
;       const u16* a_ = ks ? a + dsw : a;
;       const u16* b_ = ks ? b + dsw : b;
;       bf16x8 bfr[NJ];
; #pragma unroll
;       for (int j = 0; j < NJ; ++j) bfr[j] = *(const bf16x8*)(b_ + j * 16 * 64);
; #pragma unroll
;       for (int ih = 0; ih < MI / 4; ++ih) {
;         bf16x8 af[4];
; #pragma unroll
;         for (int i = 0; i < 4; ++i) af[i] = *(const bf16x8*)(a_ + (ih * 4 + i) * 16 * 64);
; #pragma unroll
;         for (int i = 0; i < 4; ++i)
; #pragma unroll
;           for (int j = 0; j < NJ; ++j) acc[ih * 4 + i][j] = mfma16(af[i], bfr[j], acc[ih * 4 + i][j]);
;       }
;     }
;     __builtin_amdgcn_s_setprio(0);
;     __builtin_amdgcn_sched_barrier(0);
;     __syncthreads();
;   }
	ds_write_b128 v170, v[2:5]
	global_load_dwordx4 v[2:5], v250, s[50:51]
	s_waitcnt lgkmcnt(3)
	v_mfma_f32_16x16x32_bf16 v[126:129], v[238:241], v[212:215], v[126:129]
	v_mfma_f32_16x16x32_bf16 v[122:125], v[238:241], v[216:219], v[122:125]
	v_mfma_f32_16x16x32_bf16 v[118:121], v[238:241], v[220:223], v[118:121]
	v_mfma_f32_16x16x32_bf16 v[114:117], v[238:241], v[224:227], v[114:117]
	ds_read_b128 v[238:241], v228 offset:10240
	s_waitcnt vmcnt(7)
	ds_write_b128 v170, v[6:9] offset:8192
	global_load_dwordx4 v[6:9], v251, s[50:51]
	ds_read_b128 v[242:245], v229
	s_waitcnt lgkmcnt(5)
	v_mfma_f32_16x16x32_bf16 v[110:113], v[208:211], v[212:215], v[110:113]
	v_mfma_f32_16x16x32_bf16 v[106:109], v[208:211], v[216:219], v[106:109]
	v_mfma_f32_16x16x32_bf16 v[102:105], v[208:211], v[220:223], v[102:105]
	v_mfma_f32_16x16x32_bf16 v[98:101], v[208:211], v[224:227], v[98:101]
	ds_read_b128 v[208:211], v228 offset:12288
	s_waitcnt vmcnt(7)
	ds_write_b128 v170, v[10:13] offset:16384
	global_load_dwordx4 v[10:13], v172, s[50:51]
	ds_read_b128 v[246:249], v229 offset:2048
	s_waitcnt lgkmcnt(7)
	v_mfma_f32_16x16x32_bf16 v[94:97], v[234:237], v[212:215], v[94:97]
	v_mfma_f32_16x16x32_bf16 v[90:93], v[234:237], v[216:219], v[90:93]
	v_mfma_f32_16x16x32_bf16 v[86:89], v[234:237], v[220:223], v[86:89]
	v_mfma_f32_16x16x32_bf16 v[82:85], v[234:237], v[224:227], v[82:85]
	ds_read_b128 v[234:237], v228 offset:14336
	s_waitcnt vmcnt(7)
	ds_write_b128 v170, v[18:21] offset:24576
	global_load_dwordx4 v[18:21], v173, s[50:51]
	s_waitcnt lgkmcnt(7)
	v_mfma_f32_16x16x32_bf16 v[78:81], v[238:241], v[212:215], v[78:81]
	v_mfma_f32_16x16x32_bf16 v[74:77], v[238:241], v[216:219], v[74:77]
	v_mfma_f32_16x16x32_bf16 v[70:73], v[238:241], v[220:223], v[70:73]
	v_mfma_f32_16x16x32_bf16 v[66:69], v[238:241], v[224:227], v[66:69]
	v_add_u32_e32 v228, v228, v196
	ds_read_b128 v[238:241], v228
	s_waitcnt vmcnt(7)
	ds_write_b128 v171, v[14:17]
	global_load_dwordx4 v[14:17], v250, s[52:53]
	s_waitcnt lgkmcnt(6)
	v_mfma_f32_16x16x32_bf16 v[62:65], v[208:211], v[212:215], v[62:65]
	v_mfma_f32_16x16x32_bf16 v[58:61], v[208:211], v[216:219], v[58:61]
	v_mfma_f32_16x16x32_bf16 v[54:57], v[208:211], v[220:223], v[54:57]
	v_mfma_f32_16x16x32_bf16 v[50:53], v[208:211], v[224:227], v[50:53]
	ds_read_b128 v[208:211], v228 offset:2048
	s_waitcnt vmcnt(7)
	ds_write_b128 v171, v[22:25] offset:8192
	global_load_dwordx4 v[22:25], v251, s[52:53]
	s_waitcnt lgkmcnt(5)
	v_mfma_f32_16x16x32_bf16 v[38:41], v[234:237], v[220:223], v[38:41]
	v_mfma_f32_16x16x32_bf16 v[34:37], v[234:237], v[224:227], v[34:37]
	ds_read_b128 v[220:223], v229 offset:4096
	ds_read_b128 v[224:227], v229 offset:6144
	v_mfma_f32_16x16x32_bf16 v[46:49], v[234:237], v[212:215], v[46:49]
	v_mfma_f32_16x16x32_bf16 v[42:45], v[234:237], v[216:219], v[42:45]
	ds_read_b128 v[234:237], v228 offset:4096
	s_waitcnt vmcnt(7)
	ds_write_b128 v171, v[26:29] offset:16384
	global_load_dwordx4 v[26:29], v172, s[52:53]
	s_waitcnt lgkmcnt(7)
	v_mfma_f32_16x16x32_bf16 v[158:161], v[238:241], v[242:245], v[158:161]
	v_mfma_f32_16x16x32_bf16 v[154:157], v[238:241], v[246:249], v[154:157]
	s_waitcnt lgkmcnt(2)
	v_mfma_f32_16x16x32_bf16 v[150:153], v[238:241], v[220:223], v[150:153]
	v_mfma_f32_16x16x32_bf16 v[146:149], v[238:241], v[224:227], v[146:149]
	ds_read_b128 v[238:241], v228 offset:6144
	s_waitcnt vmcnt(7)
	ds_write_b128 v171, v[30:33] offset:24576
	global_load_dwordx4 v[30:33], v173, s[52:53]
	s_waitcnt lgkmcnt(7)
	v_mfma_f32_16x16x32_bf16 v[142:145], v[208:211], v[242:245], v[142:145]
	v_mfma_f32_16x16x32_bf16 v[138:141], v[208:211], v[246:249], v[138:141]
	v_mfma_f32_16x16x32_bf16 v[134:137], v[208:211], v[220:223], v[134:137]
	v_mfma_f32_16x16x32_bf16 v[130:133], v[208:211], v[224:227], v[130:133]
	ds_read_b128 v[208:211], v228 offset:8192
	s_waitcnt lgkmcnt(4)
	v_mfma_f32_16x16x32_bf16 v[126:129], v[234:237], v[242:245], v[126:129]
	v_mfma_f32_16x16x32_bf16 v[122:125], v[234:237], v[246:249], v[122:125]
	v_mfma_f32_16x16x32_bf16 v[118:121], v[234:237], v[220:223], v[118:121]
	v_mfma_f32_16x16x32_bf16 v[114:117], v[234:237], v[224:227], v[114:117]
	ds_read_b128 v[234:237], v228 offset:10240
	s_waitcnt lgkmcnt(3)
	v_mfma_f32_16x16x32_bf16 v[110:113], v[238:241], v[242:245], v[110:113]
	v_mfma_f32_16x16x32_bf16 v[106:109], v[238:241], v[246:249], v[106:109]
	v_mfma_f32_16x16x32_bf16 v[102:105], v[238:241], v[220:223], v[102:105]
	v_mfma_f32_16x16x32_bf16 v[98:101], v[238:241], v[224:227], v[98:101]
	ds_read_b128 v[238:241], v228 offset:12288
	s_waitcnt lgkmcnt(2)
	v_mfma_f32_16x16x32_bf16 v[94:97], v[208:211], v[242:245], v[94:97]
	v_mfma_f32_16x16x32_bf16 v[90:93], v[208:211], v[246:249], v[90:93]
	v_mfma_f32_16x16x32_bf16 v[86:89], v[208:211], v[220:223], v[86:89]
	v_mfma_f32_16x16x32_bf16 v[82:85], v[208:211], v[224:227], v[82:85]
	ds_read_b128 v[208:211], v228 offset:14336
	s_waitcnt lgkmcnt(2)
	v_mfma_f32_16x16x32_bf16 v[78:81], v[234:237], v[242:245], v[78:81]
	v_mfma_f32_16x16x32_bf16 v[74:77], v[234:237], v[246:249], v[74:77]
	v_mfma_f32_16x16x32_bf16 v[70:73], v[234:237], v[220:223], v[70:73]
	v_mfma_f32_16x16x32_bf16 v[66:69], v[234:237], v[224:227], v[66:69]
	s_waitcnt lgkmcnt(1)
	v_mfma_f32_16x16x32_bf16 v[62:65], v[238:241], v[242:245], v[62:65]
	v_mfma_f32_16x16x32_bf16 v[58:61], v[238:241], v[246:249], v[58:61]
	v_mfma_f32_16x16x32_bf16 v[54:57], v[238:241], v[220:223], v[54:57]
	v_mfma_f32_16x16x32_bf16 v[50:53], v[238:241], v[224:227], v[50:53]
	s_waitcnt lgkmcnt(0)
	v_mfma_f32_16x16x32_bf16 v[46:49], v[208:211], v[242:245], v[46:49]
	v_mfma_f32_16x16x32_bf16 v[42:45], v[208:211], v[246:249], v[42:45]
	v_mfma_f32_16x16x32_bf16 v[38:41], v[208:211], v[220:223], v[38:41]
	v_mfma_f32_16x16x32_bf16 v[34:37], v[208:211], v[224:227], v[34:37]
	s_setprio 0
	s_add_i32 s43, s43, 1
	s_add_u32 s22, s22, 64
	s_addc_u32 s23, s23, 0
	s_addk_i32 s42, 0x4000
	s_cmpk_lg_i32 s22, 0x480
	s_barrier
; __device__ __forceinline__ float sigmoidf_(float x) { return 1.0f / (1.0f + __expf(-x)); }
; __device__ __forceinline__ float siluf_(float x) { return x / (1.0f + __expf(-x)); }
; __device__ __forceinline__ void phase_ffn_up(const Params& p, const u16* Wgu, u16* smem, volatile LAS unsigned* vb_) {
;     ...
; #pragma unroll
;     for (int i = 0; i < 8; ++i)
; #pragma unroll
;       for (int jp = 0; jp < 2; ++jp) {
; #pragma unroll
;         for (int r = 0; r < 4; ++r) {
;           const float g = acc[i][2 * jp][r], u = acc[i][2 * jp + 1][r];
;           smem[(wm * 128 + i * 16 + (lane >> 4) * 4 + r) * 136 + (wn * 2 + jp) * 16 + (lane & 15)] = f2bf(siluf_(g) * u);
;         }
;         __builtin_amdgcn_sched_barrier(0);
;       }
	s_cbranch_scc1 .LBB0_601
	v_mul_f32_e32 v170, 0xbfb8aa3b, v158
	v_exp_f32_e32 v170, v170
	s_nop 0
	v_add_f32_e32 v170, 1.0, v170
	v_div_scale_f32 v171, s[12:13], v170, v170, v158
	v_rcp_f32_e32 v172, v171
	s_nop 0
	v_fma_f32 v173, -v171, v172, 1.0
	v_fmac_f32_e32 v172, v173, v172
	v_div_scale_f32 v173, vcc, v158, v170, v158
	v_mul_f32_e32 v208, v173, v172
	v_fma_f32 v209, -v171, v208, v173
	v_fmac_f32_e32 v208, v209, v172
	v_fma_f32 v171, -v171, v208, v173
	v_div_fmas_f32 v171, v171, v172, v208
	v_div_fixup_f32 v158, v171, v170, v158
	v_mul_f32_e32 v154, v154, v158
	v_cvt_pk_bf16_f32 v154, v154, s0
	ds_write_b16 v168, v154
	v_mul_f32_e32 v154, 0xbfb8aa3b, v159
	v_exp_f32_e32 v154, v154
	s_nop 0
	v_add_f32_e32 v154, 1.0, v154
	v_div_scale_f32 v158, s[12:13], v154, v154, v159
	v_rcp_f32_e32 v170, v158
	s_nop 0
	v_fma_f32 v171, -v158, v170, 1.0
	v_fmac_f32_e32 v170, v171, v170
	v_div_scale_f32 v171, vcc, v159, v154, v159
	v_mul_f32_e32 v172, v171, v170
	v_fma_f32 v173, -v158, v172, v171
	v_fmac_f32_e32 v172, v173, v170
	v_fma_f32 v158, -v158, v172, v171
	v_div_fmas_f32 v158, v158, v170, v172
	v_div_fixup_f32 v154, v158, v154, v159
	v_mul_f32_e32 v154, v155, v154
	v_cvt_pk_bf16_f32 v154, v154, s0
	ds_write_b16 v168, v154 offset:272
	v_mul_f32_e32 v154, 0xbfb8aa3b, v160
	v_exp_f32_e32 v154, v154
	s_nop 0
	v_add_f32_e32 v154, 1.0, v154
	v_div_scale_f32 v155, s[12:13], v154, v154, v160
	v_rcp_f32_e32 v158, v155
	s_nop 0
	v_fma_f32 v159, -v155, v158, 1.0
	v_fmac_f32_e32 v158, v159, v158
	v_div_scale_f32 v159, vcc, v160, v154, v160
	v_mul_f32_e32 v170, v159, v158
	v_fma_f32 v171, -v155, v170, v159
	v_fmac_f32_e32 v170, v171, v158
	v_fma_f32 v155, -v155, v170, v159
	v_div_fmas_f32 v155, v155, v158, v170
	v_div_fixup_f32 v154, v155, v154, v160
	v_mul_f32_e32 v154, v156, v154
	v_cvt_pk_bf16_f32 v154, v154, s0
	ds_write_b16 v168, v154 offset:544
	v_mul_f32_e32 v154, 0xbfb8aa3b, v161
	v_exp_f32_e32 v154, v154
	s_nop 0
	v_add_f32_e32 v154, 1.0, v154
	v_div_scale_f32 v155, s[12:13], v154, v154, v161
	v_rcp_f32_e32 v156, v155
	s_nop 0
	v_fma_f32 v158, -v155, v156, 1.0
	v_fmac_f32_e32 v156, v158, v156
	v_div_scale_f32 v158, vcc, v161, v154, v161
	v_mul_f32_e32 v159, v158, v156
	v_fma_f32 v160, -v155, v159, v158
	v_fmac_f32_e32 v159, v160, v156
	v_fma_f32 v155, -v155, v159, v158
	v_div_fmas_f32 v155, v155, v156, v159
	v_div_fixup_f32 v154, v155, v154, v161
	v_mul_f32_e32 v154, v157, v154
	v_cvt_pk_bf16_f32 v154, v154, s0
	ds_write_b16 v168, v154 offset:816
	v_mul_f32_e32 v154, 0xbfb8aa3b, v150
	v_exp_f32_e32 v154, v154
	s_nop 0
	v_add_f32_e32 v154, 1.0, v154
	v_div_scale_f32 v155, s[12:13], v154, v154, v150
	v_rcp_f32_e32 v156, v155
	s_nop 0
	v_fma_f32 v157, -v155, v156, 1.0
	v_fmac_f32_e32 v156, v157, v156
	v_div_scale_f32 v157, vcc, v150, v154, v150
	v_mul_f32_e32 v158, v157, v156
	v_fma_f32 v159, -v155, v158, v157
	v_fmac_f32_e32 v158, v159, v156
	v_fma_f32 v155, -v155, v158, v157
	v_div_fmas_f32 v155, v155, v156, v158
	v_div_fixup_f32 v150, v155, v154, v150
	v_mul_f32_e32 v146, v146, v150
	v_cvt_pk_bf16_f32 v146, v146, s0
	ds_write_b16 v168, v146 offset:32
	v_mul_f32_e32 v146, 0xbfb8aa3b, v151
	v_exp_f32_e32 v146, v146
	s_nop 0
	v_add_f32_e32 v146, 1.0, v146
	v_div_scale_f32 v150, s[12:13], v146, v146, v151
	v_rcp_f32_e32 v154, v150
	s_nop 0
	v_fma_f32 v155, -v150, v154, 1.0
	v_fmac_f32_e32 v154, v155, v154
	v_div_scale_f32 v155, vcc, v151, v146, v151
	v_mul_f32_e32 v156, v155, v154
	v_fma_f32 v157, -v150, v156, v155
	v_fmac_f32_e32 v156, v157, v154
	v_fma_f32 v150, -v150, v156, v155
	v_div_fmas_f32 v150, v150, v154, v156
	v_div_fixup_f32 v146, v150, v146, v151
	v_mul_f32_e32 v146, v147, v146
	v_cvt_pk_bf16_f32 v146, v146, s0
	ds_write_b16 v168, v146 offset:304
	v_mul_f32_e32 v146, 0xbfb8aa3b, v152
	v_exp_f32_e32 v146, v146
	s_nop 0
	v_add_f32_e32 v146, 1.0, v146
	v_div_scale_f32 v147, s[12:13], v146, v146, v152
	v_rcp_f32_e32 v150, v147
	s_nop 0
	v_fma_f32 v151, -v147, v150, 1.0
	v_fmac_f32_e32 v150, v151, v150
	v_div_scale_f32 v151, vcc, v152, v146, v152
	v_mul_f32_e32 v154, v151, v150
	v_fma_f32 v155, -v147, v154, v151
	v_fmac_f32_e32 v154, v155, v150
	v_fma_f32 v147, -v147, v154, v151
	v_div_fmas_f32 v147, v147, v150, v154
	v_div_fixup_f32 v146, v147, v146, v152
	v_mul_f32_e32 v146, v148, v146
	v_cvt_pk_bf16_f32 v146, v146, s0
	ds_write_b16 v168, v146 offset:576
	v_mul_f32_e32 v146, 0xbfb8aa3b, v153
	v_exp_f32_e32 v146, v146
	s_nop 0
	v_add_f32_e32 v146, 1.0, v146
	v_div_scale_f32 v147, s[12:13], v146, v146, v153
	v_rcp_f32_e32 v148, v147
	s_nop 0
	v_fma_f32 v150, -v147, v148, 1.0
	v_fmac_f32_e32 v148, v150, v148
	v_div_scale_f32 v150, vcc, v153, v146, v153
	v_mul_f32_e32 v151, v150, v148
	v_fma_f32 v152, -v147, v151, v150
	v_fmac_f32_e32 v151, v152, v148
	v_fma_f32 v147, -v147, v151, v150
	v_div_fmas_f32 v147, v147, v148, v151
	v_div_fixup_f32 v146, v147, v146, v153
	v_mul_f32_e32 v146, v149, v146
	v_cvt_pk_bf16_f32 v146, v146, s0
	ds_write_b16 v168, v146 offset:848
	v_mul_f32_e32 v146, 0xbfb8aa3b, v142
	v_exp_f32_e32 v146, v146
	s_nop 0
	v_add_f32_e32 v146, 1.0, v146
	v_div_scale_f32 v147, s[12:13], v146, v146, v142
	v_rcp_f32_e32 v148, v147
	s_nop 0
	v_fma_f32 v149, -v147, v148, 1.0
	v_fmac_f32_e32 v148, v149, v148
	v_div_scale_f32 v149, vcc, v142, v146, v142
	v_mul_f32_e32 v150, v149, v148
	v_fma_f32 v151, -v147, v150, v149
	v_fmac_f32_e32 v150, v151, v148
	v_fma_f32 v147, -v147, v150, v149
	v_div_fmas_f32 v147, v147, v148, v150
	v_div_fixup_f32 v142, v147, v146, v142
	v_mul_f32_e32 v138, v138, v142
	v_cvt_pk_bf16_f32 v138, v138, s0
	ds_write_b16 v168, v138 offset:4352
	v_mul_f32_e32 v138, 0xbfb8aa3b, v143
	v_exp_f32_e32 v138, v138
	s_nop 0
; __device__ __forceinline__ float sigmoidf_(float x) { return 1.0f / (1.0f + __expf(-x)); }
; __device__ __forceinline__ float siluf_(float x) { return x / (1.0f + __expf(-x)); }
; __device__ __forceinline__ void phase_ffn_up(const Params& p, const u16* Wgu, u16* smem, volatile LAS unsigned* vb_) {
;     ...
; #pragma unroll
;     for (int i = 0; i < 8; ++i)
; #pragma unroll
;       for (int jp = 0; jp < 2; ++jp) {
; #pragma unroll
;         for (int r = 0; r < 4; ++r) {
;           const float g = acc[i][2 * jp][r], u = acc[i][2 * jp + 1][r];
;           smem[(wm * 128 + i * 16 + (lane >> 4) * 4 + r) * 136 + (wn * 2 + jp) * 16 + (lane & 15)] = f2bf(siluf_(g) * u);
;         }
;         __builtin_amdgcn_sched_barrier(0);
;       }
	v_add_f32_e32 v138, 1.0, v138
	v_div_scale_f32 v142, s[12:13], v138, v138, v143
	v_rcp_f32_e32 v146, v142
	s_nop 0
	v_fma_f32 v147, -v142, v146, 1.0
	v_fmac_f32_e32 v146, v147, v146
	v_div_scale_f32 v147, vcc, v143, v138, v143
	v_mul_f32_e32 v148, v147, v146
	v_fma_f32 v149, -v142, v148, v147
	v_fmac_f32_e32 v148, v149, v146
	v_fma_f32 v142, -v142, v148, v147
	v_div_fmas_f32 v142, v142, v146, v148
	v_div_fixup_f32 v138, v142, v138, v143
	v_mul_f32_e32 v138, v139, v138
	v_cvt_pk_bf16_f32 v138, v138, s0
	ds_write_b16 v168, v138 offset:4624
	v_mul_f32_e32 v138, 0xbfb8aa3b, v144
	v_exp_f32_e32 v138, v138
	s_nop 0
	v_add_f32_e32 v138, 1.0, v138
	v_div_scale_f32 v139, s[12:13], v138, v138, v144
	v_rcp_f32_e32 v142, v139
	s_nop 0
	v_fma_f32 v143, -v139, v142, 1.0
	v_fmac_f32_e32 v142, v143, v142
	v_div_scale_f32 v143, vcc, v144, v138, v144
	v_mul_f32_e32 v146, v143, v142
	v_fma_f32 v147, -v139, v146, v143
	v_fmac_f32_e32 v146, v147, v142
	v_fma_f32 v139, -v139, v146, v143
	v_div_fmas_f32 v139, v139, v142, v146
	v_div_fixup_f32 v138, v139, v138, v144
	v_mul_f32_e32 v138, v140, v138
	v_cvt_pk_bf16_f32 v138, v138, s0
	ds_write_b16 v168, v138 offset:4896
	v_mul_f32_e32 v138, 0xbfb8aa3b, v145
	v_exp_f32_e32 v138, v138
	s_nop 0
	v_add_f32_e32 v138, 1.0, v138
	v_div_scale_f32 v139, s[12:13], v138, v138, v145
	v_rcp_f32_e32 v140, v139
	s_nop 0
	v_fma_f32 v142, -v139, v140, 1.0
	v_fmac_f32_e32 v140, v142, v140
	v_div_scale_f32 v142, vcc, v145, v138, v145
	v_mul_f32_e32 v143, v142, v140
	v_fma_f32 v144, -v139, v143, v142
	v_fmac_f32_e32 v143, v144, v140
	v_fma_f32 v139, -v139, v143, v142
	v_div_fmas_f32 v139, v139, v140, v143
	v_div_fixup_f32 v138, v139, v138, v145
	v_mul_f32_e32 v138, v141, v138
	v_cvt_pk_bf16_f32 v138, v138, s0
	ds_write_b16 v168, v138 offset:5168
	v_mul_f32_e32 v138, 0xbfb8aa3b, v134
	v_exp_f32_e32 v138, v138
	s_nop 0
	v_add_f32_e32 v138, 1.0, v138
	v_div_scale_f32 v139, s[12:13], v138, v138, v134
	v_rcp_f32_e32 v140, v139
	s_nop 0
	v_fma_f32 v141, -v139, v140, 1.0
	v_fmac_f32_e32 v140, v141, v140
	v_div_scale_f32 v141, vcc, v134, v138, v134
	v_mul_f32_e32 v142, v141, v140
	v_fma_f32 v143, -v139, v142, v141
	v_fmac_f32_e32 v142, v143, v140
	v_fma_f32 v139, -v139, v142, v141
	v_div_fmas_f32 v139, v139, v140, v142
	v_div_fixup_f32 v134, v139, v138, v134
	v_mul_f32_e32 v130, v130, v134
	v_cvt_pk_bf16_f32 v130, v130, s0
	ds_write_b16 v168, v130 offset:4384
	v_mul_f32_e32 v130, 0xbfb8aa3b, v135
	v_exp_f32_e32 v130, v130
	s_nop 0
	v_add_f32_e32 v130, 1.0, v130
	v_div_scale_f32 v134, s[12:13], v130, v130, v135
	v_rcp_f32_e32 v138, v134
	s_nop 0
	v_fma_f32 v139, -v134, v138, 1.0
	v_fmac_f32_e32 v138, v139, v138
	v_div_scale_f32 v139, vcc, v135, v130, v135
	v_mul_f32_e32 v140, v139, v138
	v_fma_f32 v141, -v134, v140, v139
	v_fmac_f32_e32 v140, v141, v138
	v_fma_f32 v134, -v134, v140, v139
	v_div_fmas_f32 v134, v134, v138, v140
	v_div_fixup_f32 v130, v134, v130, v135
	v_mul_f32_e32 v130, v131, v130
	v_cvt_pk_bf16_f32 v130, v130, s0
	ds_write_b16 v168, v130 offset:4656
	v_mul_f32_e32 v130, 0xbfb8aa3b, v136
	v_exp_f32_e32 v130, v130
	s_nop 0
	v_add_f32_e32 v130, 1.0, v130
	v_div_scale_f32 v131, s[12:13], v130, v130, v136
	v_rcp_f32_e32 v134, v131
	s_nop 0
	v_fma_f32 v135, -v131, v134, 1.0
	v_fmac_f32_e32 v134, v135, v134
	v_div_scale_f32 v135, vcc, v136, v130, v136
	v_mul_f32_e32 v138, v135, v134
	v_fma_f32 v139, -v131, v138, v135
	v_fmac_f32_e32 v138, v139, v134
	v_fma_f32 v131, -v131, v138, v135
	v_div_fmas_f32 v131, v131, v134, v138
	v_div_fixup_f32 v130, v131, v130, v136
	v_mul_f32_e32 v130, v132, v130
	v_cvt_pk_bf16_f32 v130, v130, s0
	ds_write_b16 v168, v130 offset:4928
	v_mul_f32_e32 v130, 0xbfb8aa3b, v137
	v_exp_f32_e32 v130, v130
	s_nop 0
	v_add_f32_e32 v130, 1.0, v130
	v_div_scale_f32 v131, s[12:13], v130, v130, v137
	v_rcp_f32_e32 v132, v131
	s_nop 0
	v_fma_f32 v134, -v131, v132, 1.0
	v_fmac_f32_e32 v132, v134, v132
	v_div_scale_f32 v134, vcc, v137, v130, v137
	v_mul_f32_e32 v135, v134, v132
	v_fma_f32 v136, -v131, v135, v134
	v_fmac_f32_e32 v135, v136, v132
	v_fma_f32 v131, -v131, v135, v134
	v_div_fmas_f32 v131, v131, v132, v135
	v_div_fixup_f32 v130, v131, v130, v137
	v_mul_f32_e32 v130, v133, v130
	v_cvt_pk_bf16_f32 v130, v130, s0
	ds_write_b16 v168, v130 offset:5200
	v_mul_f32_e32 v130, 0xbfb8aa3b, v126
	v_exp_f32_e32 v130, v130
	s_nop 0
	v_add_f32_e32 v130, 1.0, v130
	v_div_scale_f32 v131, s[12:13], v130, v130, v126
	v_rcp_f32_e32 v132, v131
	s_nop 0
	v_fma_f32 v133, -v131, v132, 1.0
	v_fmac_f32_e32 v132, v133, v132
	v_div_scale_f32 v133, vcc, v126, v130, v126
	v_mul_f32_e32 v134, v133, v132
	v_fma_f32 v135, -v131, v134, v133
	v_fmac_f32_e32 v134, v135, v132
	v_fma_f32 v131, -v131, v134, v133
	v_div_fmas_f32 v131, v131, v132, v134
	v_div_fixup_f32 v126, v131, v130, v126
	v_mul_f32_e32 v122, v122, v126
	v_cvt_pk_bf16_f32 v122, v122, s0
	ds_write_b16 v168, v122 offset:8704
	v_mul_f32_e32 v122, 0xbfb8aa3b, v127
	v_exp_f32_e32 v122, v122
	s_nop 0
	v_add_f32_e32 v122, 1.0, v122
	v_div_scale_f32 v126, s[12:13], v122, v122, v127
	v_rcp_f32_e32 v130, v126
	s_nop 0
	v_fma_f32 v131, -v126, v130, 1.0
	v_fmac_f32_e32 v130, v131, v130
	v_div_scale_f32 v131, vcc, v127, v122, v127
	v_mul_f32_e32 v132, v131, v130
	v_fma_f32 v133, -v126, v132, v131
	v_fmac_f32_e32 v132, v133, v130
	v_fma_f32 v126, -v126, v132, v131
	v_div_fmas_f32 v126, v126, v130, v132
	v_div_fixup_f32 v122, v126, v122, v127
	v_mul_f32_e32 v122, v123, v122
	v_cvt_pk_bf16_f32 v122, v122, s0
	ds_write_b16 v168, v122 offset:8976
	v_mul_f32_e32 v122, 0xbfb8aa3b, v128
	v_exp_f32_e32 v122, v122
	s_nop 0
	v_add_f32_e32 v122, 1.0, v122
	v_div_scale_f32 v123, s[12:13], v122, v122, v128
; __device__ __forceinline__ float sigmoidf_(float x) { return 1.0f / (1.0f + __expf(-x)); }
; __device__ __forceinline__ float siluf_(float x) { return x / (1.0f + __expf(-x)); }
; __device__ __forceinline__ void phase_ffn_up(const Params& p, const u16* Wgu, u16* smem, volatile LAS unsigned* vb_) {
;     ...
; #pragma unroll
;     for (int i = 0; i < 8; ++i)
; #pragma unroll
;       for (int jp = 0; jp < 2; ++jp) {
; #pragma unroll
;         for (int r = 0; r < 4; ++r) {
;           const float g = acc[i][2 * jp][r], u = acc[i][2 * jp + 1][r];
;           smem[(wm * 128 + i * 16 + (lane >> 4) * 4 + r) * 136 + (wn * 2 + jp) * 16 + (lane & 15)] = f2bf(siluf_(g) * u);
;         }
;         __builtin_amdgcn_sched_barrier(0);
;       }
	v_rcp_f32_e32 v126, v123
	s_nop 0
	v_fma_f32 v127, -v123, v126, 1.0
	v_fmac_f32_e32 v126, v127, v126
	v_div_scale_f32 v127, vcc, v128, v122, v128
	v_mul_f32_e32 v130, v127, v126
	v_fma_f32 v131, -v123, v130, v127
	v_fmac_f32_e32 v130, v131, v126
	v_fma_f32 v123, -v123, v130, v127
	v_div_fmas_f32 v123, v123, v126, v130
	v_div_fixup_f32 v122, v123, v122, v128
	v_mul_f32_e32 v122, v124, v122
	v_cvt_pk_bf16_f32 v122, v122, s0
	ds_write_b16 v168, v122 offset:9248
	v_mul_f32_e32 v122, 0xbfb8aa3b, v129
	v_exp_f32_e32 v122, v122
	s_nop 0
	v_add_f32_e32 v122, 1.0, v122
	v_div_scale_f32 v123, s[12:13], v122, v122, v129
	v_rcp_f32_e32 v124, v123
	s_nop 0
	v_fma_f32 v126, -v123, v124, 1.0
	v_fmac_f32_e32 v124, v126, v124
	v_div_scale_f32 v126, vcc, v129, v122, v129
	v_mul_f32_e32 v127, v126, v124
	v_fma_f32 v128, -v123, v127, v126
	v_fmac_f32_e32 v127, v128, v124
	v_fma_f32 v123, -v123, v127, v126
	v_div_fmas_f32 v123, v123, v124, v127
	v_div_fixup_f32 v122, v123, v122, v129
	v_mul_f32_e32 v122, v125, v122
	v_cvt_pk_bf16_f32 v122, v122, s0
	ds_write_b16 v168, v122 offset:9520
	v_mul_f32_e32 v122, 0xbfb8aa3b, v118
	v_exp_f32_e32 v122, v122
	s_nop 0
	v_add_f32_e32 v122, 1.0, v122
	v_div_scale_f32 v123, s[12:13], v122, v122, v118
	v_rcp_f32_e32 v124, v123
	s_nop 0
	v_fma_f32 v125, -v123, v124, 1.0
	v_fmac_f32_e32 v124, v125, v124
	v_div_scale_f32 v125, vcc, v118, v122, v118
	v_mul_f32_e32 v126, v125, v124
	v_fma_f32 v127, -v123, v126, v125
	v_fmac_f32_e32 v126, v127, v124
	v_fma_f32 v123, -v123, v126, v125
	v_div_fmas_f32 v123, v123, v124, v126
	v_div_fixup_f32 v118, v123, v122, v118
	v_mul_f32_e32 v114, v114, v118
	v_cvt_pk_bf16_f32 v114, v114, s0
	ds_write_b16 v168, v114 offset:8736
	v_mul_f32_e32 v114, 0xbfb8aa3b, v119
	v_exp_f32_e32 v114, v114
	s_nop 0
	v_add_f32_e32 v114, 1.0, v114
	v_div_scale_f32 v118, s[12:13], v114, v114, v119
	v_rcp_f32_e32 v122, v118
	s_nop 0
	v_fma_f32 v123, -v118, v122, 1.0
	v_fmac_f32_e32 v122, v123, v122
	v_div_scale_f32 v123, vcc, v119, v114, v119
	v_mul_f32_e32 v124, v123, v122
	v_fma_f32 v125, -v118, v124, v123
	v_fmac_f32_e32 v124, v125, v122
	v_fma_f32 v118, -v118, v124, v123
	v_div_fmas_f32 v118, v118, v122, v124
	v_div_fixup_f32 v114, v118, v114, v119
	v_mul_f32_e32 v114, v115, v114
	v_cvt_pk_bf16_f32 v114, v114, s0
	ds_write_b16 v168, v114 offset:9008
	v_mul_f32_e32 v114, 0xbfb8aa3b, v120
	v_exp_f32_e32 v114, v114
	s_nop 0
	v_add_f32_e32 v114, 1.0, v114
	v_div_scale_f32 v115, s[12:13], v114, v114, v120
	v_rcp_f32_e32 v118, v115
	s_nop 0
	v_fma_f32 v119, -v115, v118, 1.0
	v_fmac_f32_e32 v118, v119, v118
	v_div_scale_f32 v119, vcc, v120, v114, v120
	v_mul_f32_e32 v122, v119, v118
	v_fma_f32 v123, -v115, v122, v119
	v_fmac_f32_e32 v122, v123, v118
	v_fma_f32 v115, -v115, v122, v119
	v_div_fmas_f32 v115, v115, v118, v122
	v_div_fixup_f32 v114, v115, v114, v120
	v_mul_f32_e32 v114, v116, v114
	v_cvt_pk_bf16_f32 v114, v114, s0
	ds_write_b16 v168, v114 offset:9280
	v_mul_f32_e32 v114, 0xbfb8aa3b, v121
	v_exp_f32_e32 v114, v114
	s_nop 0
	v_add_f32_e32 v114, 1.0, v114
	v_div_scale_f32 v115, s[12:13], v114, v114, v121
	v_rcp_f32_e32 v116, v115
	s_nop 0
	v_fma_f32 v118, -v115, v116, 1.0
	v_fmac_f32_e32 v116, v118, v116
	v_div_scale_f32 v118, vcc, v121, v114, v121
	v_mul_f32_e32 v119, v118, v116
	v_fma_f32 v120, -v115, v119, v118
	v_fmac_f32_e32 v119, v120, v116
	v_fma_f32 v115, -v115, v119, v118
	v_div_fmas_f32 v115, v115, v116, v119
	v_div_fixup_f32 v114, v115, v114, v121
	v_mul_f32_e32 v114, v117, v114
	v_cvt_pk_bf16_f32 v114, v114, s0
	ds_write_b16 v168, v114 offset:9552
	v_mul_f32_e32 v114, 0xbfb8aa3b, v110
	v_exp_f32_e32 v114, v114
	s_nop 0
	v_add_f32_e32 v114, 1.0, v114
	v_div_scale_f32 v115, s[12:13], v114, v114, v110
	v_rcp_f32_e32 v116, v115
	s_nop 0
	v_fma_f32 v117, -v115, v116, 1.0
	v_fmac_f32_e32 v116, v117, v116
	v_div_scale_f32 v117, vcc, v110, v114, v110
	v_mul_f32_e32 v118, v117, v116
	v_fma_f32 v119, -v115, v118, v117
	v_fmac_f32_e32 v118, v119, v116
	v_fma_f32 v115, -v115, v118, v117
	v_div_fmas_f32 v115, v115, v116, v118
	v_div_fixup_f32 v110, v115, v114, v110
	v_mul_f32_e32 v106, v106, v110
	v_cvt_pk_bf16_f32 v106, v106, s0
	ds_write_b16 v168, v106 offset:13056
	v_mul_f32_e32 v106, 0xbfb8aa3b, v111
	v_exp_f32_e32 v106, v106
	s_nop 0
	v_add_f32_e32 v106, 1.0, v106
	v_div_scale_f32 v110, s[12:13], v106, v106, v111
	v_rcp_f32_e32 v114, v110
	s_nop 0
	v_fma_f32 v115, -v110, v114, 1.0
	v_fmac_f32_e32 v114, v115, v114
	v_div_scale_f32 v115, vcc, v111, v106, v111
	v_mul_f32_e32 v116, v115, v114
	v_fma_f32 v117, -v110, v116, v115
	v_fmac_f32_e32 v116, v117, v114
	v_fma_f32 v110, -v110, v116, v115
	v_div_fmas_f32 v110, v110, v114, v116
	v_div_fixup_f32 v106, v110, v106, v111
	v_mul_f32_e32 v106, v107, v106
	v_cvt_pk_bf16_f32 v106, v106, s0
	ds_write_b16 v168, v106 offset:13328
	v_mul_f32_e32 v106, 0xbfb8aa3b, v112
	v_exp_f32_e32 v106, v106
	s_nop 0
	v_add_f32_e32 v106, 1.0, v106
	v_div_scale_f32 v107, s[12:13], v106, v106, v112
	v_rcp_f32_e32 v110, v107
	s_nop 0
	v_fma_f32 v111, -v107, v110, 1.0
	v_fmac_f32_e32 v110, v111, v110
	v_div_scale_f32 v111, vcc, v112, v106, v112
	v_mul_f32_e32 v114, v111, v110
	v_fma_f32 v115, -v107, v114, v111
	v_fmac_f32_e32 v114, v115, v110
	v_fma_f32 v107, -v107, v114, v111
	v_div_fmas_f32 v107, v107, v110, v114
	v_div_fixup_f32 v106, v107, v106, v112
	v_mul_f32_e32 v106, v108, v106
	v_cvt_pk_bf16_f32 v106, v106, s0
	ds_write_b16 v168, v106 offset:13600
	v_mul_f32_e32 v106, 0xbfb8aa3b, v113
	v_exp_f32_e32 v106, v106
	s_nop 0
	v_add_f32_e32 v106, 1.0, v106
	v_div_scale_f32 v107, s[12:13], v106, v106, v113
	v_rcp_f32_e32 v108, v107
	s_nop 0
	v_fma_f32 v110, -v107, v108, 1.0
; __device__ __forceinline__ float sigmoidf_(float x) { return 1.0f / (1.0f + __expf(-x)); }
; __device__ __forceinline__ float siluf_(float x) { return x / (1.0f + __expf(-x)); }
; __device__ __forceinline__ void phase_ffn_up(const Params& p, const u16* Wgu, u16* smem, volatile LAS unsigned* vb_) {
;     ...
; #pragma unroll
;     for (int i = 0; i < 8; ++i)
; #pragma unroll
;       for (int jp = 0; jp < 2; ++jp) {
; #pragma unroll
;         for (int r = 0; r < 4; ++r) {
;           const float g = acc[i][2 * jp][r], u = acc[i][2 * jp + 1][r];
;           smem[(wm * 128 + i * 16 + (lane >> 4) * 4 + r) * 136 + (wn * 2 + jp) * 16 + (lane & 15)] = f2bf(siluf_(g) * u);
;         }
;         __builtin_amdgcn_sched_barrier(0);
;       }
	v_fmac_f32_e32 v108, v110, v108
	v_div_scale_f32 v110, vcc, v113, v106, v113
	v_mul_f32_e32 v111, v110, v108
	v_fma_f32 v112, -v107, v111, v110
	v_fmac_f32_e32 v111, v112, v108
	v_fma_f32 v107, -v107, v111, v110
	v_div_fmas_f32 v107, v107, v108, v111
	v_div_fixup_f32 v106, v107, v106, v113
	v_mul_f32_e32 v106, v109, v106
	v_cvt_pk_bf16_f32 v106, v106, s0
	ds_write_b16 v168, v106 offset:13872
	v_mul_f32_e32 v106, 0xbfb8aa3b, v102
	v_exp_f32_e32 v106, v106
	s_nop 0
	v_add_f32_e32 v106, 1.0, v106
	v_div_scale_f32 v107, s[12:13], v106, v106, v102
	v_rcp_f32_e32 v108, v107
	s_nop 0
	v_fma_f32 v109, -v107, v108, 1.0
	v_fmac_f32_e32 v108, v109, v108
	v_div_scale_f32 v109, vcc, v102, v106, v102
	v_mul_f32_e32 v110, v109, v108
	v_fma_f32 v111, -v107, v110, v109
	v_fmac_f32_e32 v110, v111, v108
	v_fma_f32 v107, -v107, v110, v109
	v_div_fmas_f32 v107, v107, v108, v110
	v_div_fixup_f32 v102, v107, v106, v102
	v_mul_f32_e32 v98, v98, v102
	v_cvt_pk_bf16_f32 v98, v98, s0
	ds_write_b16 v168, v98 offset:13088
	v_mul_f32_e32 v98, 0xbfb8aa3b, v103
	v_exp_f32_e32 v98, v98
	s_nop 0
	v_add_f32_e32 v98, 1.0, v98
	v_div_scale_f32 v102, s[12:13], v98, v98, v103
	v_rcp_f32_e32 v106, v102
	s_nop 0
	v_fma_f32 v107, -v102, v106, 1.0
	v_fmac_f32_e32 v106, v107, v106
	v_div_scale_f32 v107, vcc, v103, v98, v103
	v_mul_f32_e32 v108, v107, v106
	v_fma_f32 v109, -v102, v108, v107
	v_fmac_f32_e32 v108, v109, v106
	v_fma_f32 v102, -v102, v108, v107
	v_div_fmas_f32 v102, v102, v106, v108
	v_div_fixup_f32 v98, v102, v98, v103
	v_mul_f32_e32 v98, v99, v98
	v_cvt_pk_bf16_f32 v98, v98, s0
	ds_write_b16 v168, v98 offset:13360
	v_mul_f32_e32 v98, 0xbfb8aa3b, v104
	v_exp_f32_e32 v98, v98
	s_nop 0
	v_add_f32_e32 v98, 1.0, v98
	v_div_scale_f32 v99, s[12:13], v98, v98, v104
	v_rcp_f32_e32 v102, v99
	s_nop 0
	v_fma_f32 v103, -v99, v102, 1.0
	v_fmac_f32_e32 v102, v103, v102
	v_div_scale_f32 v103, vcc, v104, v98, v104
	v_mul_f32_e32 v106, v103, v102
	v_fma_f32 v107, -v99, v106, v103
	v_fmac_f32_e32 v106, v107, v102
	v_fma_f32 v99, -v99, v106, v103
	v_div_fmas_f32 v99, v99, v102, v106
	v_div_fixup_f32 v98, v99, v98, v104
	v_mul_f32_e32 v98, v100, v98
	v_cvt_pk_bf16_f32 v98, v98, s0
	ds_write_b16 v168, v98 offset:13632
	v_mul_f32_e32 v98, 0xbfb8aa3b, v105
	v_exp_f32_e32 v98, v98
	s_nop 0
	v_add_f32_e32 v98, 1.0, v98
	v_div_scale_f32 v99, s[12:13], v98, v98, v105
	v_rcp_f32_e32 v100, v99
	s_nop 0
	v_fma_f32 v102, -v99, v100, 1.0
	v_fmac_f32_e32 v100, v102, v100
	v_div_scale_f32 v102, vcc, v105, v98, v105
	v_mul_f32_e32 v103, v102, v100
	v_fma_f32 v104, -v99, v103, v102
	v_fmac_f32_e32 v103, v104, v100
	v_fma_f32 v99, -v99, v103, v102
	v_div_fmas_f32 v99, v99, v100, v103
	v_div_fixup_f32 v98, v99, v98, v105
	v_mul_f32_e32 v98, v101, v98
	v_cvt_pk_bf16_f32 v98, v98, s0
	ds_write_b16 v168, v98 offset:13904
	v_mul_f32_e32 v98, 0xbfb8aa3b, v94
	v_exp_f32_e32 v98, v98
	s_nop 0
	v_add_f32_e32 v98, 1.0, v98
	v_div_scale_f32 v99, s[12:13], v98, v98, v94
	v_rcp_f32_e32 v100, v99
	s_nop 0
	v_fma_f32 v101, -v99, v100, 1.0
	v_fmac_f32_e32 v100, v101, v100
	v_div_scale_f32 v101, vcc, v94, v98, v94
	v_mul_f32_e32 v102, v101, v100
	v_fma_f32 v103, -v99, v102, v101
	v_fmac_f32_e32 v102, v103, v100
	v_fma_f32 v99, -v99, v102, v101
	v_div_fmas_f32 v99, v99, v100, v102
	v_div_fixup_f32 v94, v99, v98, v94
	v_mul_f32_e32 v90, v90, v94
	v_cvt_pk_bf16_f32 v90, v90, s0
	ds_write_b16 v168, v90 offset:17408
	v_mul_f32_e32 v90, 0xbfb8aa3b, v95
	v_exp_f32_e32 v90, v90
	s_nop 0
	v_add_f32_e32 v90, 1.0, v90
	v_div_scale_f32 v94, s[12:13], v90, v90, v95
	v_rcp_f32_e32 v98, v94
	s_nop 0
	v_fma_f32 v99, -v94, v98, 1.0
	v_fmac_f32_e32 v98, v99, v98
	v_div_scale_f32 v99, vcc, v95, v90, v95
	v_mul_f32_e32 v100, v99, v98
	v_fma_f32 v101, -v94, v100, v99
	v_fmac_f32_e32 v100, v101, v98
	v_fma_f32 v94, -v94, v100, v99
	v_div_fmas_f32 v94, v94, v98, v100
	v_div_fixup_f32 v90, v94, v90, v95
	v_mul_f32_e32 v90, v91, v90
	v_cvt_pk_bf16_f32 v90, v90, s0
	ds_write_b16 v168, v90 offset:17680
	v_mul_f32_e32 v90, 0xbfb8aa3b, v96
	v_exp_f32_e32 v90, v90
	s_nop 0
	v_add_f32_e32 v90, 1.0, v90
	v_div_scale_f32 v91, s[12:13], v90, v90, v96
	v_rcp_f32_e32 v94, v91
	s_nop 0
	v_fma_f32 v95, -v91, v94, 1.0
	v_fmac_f32_e32 v94, v95, v94
	v_div_scale_f32 v95, vcc, v96, v90, v96
	v_mul_f32_e32 v98, v95, v94
	v_fma_f32 v99, -v91, v98, v95
	v_fmac_f32_e32 v98, v99, v94
	v_fma_f32 v91, -v91, v98, v95
	v_div_fmas_f32 v91, v91, v94, v98
	v_div_fixup_f32 v90, v91, v90, v96
	v_mul_f32_e32 v90, v92, v90
	v_cvt_pk_bf16_f32 v90, v90, s0
	ds_write_b16 v168, v90 offset:17952
	v_mul_f32_e32 v90, 0xbfb8aa3b, v97
	v_exp_f32_e32 v90, v90
	s_nop 0
	v_add_f32_e32 v90, 1.0, v90
	v_div_scale_f32 v91, s[12:13], v90, v90, v97
	v_rcp_f32_e32 v92, v91
	s_nop 0
	v_fma_f32 v94, -v91, v92, 1.0
	v_fmac_f32_e32 v92, v94, v92
	v_div_scale_f32 v94, vcc, v97, v90, v97
	v_mul_f32_e32 v95, v94, v92
	v_fma_f32 v96, -v91, v95, v94
	v_fmac_f32_e32 v95, v96, v92
	v_fma_f32 v91, -v91, v95, v94
	v_div_fmas_f32 v91, v91, v92, v95
	v_div_fixup_f32 v90, v91, v90, v97
	v_mul_f32_e32 v90, v93, v90
	v_cvt_pk_bf16_f32 v90, v90, s0
	ds_write_b16 v168, v90 offset:18224
	v_mul_f32_e32 v90, 0xbfb8aa3b, v86
	v_exp_f32_e32 v90, v90
	s_nop 0
	v_add_f32_e32 v90, 1.0, v90
	v_div_scale_f32 v91, s[12:13], v90, v90, v86
	v_rcp_f32_e32 v92, v91
	s_nop 0
	v_fma_f32 v93, -v91, v92, 1.0
	v_fmac_f32_e32 v92, v93, v92
	v_div_scale_f32 v93, vcc, v86, v90, v86
	v_mul_f32_e32 v94, v93, v92
	v_fma_f32 v95, -v91, v94, v93
	v_fmac_f32_e32 v94, v95, v92
	v_fma_f32 v91, -v91, v94, v93
	v_div_fmas_f32 v91, v91, v92, v94
	v_div_fixup_f32 v86, v91, v90, v86
	v_mul_f32_e32 v82, v82, v86
	v_cvt_pk_bf16_f32 v82, v82, s0
; __device__ __forceinline__ float sigmoidf_(float x) { return 1.0f / (1.0f + __expf(-x)); }
; __device__ __forceinline__ float siluf_(float x) { return x / (1.0f + __expf(-x)); }
; __device__ __forceinline__ void phase_ffn_up(const Params& p, const u16* Wgu, u16* smem, volatile LAS unsigned* vb_) {
;     ...
; #pragma unroll
;     for (int i = 0; i < 8; ++i)
; #pragma unroll
;       for (int jp = 0; jp < 2; ++jp) {
; #pragma unroll
;         for (int r = 0; r < 4; ++r) {
;           const float g = acc[i][2 * jp][r], u = acc[i][2 * jp + 1][r];
;           smem[(wm * 128 + i * 16 + (lane >> 4) * 4 + r) * 136 + (wn * 2 + jp) * 16 + (lane & 15)] = f2bf(siluf_(g) * u);
;         }
;         __builtin_amdgcn_sched_barrier(0);
;       }
	ds_write_b16 v168, v82 offset:17440
	v_mul_f32_e32 v82, 0xbfb8aa3b, v87
	v_exp_f32_e32 v82, v82
	s_nop 0
	v_add_f32_e32 v82, 1.0, v82
	v_div_scale_f32 v86, s[12:13], v82, v82, v87
	v_rcp_f32_e32 v90, v86
	s_nop 0
	v_fma_f32 v91, -v86, v90, 1.0
	v_fmac_f32_e32 v90, v91, v90
	v_div_scale_f32 v91, vcc, v87, v82, v87
	v_mul_f32_e32 v92, v91, v90
	v_fma_f32 v93, -v86, v92, v91
	v_fmac_f32_e32 v92, v93, v90
	v_fma_f32 v86, -v86, v92, v91
	v_div_fmas_f32 v86, v86, v90, v92
	v_div_fixup_f32 v82, v86, v82, v87
	v_mul_f32_e32 v82, v83, v82
	v_cvt_pk_bf16_f32 v82, v82, s0
	ds_write_b16 v168, v82 offset:17712
	v_mul_f32_e32 v82, 0xbfb8aa3b, v88
	v_exp_f32_e32 v82, v82
	s_nop 0
	v_add_f32_e32 v82, 1.0, v82
	v_div_scale_f32 v83, s[12:13], v82, v82, v88
	v_rcp_f32_e32 v86, v83
	s_nop 0
	v_fma_f32 v87, -v83, v86, 1.0
	v_fmac_f32_e32 v86, v87, v86
	v_div_scale_f32 v87, vcc, v88, v82, v88
	v_mul_f32_e32 v90, v87, v86
	v_fma_f32 v91, -v83, v90, v87
	v_fmac_f32_e32 v90, v91, v86
	v_fma_f32 v83, -v83, v90, v87
	v_div_fmas_f32 v83, v83, v86, v90
	v_div_fixup_f32 v82, v83, v82, v88
	v_mul_f32_e32 v82, v84, v82
	v_cvt_pk_bf16_f32 v82, v82, s0
	ds_write_b16 v168, v82 offset:17984
	v_mul_f32_e32 v82, 0xbfb8aa3b, v89
	v_exp_f32_e32 v82, v82
	s_nop 0
	v_add_f32_e32 v82, 1.0, v82
	v_div_scale_f32 v83, s[12:13], v82, v82, v89
	v_rcp_f32_e32 v84, v83
	s_nop 0
	v_fma_f32 v86, -v83, v84, 1.0
	v_fmac_f32_e32 v84, v86, v84
	v_div_scale_f32 v86, vcc, v89, v82, v89
	v_mul_f32_e32 v87, v86, v84
	v_fma_f32 v88, -v83, v87, v86
	v_fmac_f32_e32 v87, v88, v84
	v_fma_f32 v83, -v83, v87, v86
	v_div_fmas_f32 v83, v83, v84, v87
	v_div_fixup_f32 v82, v83, v82, v89
	v_mul_f32_e32 v82, v85, v82
	v_cvt_pk_bf16_f32 v82, v82, s0
	ds_write_b16 v168, v82 offset:18256
	v_mul_f32_e32 v82, 0xbfb8aa3b, v78
	v_exp_f32_e32 v82, v82
	s_nop 0
	v_add_f32_e32 v82, 1.0, v82
	v_div_scale_f32 v83, s[12:13], v82, v82, v78
	v_rcp_f32_e32 v84, v83
	s_nop 0
	v_fma_f32 v85, -v83, v84, 1.0
	v_fmac_f32_e32 v84, v85, v84
	v_div_scale_f32 v85, vcc, v78, v82, v78
	v_mul_f32_e32 v86, v85, v84
	v_fma_f32 v87, -v83, v86, v85
	v_fmac_f32_e32 v86, v87, v84
	v_fma_f32 v83, -v83, v86, v85
	v_div_fmas_f32 v83, v83, v84, v86
	v_div_fixup_f32 v78, v83, v82, v78
	v_mul_f32_e32 v74, v74, v78
	v_cvt_pk_bf16_f32 v74, v74, s0
	ds_write_b16 v168, v74 offset:21760
	v_mul_f32_e32 v74, 0xbfb8aa3b, v79
	v_exp_f32_e32 v74, v74
	s_nop 0
	v_add_f32_e32 v74, 1.0, v74
	v_div_scale_f32 v78, s[12:13], v74, v74, v79
	v_rcp_f32_e32 v82, v78
	s_nop 0
	v_fma_f32 v83, -v78, v82, 1.0
	v_fmac_f32_e32 v82, v83, v82
	v_div_scale_f32 v83, vcc, v79, v74, v79
	v_mul_f32_e32 v84, v83, v82
	v_fma_f32 v85, -v78, v84, v83
	v_fmac_f32_e32 v84, v85, v82
	v_fma_f32 v78, -v78, v84, v83
	v_div_fmas_f32 v78, v78, v82, v84
	v_div_fixup_f32 v74, v78, v74, v79
	v_mul_f32_e32 v74, v75, v74
	v_cvt_pk_bf16_f32 v74, v74, s0
	ds_write_b16 v168, v74 offset:22032
	v_mul_f32_e32 v74, 0xbfb8aa3b, v80
	v_exp_f32_e32 v74, v74
	s_nop 0
	v_add_f32_e32 v74, 1.0, v74
	v_div_scale_f32 v75, s[12:13], v74, v74, v80
	v_rcp_f32_e32 v78, v75
	s_nop 0
	v_fma_f32 v79, -v75, v78, 1.0
	v_fmac_f32_e32 v78, v79, v78
	v_div_scale_f32 v79, vcc, v80, v74, v80
	v_mul_f32_e32 v82, v79, v78
	v_fma_f32 v83, -v75, v82, v79
	v_fmac_f32_e32 v82, v83, v78
	v_fma_f32 v75, -v75, v82, v79
	v_div_fmas_f32 v75, v75, v78, v82
	v_div_fixup_f32 v74, v75, v74, v80
	v_mul_f32_e32 v74, v76, v74
	v_cvt_pk_bf16_f32 v74, v74, s0
	ds_write_b16 v168, v74 offset:22304
	v_mul_f32_e32 v74, 0xbfb8aa3b, v81
	v_exp_f32_e32 v74, v74
	s_nop 0
	v_add_f32_e32 v74, 1.0, v74
	v_div_scale_f32 v75, s[12:13], v74, v74, v81
	v_rcp_f32_e32 v76, v75
	s_nop 0
	v_fma_f32 v78, -v75, v76, 1.0
	v_fmac_f32_e32 v76, v78, v76
	v_div_scale_f32 v78, vcc, v81, v74, v81
	v_mul_f32_e32 v79, v78, v76
	v_fma_f32 v80, -v75, v79, v78
	v_fmac_f32_e32 v79, v80, v76
	v_fma_f32 v75, -v75, v79, v78
	v_div_fmas_f32 v75, v75, v76, v79
	v_div_fixup_f32 v74, v75, v74, v81
	v_mul_f32_e32 v74, v77, v74
	v_cvt_pk_bf16_f32 v74, v74, s0
	ds_write_b16 v168, v74 offset:22576
	v_mul_f32_e32 v74, 0xbfb8aa3b, v70
	v_exp_f32_e32 v74, v74
	s_nop 0
	v_add_f32_e32 v74, 1.0, v74
	v_div_scale_f32 v75, s[12:13], v74, v74, v70
	v_rcp_f32_e32 v76, v75
	s_nop 0
	v_fma_f32 v77, -v75, v76, 1.0
	v_fmac_f32_e32 v76, v77, v76
	v_div_scale_f32 v77, vcc, v70, v74, v70
	v_mul_f32_e32 v78, v77, v76
	v_fma_f32 v79, -v75, v78, v77
	v_fmac_f32_e32 v78, v79, v76
	v_fma_f32 v75, -v75, v78, v77
	v_div_fmas_f32 v75, v75, v76, v78
	v_div_fixup_f32 v70, v75, v74, v70
	v_mul_f32_e32 v66, v66, v70
	v_cvt_pk_bf16_f32 v66, v66, s0
	ds_write_b16 v168, v66 offset:21792
	v_mul_f32_e32 v66, 0xbfb8aa3b, v71
	v_exp_f32_e32 v66, v66
	s_nop 0
	v_add_f32_e32 v66, 1.0, v66
	v_div_scale_f32 v70, s[12:13], v66, v66, v71
	v_rcp_f32_e32 v74, v70
	s_nop 0
	v_fma_f32 v75, -v70, v74, 1.0
	v_fmac_f32_e32 v74, v75, v74
	v_div_scale_f32 v75, vcc, v71, v66, v71
	v_mul_f32_e32 v76, v75, v74
	v_fma_f32 v77, -v70, v76, v75
	v_fmac_f32_e32 v76, v77, v74
	v_fma_f32 v70, -v70, v76, v75
	v_div_fmas_f32 v70, v70, v74, v76
	v_div_fixup_f32 v66, v70, v66, v71
	v_mul_f32_e32 v66, v67, v66
	v_cvt_pk_bf16_f32 v66, v66, s0
	ds_write_b16 v168, v66 offset:22064
	v_mul_f32_e32 v66, 0xbfb8aa3b, v72
	v_exp_f32_e32 v66, v66
	s_nop 0
	v_add_f32_e32 v66, 1.0, v66
	v_div_scale_f32 v67, s[12:13], v66, v66, v72
	v_rcp_f32_e32 v70, v67
	s_nop 0
	v_fma_f32 v71, -v67, v70, 1.0
	v_fmac_f32_e32 v70, v71, v70
	v_div_scale_f32 v71, vcc, v72, v66, v72
	v_mul_f32_e32 v74, v71, v70
	v_fma_f32 v75, -v67, v74, v71
	v_fmac_f32_e32 v74, v75, v70
	v_fma_f32 v67, -v67, v74, v71
	v_div_fmas_f32 v67, v67, v70, v74
	v_div_fixup_f32 v66, v67, v66, v72
; __device__ __forceinline__ float sigmoidf_(float x) { return 1.0f / (1.0f + __expf(-x)); }
; __device__ __forceinline__ float siluf_(float x) { return x / (1.0f + __expf(-x)); }
; __device__ __forceinline__ void phase_ffn_up(const Params& p, const u16* Wgu, u16* smem, volatile LAS unsigned* vb_) {
;     ...
; #pragma unroll
;     for (int i = 0; i < 8; ++i)
; #pragma unroll
;       for (int jp = 0; jp < 2; ++jp) {
; #pragma unroll
;         for (int r = 0; r < 4; ++r) {
;           const float g = acc[i][2 * jp][r], u = acc[i][2 * jp + 1][r];
;           smem[(wm * 128 + i * 16 + (lane >> 4) * 4 + r) * 136 + (wn * 2 + jp) * 16 + (lane & 15)] = f2bf(siluf_(g) * u);
;         }
;         __builtin_amdgcn_sched_barrier(0);
;       }
	v_mul_f32_e32 v66, v68, v66
	v_cvt_pk_bf16_f32 v66, v66, s0
	ds_write_b16 v168, v66 offset:22336
	v_mul_f32_e32 v66, 0xbfb8aa3b, v73
	v_exp_f32_e32 v66, v66
	s_nop 0
	v_add_f32_e32 v66, 1.0, v66
	v_div_scale_f32 v67, s[12:13], v66, v66, v73
	v_rcp_f32_e32 v68, v67
	s_nop 0
	v_fma_f32 v70, -v67, v68, 1.0
	v_fmac_f32_e32 v68, v70, v68
	v_div_scale_f32 v70, vcc, v73, v66, v73
	v_mul_f32_e32 v71, v70, v68
	v_fma_f32 v72, -v67, v71, v70
	v_fmac_f32_e32 v71, v72, v68
	v_fma_f32 v67, -v67, v71, v70
	v_div_fmas_f32 v67, v67, v68, v71
	v_div_fixup_f32 v66, v67, v66, v73
	v_mul_f32_e32 v66, v69, v66
	v_cvt_pk_bf16_f32 v66, v66, s0
	ds_write_b16 v168, v66 offset:22608
	v_mul_f32_e32 v66, 0xbfb8aa3b, v62
	v_exp_f32_e32 v66, v66
	s_nop 0
	v_add_f32_e32 v66, 1.0, v66
	v_div_scale_f32 v67, s[12:13], v66, v66, v62
	v_rcp_f32_e32 v68, v67
	s_nop 0
	v_fma_f32 v69, -v67, v68, 1.0
	v_fmac_f32_e32 v68, v69, v68
	v_div_scale_f32 v69, vcc, v62, v66, v62
	v_mul_f32_e32 v70, v69, v68
	v_fma_f32 v71, -v67, v70, v69
	v_fmac_f32_e32 v70, v71, v68
	v_fma_f32 v67, -v67, v70, v69
	v_div_fmas_f32 v67, v67, v68, v70
	v_div_fixup_f32 v62, v67, v66, v62
	v_mul_f32_e32 v58, v58, v62
	v_cvt_pk_bf16_f32 v58, v58, s0
	ds_write_b16 v168, v58 offset:26112
	v_mul_f32_e32 v58, 0xbfb8aa3b, v63
	v_exp_f32_e32 v58, v58
	s_nop 0
	v_add_f32_e32 v58, 1.0, v58
	v_div_scale_f32 v62, s[12:13], v58, v58, v63
	v_rcp_f32_e32 v66, v62
	s_nop 0
	v_fma_f32 v67, -v62, v66, 1.0
	v_fmac_f32_e32 v66, v67, v66
	v_div_scale_f32 v67, vcc, v63, v58, v63
	v_mul_f32_e32 v68, v67, v66
	v_fma_f32 v69, -v62, v68, v67
	v_fmac_f32_e32 v68, v69, v66
	v_fma_f32 v62, -v62, v68, v67
	v_div_fmas_f32 v62, v62, v66, v68
	v_div_fixup_f32 v58, v62, v58, v63
	v_mul_f32_e32 v58, v59, v58
	v_cvt_pk_bf16_f32 v58, v58, s0
	ds_write_b16 v168, v58 offset:26384
	v_mul_f32_e32 v58, 0xbfb8aa3b, v64
	v_exp_f32_e32 v58, v58
	s_nop 0
	v_add_f32_e32 v58, 1.0, v58
	v_div_scale_f32 v59, s[12:13], v58, v58, v64
	v_rcp_f32_e32 v62, v59
	s_nop 0
	v_fma_f32 v63, -v59, v62, 1.0
	v_fmac_f32_e32 v62, v63, v62
	v_div_scale_f32 v63, vcc, v64, v58, v64
	v_mul_f32_e32 v66, v63, v62
	v_fma_f32 v67, -v59, v66, v63
	v_fmac_f32_e32 v66, v67, v62
	v_fma_f32 v59, -v59, v66, v63
	v_div_fmas_f32 v59, v59, v62, v66
	v_div_fixup_f32 v58, v59, v58, v64
	v_mul_f32_e32 v58, v60, v58
	v_cvt_pk_bf16_f32 v58, v58, s0
	ds_write_b16 v168, v58 offset:26656
	v_mul_f32_e32 v58, 0xbfb8aa3b, v65
	v_exp_f32_e32 v58, v58
	s_nop 0
	v_add_f32_e32 v58, 1.0, v58
	v_div_scale_f32 v59, s[12:13], v58, v58, v65
	v_rcp_f32_e32 v60, v59
	s_nop 0
	v_fma_f32 v62, -v59, v60, 1.0
	v_fmac_f32_e32 v60, v62, v60
	v_div_scale_f32 v62, vcc, v65, v58, v65
	v_mul_f32_e32 v63, v62, v60
	v_fma_f32 v64, -v59, v63, v62
	v_fmac_f32_e32 v63, v64, v60
	v_fma_f32 v59, -v59, v63, v62
	v_div_fmas_f32 v59, v59, v60, v63
	v_div_fixup_f32 v58, v59, v58, v65
	v_mul_f32_e32 v58, v61, v58
	v_cvt_pk_bf16_f32 v58, v58, s0
	ds_write_b16 v168, v58 offset:26928
	v_mul_f32_e32 v58, 0xbfb8aa3b, v54
	v_exp_f32_e32 v58, v58
	s_nop 0
	v_add_f32_e32 v58, 1.0, v58
	v_div_scale_f32 v59, s[12:13], v58, v58, v54
	v_rcp_f32_e32 v60, v59
	s_nop 0
	v_fma_f32 v61, -v59, v60, 1.0
	v_fmac_f32_e32 v60, v61, v60
	v_div_scale_f32 v61, vcc, v54, v58, v54
	v_mul_f32_e32 v62, v61, v60
	v_fma_f32 v63, -v59, v62, v61
	v_fmac_f32_e32 v62, v63, v60
	v_fma_f32 v59, -v59, v62, v61
	v_div_fmas_f32 v59, v59, v60, v62
	v_div_fixup_f32 v54, v59, v58, v54
	v_mul_f32_e32 v50, v50, v54
	v_cvt_pk_bf16_f32 v50, v50, s0
	ds_write_b16 v168, v50 offset:26144
	v_mul_f32_e32 v50, 0xbfb8aa3b, v55
	v_exp_f32_e32 v50, v50
	s_nop 0
	v_add_f32_e32 v50, 1.0, v50
	v_div_scale_f32 v54, s[12:13], v50, v50, v55
	v_rcp_f32_e32 v58, v54
	s_nop 0
	v_fma_f32 v59, -v54, v58, 1.0
	v_fmac_f32_e32 v58, v59, v58
	v_div_scale_f32 v59, vcc, v55, v50, v55
	v_mul_f32_e32 v60, v59, v58
	v_fma_f32 v61, -v54, v60, v59
	v_fmac_f32_e32 v60, v61, v58
	v_fma_f32 v54, -v54, v60, v59
	v_div_fmas_f32 v54, v54, v58, v60
	v_div_fixup_f32 v50, v54, v50, v55
	v_mul_f32_e32 v50, v51, v50
	v_cvt_pk_bf16_f32 v50, v50, s0
	ds_write_b16 v168, v50 offset:26416
	v_mul_f32_e32 v50, 0xbfb8aa3b, v56
	v_exp_f32_e32 v50, v50
	s_nop 0
	v_add_f32_e32 v50, 1.0, v50
	v_div_scale_f32 v51, s[12:13], v50, v50, v56
	v_rcp_f32_e32 v54, v51
	s_nop 0
	v_fma_f32 v55, -v51, v54, 1.0
	v_fmac_f32_e32 v54, v55, v54
	v_div_scale_f32 v55, vcc, v56, v50, v56
	v_mul_f32_e32 v58, v55, v54
	v_fma_f32 v59, -v51, v58, v55
	v_fmac_f32_e32 v58, v59, v54
	v_fma_f32 v51, -v51, v58, v55
	v_div_fmas_f32 v51, v51, v54, v58
	v_div_fixup_f32 v50, v51, v50, v56
	v_mul_f32_e32 v50, v52, v50
	v_cvt_pk_bf16_f32 v50, v50, s0
	ds_write_b16 v168, v50 offset:26688
	v_mul_f32_e32 v50, 0xbfb8aa3b, v57
	v_exp_f32_e32 v50, v50
	s_nop 0
	v_add_f32_e32 v50, 1.0, v50
	v_div_scale_f32 v51, s[12:13], v50, v50, v57
	v_rcp_f32_e32 v52, v51
	s_nop 0
	v_fma_f32 v54, -v51, v52, 1.0
	v_fmac_f32_e32 v52, v54, v52
	v_div_scale_f32 v54, vcc, v57, v50, v57
	v_mul_f32_e32 v55, v54, v52
	v_fma_f32 v56, -v51, v55, v54
	v_fmac_f32_e32 v55, v56, v52
	v_fma_f32 v51, -v51, v55, v54
	v_div_fmas_f32 v51, v51, v52, v55
	v_div_fixup_f32 v50, v51, v50, v57
	v_mul_f32_e32 v50, v53, v50
	v_cvt_pk_bf16_f32 v50, v50, s0
	ds_write_b16 v168, v50 offset:26960
	v_mul_f32_e32 v50, 0xbfb8aa3b, v46
	v_exp_f32_e32 v50, v50
	s_nop 0
	v_add_f32_e32 v50, 1.0, v50
	v_div_scale_f32 v51, s[12:13], v50, v50, v46
	v_rcp_f32_e32 v52, v51
	s_nop 0
	v_fma_f32 v53, -v51, v52, 1.0
	v_fmac_f32_e32 v52, v53, v52
	v_div_scale_f32 v53, vcc, v46, v50, v46
	v_mul_f32_e32 v54, v53, v52
	v_fma_f32 v55, -v51, v54, v53
	v_fmac_f32_e32 v54, v55, v52
	v_fma_f32 v51, -v51, v54, v53
	v_div_fmas_f32 v51, v51, v52, v54
; __device__ __forceinline__ float siluf_(float x) { return x / (1.0f + __expf(-x)); }
; __device__ __forceinline__ void phase_ffn_up(const Params& p, const u16* Wgu, u16* smem, volatile LAS unsigned* vb_) {
;     ...
;         for (int r = 0; r < 4; ++r) {
;           const float g = acc[i][2 * jp][r], u = acc[i][2 * jp + 1][r];
;           smem[(wm * 128 + i * 16 + (lane >> 4) * 4 + r) * 136 + (wn * 2 + jp) * 16 + (lane & 15)] = f2bf(siluf_(g) * u);
;         }
;         __builtin_amdgcn_sched_barrier(0);
;       }
;     __syncthreads();
; #pragma unroll
;     for (int k = 0; k < 8; ++k) {
;       const int c = tid + 512 * k;
;       const int row = c >> 4, ch = c & 15;
;       const uint4 v = *(const uint4*)(smem + row * 136 + ch * 8);
;       *(uint4*)(act + (size_t)(mt * 256 + row) * DFF + nt * 128 + ch * 8) = v;
;     }
;     __syncthreads();
	v_div_fixup_f32 v46, v51, v50, v46
	v_mul_f32_e32 v42, v42, v46
	v_cvt_pk_bf16_f32 v42, v42, s0
	ds_write_b16 v168, v42 offset:30464
	v_mul_f32_e32 v42, 0xbfb8aa3b, v47
	v_exp_f32_e32 v42, v42
	s_nop 0
	v_add_f32_e32 v42, 1.0, v42
	v_div_scale_f32 v46, s[12:13], v42, v42, v47
	v_rcp_f32_e32 v50, v46
	s_nop 0
	v_fma_f32 v51, -v46, v50, 1.0
	v_fmac_f32_e32 v50, v51, v50
	v_div_scale_f32 v51, vcc, v47, v42, v47
	v_mul_f32_e32 v52, v51, v50
	v_fma_f32 v53, -v46, v52, v51
	v_fmac_f32_e32 v52, v53, v50
	v_fma_f32 v46, -v46, v52, v51
	v_div_fmas_f32 v46, v46, v50, v52
	v_div_fixup_f32 v42, v46, v42, v47
	v_mul_f32_e32 v42, v43, v42
	v_cvt_pk_bf16_f32 v42, v42, s0
	ds_write_b16 v168, v42 offset:30736
	v_mul_f32_e32 v42, 0xbfb8aa3b, v48
	v_exp_f32_e32 v42, v42
	s_nop 0
	v_add_f32_e32 v42, 1.0, v42
	v_div_scale_f32 v43, s[12:13], v42, v42, v48
	v_rcp_f32_e32 v46, v43
	s_nop 0
	v_fma_f32 v47, -v43, v46, 1.0
	v_fmac_f32_e32 v46, v47, v46
	v_div_scale_f32 v47, vcc, v48, v42, v48
	v_mul_f32_e32 v50, v47, v46
	v_fma_f32 v51, -v43, v50, v47
	v_fmac_f32_e32 v50, v51, v46
	v_fma_f32 v43, -v43, v50, v47
	v_div_fmas_f32 v43, v43, v46, v50
	v_div_fixup_f32 v42, v43, v42, v48
	v_mul_f32_e32 v42, v44, v42
	v_cvt_pk_bf16_f32 v42, v42, s0
	ds_write_b16 v168, v42 offset:31008
	v_mul_f32_e32 v42, 0xbfb8aa3b, v49
	v_exp_f32_e32 v42, v42
	s_nop 0
	v_add_f32_e32 v42, 1.0, v42
	v_div_scale_f32 v43, s[12:13], v42, v42, v49
	v_rcp_f32_e32 v44, v43
	s_nop 0
	v_fma_f32 v46, -v43, v44, 1.0
	v_fmac_f32_e32 v44, v46, v44
	v_div_scale_f32 v46, vcc, v49, v42, v49
	v_mul_f32_e32 v47, v46, v44
	v_fma_f32 v48, -v43, v47, v46
	v_fmac_f32_e32 v47, v48, v44
	v_fma_f32 v43, -v43, v47, v46
	v_div_fmas_f32 v43, v43, v44, v47
	v_div_fixup_f32 v42, v43, v42, v49
	v_mul_f32_e32 v42, v45, v42
	v_cvt_pk_bf16_f32 v42, v42, s0
	ds_write_b16 v168, v42 offset:31280
	v_mul_f32_e32 v42, 0xbfb8aa3b, v38
	v_exp_f32_e32 v42, v42
	s_nop 0
	v_add_f32_e32 v42, 1.0, v42
	v_div_scale_f32 v43, s[12:13], v42, v42, v38
	v_rcp_f32_e32 v44, v43
	s_nop 0
	v_fma_f32 v45, -v43, v44, 1.0
	v_fmac_f32_e32 v44, v45, v44
	v_div_scale_f32 v45, vcc, v38, v42, v38
	v_mul_f32_e32 v46, v45, v44
	v_fma_f32 v47, -v43, v46, v45
	v_fmac_f32_e32 v46, v47, v44
	v_fma_f32 v43, -v43, v46, v45
	v_div_fmas_f32 v43, v43, v44, v46
	v_div_fixup_f32 v38, v43, v42, v38
	v_mul_f32_e32 v34, v34, v38
	v_cvt_pk_bf16_f32 v34, v34, s0
	ds_write_b16 v168, v34 offset:30496
	v_mul_f32_e32 v34, 0xbfb8aa3b, v39
	v_exp_f32_e32 v34, v34
	s_nop 0
	v_add_f32_e32 v34, 1.0, v34
	v_div_scale_f32 v38, s[12:13], v34, v34, v39
	v_rcp_f32_e32 v42, v38
	s_nop 0
	v_fma_f32 v43, -v38, v42, 1.0
	v_fmac_f32_e32 v42, v43, v42
	v_div_scale_f32 v43, vcc, v39, v34, v39
	v_mul_f32_e32 v44, v43, v42
	v_fma_f32 v45, -v38, v44, v43
	v_fmac_f32_e32 v44, v45, v42
	v_fma_f32 v38, -v38, v44, v43
	v_div_fmas_f32 v38, v38, v42, v44
	v_div_fixup_f32 v34, v38, v34, v39
	v_mul_f32_e32 v34, v35, v34
	v_cvt_pk_bf16_f32 v34, v34, s0
	ds_write_b16 v168, v34 offset:30768
	v_mul_f32_e32 v34, 0xbfb8aa3b, v40
	v_exp_f32_e32 v34, v34
	s_nop 0
	v_add_f32_e32 v34, 1.0, v34
	v_div_scale_f32 v35, s[12:13], v34, v34, v40
	v_rcp_f32_e32 v38, v35
	s_nop 0
	v_fma_f32 v39, -v35, v38, 1.0
	v_fmac_f32_e32 v38, v39, v38
	v_div_scale_f32 v39, vcc, v40, v34, v40
	v_mul_f32_e32 v42, v39, v38
	v_fma_f32 v43, -v35, v42, v39
	v_fmac_f32_e32 v42, v43, v38
	v_fma_f32 v35, -v35, v42, v39
	v_div_fmas_f32 v35, v35, v38, v42
	v_div_fixup_f32 v34, v35, v34, v40
	v_mul_f32_e32 v34, v36, v34
	v_cvt_pk_bf16_f32 v34, v34, s0
	ds_write_b16 v168, v34 offset:31040
	v_mul_f32_e32 v34, 0xbfb8aa3b, v41
	v_exp_f32_e32 v34, v34
	s_nop 0
	v_add_f32_e32 v34, 1.0, v34
	v_div_scale_f32 v35, s[12:13], v34, v34, v41
	v_rcp_f32_e32 v36, v35
	s_nop 0
	v_fma_f32 v38, -v35, v36, 1.0
	v_fmac_f32_e32 v36, v38, v36
	v_div_scale_f32 v38, vcc, v41, v34, v41
	v_mul_f32_e32 v39, v38, v36
	v_fma_f32 v40, -v35, v39, v38
	v_fmac_f32_e32 v39, v40, v36
	v_fma_f32 v35, -v35, v39, v38
	v_div_fmas_f32 v35, v35, v36, v39
	v_div_fixup_f32 v34, v35, v34, v41
	v_mul_f32_e32 v34, v37, v34
	v_cvt_pk_bf16_f32 v34, v34, s0
	ds_write_b16 v168, v34 offset:31312
	s_waitcnt lgkmcnt(0)
	s_barrier
	ds_read_b128 v[34:37], v197
	s_lshl_b32 s12, s40, 7
	s_ashr_i32 s13, s12, 31
	v_lshl_add_u64 v[38:39], s[12:13], 1, v[166:167]
	v_add_u32_e32 v40, s39, v189
	v_mad_i64_i32 v[40:41], s[12:13], v40, s7, v[38:39]
	s_waitcnt lgkmcnt(0)
	global_store_dwordx4 v[40:41], v[34:37], off
	ds_read_b128 v[34:37], v198
	v_add_u32_e32 v40, s39, v169
	v_mad_i64_i32 v[40:41], s[12:13], v40, s7, v[38:39]
	s_and_b64 vcc, exec, s[10:11]
	s_waitcnt lgkmcnt(0)
	global_store_dwordx4 v[40:41], v[34:37], off
	ds_read_b128 v[34:37], v199
	v_add_u32_e32 v40, s39, v190
	v_mad_i64_i32 v[40:41], s[12:13], v40, s7, v[38:39]
	s_mov_b32 s20, s41
	s_waitcnt lgkmcnt(0)
	global_store_dwordx4 v[40:41], v[34:37], off
	ds_read_b128 v[34:37], v200
	v_add_u32_e32 v40, s39, v191
	v_mad_i64_i32 v[40:41], s[12:13], v40, s7, v[38:39]
	s_waitcnt lgkmcnt(0)
	global_store_dwordx4 v[40:41], v[34:37], off
	ds_read_b128 v[34:37], v204
	v_add_u32_e32 v40, s39, v192
	v_mad_i64_i32 v[40:41], s[12:13], v40, s7, v[38:39]
	s_waitcnt lgkmcnt(0)
	global_store_dwordx4 v[40:41], v[34:37], off
	ds_read_b128 v[34:37], v205
	v_add_u32_e32 v40, s39, v193
	v_mad_i64_i32 v[40:41], s[12:13], v40, s7, v[38:39]
	s_waitcnt lgkmcnt(0)
	global_store_dwordx4 v[40:41], v[34:37], off
	ds_read_b128 v[34:37], v206
	v_add_u32_e32 v40, s39, v194
	v_mad_i64_i32 v[40:41], s[12:13], v40, s7, v[38:39]
	s_waitcnt lgkmcnt(0)
	global_store_dwordx4 v[40:41], v[34:37], off
	ds_read_b128 v[34:37], v207
	v_add_u32_e32 v40, s39, v195
	v_mad_i64_i32 v[38:39], s[12:13], v40, s7, v[38:39]
	s_mov_b64 s[12:13], -1
	s_waitcnt lgkmcnt(0)
	global_store_dwordx4 v[38:39], v[34:37], off
	s_barrier
	s_cbranch_vccz .LBB0_598
.LBB0_603:
	s_waitcnt vmcnt(0)
	s_cmp_gt_i32 s36, 31
	s_cbranch_scc1 .LBB0_608
	v_readlane_b32 s12, v252, 38
	v_readlane_b32 s13, v252, 39
	s_waitcnt vmcnt(15)
	v_lshlrev_b32_e32 v2, 3, v182
	v_lshl_add_u64 v[92:93], s[0:1], 0, v[0:1]
	v_lshl_add_u64 v[90:91], s[12:13], 0, v[0:1]
	v_lshlrev_b32_e32 v0, 4, v184
	v_xor_b32_e32 v3, 32, v2
	v_and_or_b32 v4, v180, s9, v179
	v_and_b32_e32 v0, 0x70, v0
	v_sub_u32_e32 v2, v3, v2
	v_lshlrev_b32_e32 v3, 4, v182
	v_lshlrev_b32_e32 v4, 7, v4
	s_mov_b32 s0, 0x10000
	s_lshl_b32 s10, s37, 3
	v_lshl_or_b32 v0, v176, 7, v0
	v_lshl_or_b32 v100, v183, 7, v3
	v_or3_b32 v101, v4, v3, s0
	v_lshlrev_b32_e32 v3, 4, v178
	s_movk_i32 s0, 0xa00
	s_and_b32 s10, s10, 56
	v_add_u32_e32 v98, 0x1400, v176
	v_add_u32_e32 v99, 0x10000, v0
	v_lshl_or_b32 v102, v177, 7, v181
	v_or3_b32 v103, v3, v179, s0
	v_lshlrev_b32_e32 v104, 1, v2
